# EpiProj: rope rows staged through the dead SA(1,1) LDS stage, epilogue vmcnt waits removed
# speedup vs baseline: 1.0082x; 1.0082x over previous
; #define PG8_STAGE(bufoff, gbase, voff) do { _Pragma("unroll") for (int _i = 0; _i < 2; ++_i) \
;         __builtin_amdgcn_global_load_lds((const unsigned*)((const char*)(gbase) + (voff)[_i]), (LAS unsigned*)(lds + (bufoff) + ldsw + _i * 8192), 16, 0, 0); } while (0)
; #define PG8_LDA(dst, b, h) do { _Pragma("unroll") for (int m = 0; m < 4; ++m) _Pragma("unroll") for (int k = 0; k < 2; ++k) dst[m][k] = *(const LAS bf16x8*)(lds + PG8_SA(b, h) + aoff + m * 2048 + k * 1024); } while (0)
; #define PG8_LDB(dst, b, h) do { _Pragma("unroll") for (int n = 0; n < 2; ++n) _Pragma("unroll") for (int k = 0; k < 2; ++k) dst[n][k] = *(const LAS bf16x8*)(lds + PG8_SB(b, h) + boff + n * 2048 + k * 1024); } while (0)
; #define PG8_MMA(ai, bj, At, Bt) do { __builtin_amdgcn_s_setprio(1); _Pragma("unroll") for (int m = 0; m < 4; ++m) _Pragma("unroll") for (int n = 0; n < 2; ++n) _Pragma("unroll") for (int k = 0; k < 2; ++k) \
;         acc[ai][bj][m][n] = __builtin_amdgcn_mfma_f32_16x16x32_bf16(Bt[n][k], At[m][k], acc[ai][bj][m][n], 0, 0, 0); __builtin_amdgcn_s_setprio(0); } while (0)
; #define PG8_WAIT_V(n) asm volatile("s_waitcnt vmcnt(" #n ")" ::: "memory")
; #define PG8_WAIT_L(n) asm volatile("s_waitcnt lgkmcnt(" #n ")" ::: "memory")
; #define PG8_BAR __builtin_amdgcn_s_barrier()
; template <class Epi, class Sched>
; DI void gemm_phase(LAS unsigned char* lds, const Gemm g, const Sched& S, const Epi& E) {
;     ...
;         for (int t = 0; t < nt; t += 2) {
;             const bool last = (t == nt - 2);
;             const char* a1 = cA + (size_t)(t + 1) * kstep;
;             const char* a2 = last ? nA : cA + (size_t)(t + 2) * kstep; const char* b2 = last ? nB : cB + (size_t)(t + 2) * kstep;
;             const char* a3 = a2 + kstep; const char* b3 = b2 + kstep;
;             PG8_LDB(B0, 0, 0); PG8_SCHED; PG8_LDA(At, 0, 0); PG8_STAGE(PG8_SA(1, 1), a1 + hstep, voffA);
;             PG8_WAIT_L(8); PG8_BAR; PG8_WAIT_L(0); PG8_MMA(0, 0, At, B0); PG8_BAR; PG8_SCHED;
;             PG8_LDB(B1, 0, 1); PG8_STAGE(PG8_SB(0, 0), b2, voffB);
;             PG8_BAR; PG8_WAIT_L(0); PG8_MMA(0, 1, At, B1); PG8_BAR;
;             PG8_LDA(At, 0, 1); PG8_STAGE(PG8_SA(0, 0), a2, voffA);
;             PG8_BAR; PG8_WAIT_L(0); PG8_MMA(1, 0, At, B0); PG8_BAR; PG8_SCHED;
;             PG8_STAGE(PG8_SB(0, 1), b2 + hstep, voffB);
;             PG8_WAIT_V(6); PG8_BAR; PG8_MMA(1, 1, At, B1); PG8_BAR;
.LBB0_196:
	s_add_u32 s0, s8, s22
	s_addc_u32 s1, s9, s23
	s_add_u32 s0, s0, 0x100
	s_addc_u32 s1, s1, 0
	s_add_u32 s24, s76, s22
	s_addc_u32 s25, s33, s23
	s_add_i32 s28, 0, 0x10000
	v_add_u32_e32 v96, s28, v173
	ds_read_b128 v[134:137], v96
	ds_read_b128 v[138:141], v96 offset:1024
	ds_read_b128 v[142:145], v96 offset:2048
	ds_read_b128 v[146:149], v96 offset:3072
	s_cmpk_eq_i32 s22, 0x700
	s_cselect_b32 s39, s2, s1
	s_cselect_b32 s38, s13, s0
	s_cselect_b32 s25, s11, s25
	s_cselect_b32 s24, s26, s24
	v_lshl_add_u64 v[214:215], v[130:131], 0, s[22:23]
	s_add_i32 m0, s6, 0xc000
	ds_read_b128 v[150:153], v193
	ds_read_b128 v[154:157], v193 offset:1024
	s_waitcnt lgkmcnt(0)
	ds_read_b128 v[188:191], v193 offset:2048
	ds_read_b128 v[194:197], v193 offset:3072
	ds_read_b128 v[198:201], v193 offset:4096
	ds_read_b128 v[202:205], v193 offset:5120
	ds_read_b128 v[206:209], v193 offset:6144
	ds_read_b128 v[210:213], v193 offset:7168
	global_load_lds_dwordx4 v[214:215], off
	v_lshl_add_u64 v[214:215], v[132:133], 0, s[22:23]
	s_add_i32 m0, s6, 0xe000
	s_nop 0
	global_load_lds_dwordx4 v[214:215], off
	s_waitcnt lgkmcnt(8)
	s_barrier
	s_waitcnt lgkmcnt(0)
	s_setprio 1
	s_waitcnt lgkmcnt(0)
	v_mfma_f32_16x16x32_bf16 v[126:129], v[134:137], v[150:153], v[126:129]
	v_mfma_f32_16x16x32_bf16 v[122:125], v[142:145], v[150:153], v[122:125]
	v_mfma_f32_16x16x32_bf16 v[118:121], v[134:137], v[188:191], v[118:121]
	v_mfma_f32_16x16x32_bf16 v[114:117], v[142:145], v[188:191], v[114:117]
	v_mfma_f32_16x16x32_bf16 v[110:113], v[134:137], v[198:201], v[110:113]
	v_mfma_f32_16x16x32_bf16 v[106:109], v[142:145], v[198:201], v[106:109]
	v_mfma_f32_16x16x32_bf16 v[102:105], v[134:137], v[206:209], v[102:105]
	v_mfma_f32_16x16x32_bf16 v[98:101], v[142:145], v[206:209], v[98:101]
	v_mfma_f32_16x16x32_bf16 v[126:129], v[138:141], v[154:157], v[126:129]
	v_mfma_f32_16x16x32_bf16 v[122:125], v[146:149], v[154:157], v[122:125]
	v_mfma_f32_16x16x32_bf16 v[118:121], v[138:141], v[194:197], v[118:121]
	v_mfma_f32_16x16x32_bf16 v[114:117], v[146:149], v[194:197], v[114:117]
	v_mfma_f32_16x16x32_bf16 v[110:113], v[138:141], v[202:205], v[110:113]
	v_mfma_f32_16x16x32_bf16 v[106:109], v[146:149], v[202:205], v[106:109]
	v_mfma_f32_16x16x32_bf16 v[102:105], v[138:141], v[210:213], v[102:105]
	v_mfma_f32_16x16x32_bf16 v[98:101], v[146:149], v[210:213], v[98:101]
	s_setprio 0
	s_barrier
	s_add_i32 s29, 0, 0x14000
	s_add_i32 s0, s28, s68
	v_add_u32_e32 v96, s29, v173
	v_lshl_add_u64 v[226:227], s[24:25], 0, v[160:161]
	s_mov_b32 m0, s0
	ds_read_b128 v[214:217], v96
	ds_read_b128 v[218:221], v96 offset:1024
	ds_read_b128 v[222:225], v96 offset:2048
	ds_read_b128 v[236:239], v96 offset:3072
	global_load_lds_dwordx4 v[226:227], off
	v_lshl_add_u64 v[240:241], s[24:25], 0, v[164:165]
	s_add_i32 m0, s0, 0x2000
	s_nop 0
	global_load_lds_dwordx4 v[240:241], off
	s_barrier
	s_waitcnt lgkmcnt(0)
	s_setprio 1
	s_waitcnt lgkmcnt(0)
	v_mfma_f32_16x16x32_bf16 v[92:95], v[214:217], v[150:153], v[92:95]
	v_mfma_f32_16x16x32_bf16 v[88:91], v[222:225], v[150:153], v[88:91]
	v_mfma_f32_16x16x32_bf16 v[84:87], v[214:217], v[188:191], v[84:87]
	v_mfma_f32_16x16x32_bf16 v[80:83], v[222:225], v[188:191], v[80:83]
	v_mfma_f32_16x16x32_bf16 v[76:79], v[214:217], v[198:201], v[76:79]
	v_mfma_f32_16x16x32_bf16 v[72:75], v[222:225], v[198:201], v[72:75]
	v_mfma_f32_16x16x32_bf16 v[68:71], v[214:217], v[206:209], v[68:71]
	v_mfma_f32_16x16x32_bf16 v[64:67], v[222:225], v[206:209], v[64:67]
	v_mfma_f32_16x16x32_bf16 v[92:95], v[218:221], v[154:157], v[92:95]
	v_mfma_f32_16x16x32_bf16 v[88:91], v[236:239], v[154:157], v[88:91]
	v_mfma_f32_16x16x32_bf16 v[84:87], v[218:221], v[194:197], v[84:87]
	v_mfma_f32_16x16x32_bf16 v[80:83], v[236:239], v[194:197], v[80:83]
	v_mfma_f32_16x16x32_bf16 v[76:79], v[218:221], v[202:205], v[76:79]
	v_mfma_f32_16x16x32_bf16 v[72:75], v[236:239], v[202:205], v[72:75]
	v_mfma_f32_16x16x32_bf16 v[68:71], v[218:221], v[210:213], v[68:71]
	v_mfma_f32_16x16x32_bf16 v[64:67], v[236:239], v[210:213], v[64:67]
	s_setprio 0
	s_mov_b32 m0, s6
	v_lshl_add_u64 v[242:243], s[38:39], 0, v[158:159]
	s_barrier
	ds_read_b128 v[150:153], v193 offset:16384
	ds_read_b128 v[154:157], v193 offset:17408
	ds_read_b128 v[188:191], v193 offset:18432
	ds_read_b128 v[194:197], v193 offset:19456
	ds_read_b128 v[198:201], v193 offset:20480
	ds_read_b128 v[202:205], v193 offset:21504
	ds_read_b128 v[206:209], v193 offset:22528
	ds_read_b128 v[210:213], v193 offset:23552
	global_load_lds_dwordx4 v[242:243], off
	v_lshl_add_u64 v[244:245], s[38:39], 0, v[162:163]
	s_mov_b32 m0, s7
	s_nop 0
	global_load_lds_dwordx4 v[244:245], off
	s_barrier
	s_waitcnt lgkmcnt(0)
	s_setprio 1
	s_waitcnt lgkmcnt(0)
	v_mfma_f32_16x16x32_bf16 v[60:63], v[134:137], v[150:153], v[60:63]
	v_mfma_f32_16x16x32_bf16 v[56:59], v[142:145], v[150:153], v[56:59]
	v_mfma_f32_16x16x32_bf16 v[52:55], v[134:137], v[188:191], v[52:55]
	v_mfma_f32_16x16x32_bf16 v[48:51], v[142:145], v[188:191], v[48:51]
	v_mfma_f32_16x16x32_bf16 v[44:47], v[134:137], v[198:201], v[44:47]
	v_mfma_f32_16x16x32_bf16 v[40:43], v[142:145], v[198:201], v[40:43]
	v_mfma_f32_16x16x32_bf16 v[36:39], v[134:137], v[206:209], v[36:39]
	v_mfma_f32_16x16x32_bf16 v[32:35], v[142:145], v[206:209], v[32:35]
	v_mfma_f32_16x16x32_bf16 v[60:63], v[138:141], v[154:157], v[60:63]
	v_mfma_f32_16x16x32_bf16 v[56:59], v[146:149], v[154:157], v[56:59]
	v_mfma_f32_16x16x32_bf16 v[52:55], v[138:141], v[194:197], v[52:55]
	v_mfma_f32_16x16x32_bf16 v[48:51], v[146:149], v[194:197], v[48:51]
	v_mfma_f32_16x16x32_bf16 v[44:47], v[138:141], v[202:205], v[44:47]
	v_mfma_f32_16x16x32_bf16 v[40:43], v[146:149], v[202:205], v[40:43]
	v_mfma_f32_16x16x32_bf16 v[36:39], v[138:141], v[210:213], v[36:39]
	v_mfma_f32_16x16x32_bf16 v[32:35], v[146:149], v[210:213], v[32:35]
	s_setprio 0
	s_barrier
; #define PG8_STAGE(bufoff, gbase, voff) do { _Pragma("unroll") for (int _i = 0; _i < 2; ++_i) \
;         __builtin_amdgcn_global_load_lds((const unsigned*)((const char*)(gbase) + (voff)[_i]), (LAS unsigned*)(lds + (bufoff) + ldsw + _i * 8192), 16, 0, 0); } while (0)
; #define PG8_LDA(dst, b, h) do { _Pragma("unroll") for (int m = 0; m < 4; ++m) _Pragma("unroll") for (int k = 0; k < 2; ++k) dst[m][k] = *(const LAS bf16x8*)(lds + PG8_SA(b, h) + aoff + m * 2048 + k * 1024); } while (0)
; #define PG8_LDB(dst, b, h) do { _Pragma("unroll") for (int n = 0; n < 2; ++n) _Pragma("unroll") for (int k = 0; k < 2; ++k) dst[n][k] = *(const LAS bf16x8*)(lds + PG8_SB(b, h) + boff + n * 2048 + k * 1024); } while (0)
; #define PG8_MMA(ai, bj, At, Bt) do { __builtin_amdgcn_s_setprio(1); _Pragma("unroll") for (int m = 0; m < 4; ++m) _Pragma("unroll") for (int n = 0; n < 2; ++n) _Pragma("unroll") for (int k = 0; k < 2; ++k) \
;         acc[ai][bj][m][n] = __builtin_amdgcn_mfma_f32_16x16x32_bf16(Bt[n][k], At[m][k], acc[ai][bj][m][n], 0, 0, 0); __builtin_amdgcn_s_setprio(0); } while (0)
; #define PG8_WAIT_V(n) asm volatile("s_waitcnt vmcnt(" #n ")" ::: "memory")
; #define PG8_WAIT_L(n) asm volatile("s_waitcnt lgkmcnt(" #n ")" ::: "memory")
; #define PG8_BAR __builtin_amdgcn_s_barrier()
; #define PG8_SCHED __builtin_amdgcn_sched_barrier(0)
; template <class Epi, class Sched>
; DI void gemm_phase(LAS unsigned char* lds, const Gemm g, const Sched& S, const Epi& E) {
;     ...
;             PG8_STAGE(PG8_SB(0, 1), b2 + hstep, voffB);
;             PG8_WAIT_V(6); PG8_BAR; PG8_MMA(1, 1, At, B1); PG8_BAR;
;             PG8_LDB(B0, 1, 0); PG8_SCHED; PG8_LDA(At, 1, 0); PG8_STAGE(PG8_SA(0, 1), a2 + hstep, voffA);
;             PG8_WAIT_L(8); PG8_BAR; PG8_WAIT_L(0); PG8_MMA(0, 0, At, B0); PG8_BAR; PG8_SCHED;
;             PG8_LDB(B1, 1, 1); PG8_STAGE(PG8_SB(1, 0), b3, voffB);
;             PG8_BAR; PG8_WAIT_L(0); PG8_MMA(0, 1, At, B1); PG8_BAR;
;             PG8_LDA(At, 1, 1); PG8_STAGE(PG8_SA(1, 0), a3, voffA);
;             PG8_BAR; PG8_WAIT_L(0); PG8_MMA(1, 0, At, B0); PG8_BAR; PG8_SCHED;
	s_add_u32 s0, s24, 0x40000
	s_addc_u32 s1, s25, 0
	s_add_i32 s28, s29, s68
	v_lshl_add_u64 v[134:135], s[0:1], 0, v[160:161]
	s_mov_b32 m0, s28
	s_nop 0
	global_load_lds_dwordx4 v[134:135], off
	v_lshl_add_u64 v[134:135], s[0:1], 0, v[164:165]
	s_add_i32 m0, s28, 0x2000
	s_nop 0
	global_load_lds_dwordx4 v[134:135], off
	s_waitcnt vmcnt(6)
	s_barrier
	s_setprio 1
	v_mfma_f32_16x16x32_bf16 v[28:31], v[214:217], v[150:153], v[28:31]
	v_mfma_f32_16x16x32_bf16 v[24:27], v[222:225], v[150:153], v[24:27]
	v_mfma_f32_16x16x32_bf16 v[20:23], v[214:217], v[188:191], v[20:23]
	v_mfma_f32_16x16x32_bf16 v[16:19], v[222:225], v[188:191], v[16:19]
	v_mfma_f32_16x16x32_bf16 v[12:15], v[214:217], v[198:201], v[12:15]
	v_mfma_f32_16x16x32_bf16 v[8:11], v[222:225], v[198:201], v[8:11]
	v_mfma_f32_16x16x32_bf16 v[4:7], v[214:217], v[206:209], v[4:7]
	v_mfma_f32_16x16x32_bf16 v[0:3], v[222:225], v[206:209], v[0:3]
	v_mfma_f32_16x16x32_bf16 v[28:31], v[218:221], v[154:157], v[28:31]
	v_mfma_f32_16x16x32_bf16 v[24:27], v[236:239], v[154:157], v[24:27]
	v_mfma_f32_16x16x32_bf16 v[20:23], v[218:221], v[194:197], v[20:23]
	v_mfma_f32_16x16x32_bf16 v[16:19], v[236:239], v[194:197], v[16:19]
	v_mfma_f32_16x16x32_bf16 v[12:15], v[218:221], v[202:205], v[12:15]
	v_mfma_f32_16x16x32_bf16 v[8:11], v[236:239], v[202:205], v[8:11]
	v_mfma_f32_16x16x32_bf16 v[4:7], v[218:221], v[210:213], v[4:7]
	v_mfma_f32_16x16x32_bf16 v[0:3], v[236:239], v[210:213], v[0:3]
	s_setprio 0
	s_add_i32 s28, 0, 0x18000
	v_add_u32_e32 v96, s28, v173
	s_barrier
	ds_read_b128 v[134:137], v96
	ds_read_b128 v[138:141], v96 offset:1024
	ds_read_b128 v[142:145], v96 offset:2048
	ds_read_b128 v[146:149], v96 offset:3072
	s_add_u32 s0, s38, 0x40000
	s_addc_u32 s1, s39, 0
	s_mov_b32 m0, s5
	v_lshl_add_u64 v[214:215], s[0:1], 0, v[158:159]
	ds_read_b128 v[150:153], v193 offset:32768
	ds_read_b128 v[154:157], v193 offset:33792
	ds_read_b128 v[188:191], v193 offset:34816
	ds_read_b128 v[194:197], v193 offset:35840
	ds_read_b128 v[198:201], v193 offset:36864
	ds_read_b128 v[202:205], v193 offset:37888
	ds_read_b128 v[206:209], v193 offset:38912
	ds_read_b128 v[210:213], v193 offset:39936
	global_load_lds_dwordx4 v[214:215], off
	v_lshl_add_u64 v[214:215], s[0:1], 0, v[162:163]
	s_mov_b32 m0, s93
	s_nop 0
	global_load_lds_dwordx4 v[214:215], off
	s_waitcnt lgkmcnt(8)
	s_barrier
	s_waitcnt lgkmcnt(0)
	s_setprio 1
	s_waitcnt lgkmcnt(0)
	v_mfma_f32_16x16x32_bf16 v[126:129], v[134:137], v[150:153], v[126:129]
	v_mfma_f32_16x16x32_bf16 v[122:125], v[142:145], v[150:153], v[122:125]
	v_mfma_f32_16x16x32_bf16 v[118:121], v[134:137], v[188:191], v[118:121]
	v_mfma_f32_16x16x32_bf16 v[114:117], v[142:145], v[188:191], v[114:117]
	v_mfma_f32_16x16x32_bf16 v[110:113], v[134:137], v[198:201], v[110:113]
	v_mfma_f32_16x16x32_bf16 v[106:109], v[142:145], v[198:201], v[106:109]
	v_mfma_f32_16x16x32_bf16 v[102:105], v[134:137], v[206:209], v[102:105]
	v_mfma_f32_16x16x32_bf16 v[98:101], v[142:145], v[206:209], v[98:101]
	v_mfma_f32_16x16x32_bf16 v[126:129], v[138:141], v[154:157], v[126:129]
	v_mfma_f32_16x16x32_bf16 v[122:125], v[146:149], v[154:157], v[122:125]
	v_mfma_f32_16x16x32_bf16 v[118:121], v[138:141], v[194:197], v[118:121]
	v_mfma_f32_16x16x32_bf16 v[114:117], v[146:149], v[194:197], v[114:117]
	v_mfma_f32_16x16x32_bf16 v[110:113], v[138:141], v[202:205], v[110:113]
	v_mfma_f32_16x16x32_bf16 v[106:109], v[146:149], v[202:205], v[106:109]
	v_mfma_f32_16x16x32_bf16 v[102:105], v[138:141], v[210:213], v[102:105]
	v_mfma_f32_16x16x32_bf16 v[98:101], v[146:149], v[210:213], v[98:101]
	s_setprio 0
	s_barrier
	s_add_i32 s29, 0, 0x1c000
	s_add_i32 s0, s28, s68
	v_add_u32_e32 v96, s29, v173
	v_lshl_add_u64 v[226:227], v[226:227], 0, s[36:37]
	s_mov_b32 m0, s0
	ds_read_b128 v[214:217], v96
	ds_read_b128 v[218:221], v96 offset:1024
	ds_read_b128 v[222:225], v96 offset:2048
	ds_read_b128 v[236:239], v96 offset:3072
	global_load_lds_dwordx4 v[226:227], off
	v_lshl_add_u64 v[226:227], v[240:241], 0, s[36:37]
	s_add_i32 m0, s0, 0x2000
	s_nop 0
	global_load_lds_dwordx4 v[226:227], off
	s_barrier
	s_waitcnt lgkmcnt(0)
	s_setprio 1
	s_waitcnt lgkmcnt(0)
	v_mfma_f32_16x16x32_bf16 v[92:95], v[214:217], v[150:153], v[92:95]
	v_mfma_f32_16x16x32_bf16 v[88:91], v[222:225], v[150:153], v[88:91]
	v_mfma_f32_16x16x32_bf16 v[84:87], v[214:217], v[188:191], v[84:87]
	v_mfma_f32_16x16x32_bf16 v[80:83], v[222:225], v[188:191], v[80:83]
	v_mfma_f32_16x16x32_bf16 v[76:79], v[214:217], v[198:201], v[76:79]
	v_mfma_f32_16x16x32_bf16 v[72:75], v[222:225], v[198:201], v[72:75]
	v_mfma_f32_16x16x32_bf16 v[68:71], v[214:217], v[206:209], v[68:71]
	v_mfma_f32_16x16x32_bf16 v[64:67], v[222:225], v[206:209], v[64:67]
	v_mfma_f32_16x16x32_bf16 v[92:95], v[218:221], v[154:157], v[92:95]
	v_mfma_f32_16x16x32_bf16 v[88:91], v[236:239], v[154:157], v[88:91]
	v_mfma_f32_16x16x32_bf16 v[84:87], v[218:221], v[194:197], v[84:87]
	v_mfma_f32_16x16x32_bf16 v[80:83], v[236:239], v[194:197], v[80:83]
	v_mfma_f32_16x16x32_bf16 v[76:79], v[218:221], v[202:205], v[76:79]
	v_mfma_f32_16x16x32_bf16 v[72:75], v[236:239], v[202:205], v[72:75]
	v_mfma_f32_16x16x32_bf16 v[68:71], v[218:221], v[210:213], v[68:71]
	v_mfma_f32_16x16x32_bf16 v[64:67], v[236:239], v[210:213], v[64:67]
	s_setprio 0
	s_mov_b32 m0, s50
	v_lshl_add_u64 v[226:227], v[242:243], 0, s[36:37]
	s_barrier
	ds_read_b128 v[150:153], v193 offset:49152
	ds_read_b128 v[154:157], v193 offset:50176
	ds_read_b128 v[188:191], v193 offset:51200
	ds_read_b128 v[194:197], v193 offset:52224
	ds_read_b128 v[198:201], v193 offset:53248
	ds_read_b128 v[202:205], v193 offset:54272
	ds_read_b128 v[206:209], v193 offset:55296
	ds_read_b128 v[210:213], v193 offset:56320
	global_load_lds_dwordx4 v[226:227], off
	v_lshl_add_u64 v[226:227], v[244:245], 0, s[36:37]
	s_mov_b32 m0, s51
	s_nop 0
	global_load_lds_dwordx4 v[226:227], off
	s_barrier
; #define PG8_STAGE(bufoff, gbase, voff) do { _Pragma("unroll") for (int _i = 0; _i < 2; ++_i) \
;         __builtin_amdgcn_global_load_lds((const unsigned*)((const char*)(gbase) + (voff)[_i]), (LAS unsigned*)(lds + (bufoff) + ldsw + _i * 8192), 16, 0, 0); } while (0)
; #define PG8_MMA(ai, bj, At, Bt) do { __builtin_amdgcn_s_setprio(1); _Pragma("unroll") for (int m = 0; m < 4; ++m) _Pragma("unroll") for (int n = 0; n < 2; ++n) _Pragma("unroll") for (int k = 0; k < 2; ++k) \
;         acc[ai][bj][m][n] = __builtin_amdgcn_mfma_f32_16x16x32_bf16(Bt[n][k], At[m][k], acc[ai][bj][m][n], 0, 0, 0); __builtin_amdgcn_s_setprio(0); } while (0)
; #define PG8_WAIT_V(n) asm volatile("s_waitcnt vmcnt(" #n ")" ::: "memory")
; #define PG8_WAIT_L(n) asm volatile("s_waitcnt lgkmcnt(" #n ")" ::: "memory")
; #define PG8_BAR __builtin_amdgcn_s_barrier()
; #define PG8_SCHED __builtin_amdgcn_sched_barrier(0)
; template <class Epi, class Sched>
; DI void gemm_phase(LAS unsigned char* lds, const Gemm g, const Sched& S, const Epi& E) {
;     ...
;             PG8_BAR; PG8_WAIT_L(0); PG8_MMA(1, 0, At, B0); PG8_BAR; PG8_SCHED;
;             PG8_STAGE(PG8_SB(1, 1), b3 + hstep, voffB);
;             PG8_WAIT_V(6); PG8_BAR; PG8_MMA(1, 1, At, B1); PG8_BAR;
;         }
;         if (cur.part < 0) E(acc, cur, wr, wc, fr, fq, lds);
;     DI void operator()(f32x4 (&acc)[2][2][4][2], const Unit& u, int wr, int wc, int fr, int fq, LAS unsigned char* lds) const {
;     ...
;                             const float* rp = ROPE + (size_t)posidx * 16;
;                             const f32x4 cs0 = *(const f32x4*)rp, cs1 = *(const f32x4*)(rp + 4), sn0 = *(const f32x4*)(rp + 8), sn1 = *(const f32x4*)(rp + 12);
	s_waitcnt lgkmcnt(0)
	s_setprio 1
	s_waitcnt lgkmcnt(0)
	v_mfma_f32_16x16x32_bf16 v[60:63], v[134:137], v[150:153], v[60:63]
	v_mfma_f32_16x16x32_bf16 v[56:59], v[142:145], v[150:153], v[56:59]
	v_mfma_f32_16x16x32_bf16 v[52:55], v[134:137], v[188:191], v[52:55]
	v_mfma_f32_16x16x32_bf16 v[48:51], v[142:145], v[188:191], v[48:51]
	v_mfma_f32_16x16x32_bf16 v[44:47], v[134:137], v[198:201], v[44:47]
	v_mfma_f32_16x16x32_bf16 v[40:43], v[142:145], v[198:201], v[40:43]
	v_mfma_f32_16x16x32_bf16 v[36:39], v[134:137], v[206:209], v[36:39]
	v_mfma_f32_16x16x32_bf16 v[32:35], v[142:145], v[206:209], v[32:35]
	v_mfma_f32_16x16x32_bf16 v[60:63], v[138:141], v[154:157], v[60:63]
	v_mfma_f32_16x16x32_bf16 v[56:59], v[146:149], v[154:157], v[56:59]
	v_mfma_f32_16x16x32_bf16 v[52:55], v[138:141], v[194:197], v[52:55]
	v_mfma_f32_16x16x32_bf16 v[48:51], v[146:149], v[194:197], v[48:51]
	v_mfma_f32_16x16x32_bf16 v[44:47], v[138:141], v[202:205], v[44:47]
	v_mfma_f32_16x16x32_bf16 v[40:43], v[146:149], v[202:205], v[40:43]
	v_mfma_f32_16x16x32_bf16 v[36:39], v[138:141], v[210:213], v[36:39]
	v_mfma_f32_16x16x32_bf16 v[32:35], v[146:149], v[210:213], v[32:35]
	s_setprio 0
	s_barrier
	s_add_u32 s0, s24, 0x40080
	s_addc_u32 s1, s25, 0
	s_add_i32 s24, s29, s68
	v_lshl_add_u64 v[134:135], s[0:1], 0, v[160:161]
	s_mov_b32 m0, s24
	s_nop 0
	global_load_lds_dwordx4 v[134:135], off
	v_lshl_add_u64 v[134:135], s[0:1], 0, v[164:165]
	s_add_i32 m0, s24, 0x2000
	s_nop 0
	global_load_lds_dwordx4 v[134:135], off
	s_waitcnt vmcnt(6)
	s_barrier
	s_setprio 1
	v_mfma_f32_16x16x32_bf16 v[28:31], v[214:217], v[150:153], v[28:31]
	v_mfma_f32_16x16x32_bf16 v[24:27], v[222:225], v[150:153], v[24:27]
	v_mfma_f32_16x16x32_bf16 v[20:23], v[214:217], v[188:191], v[20:23]
	v_mfma_f32_16x16x32_bf16 v[16:19], v[222:225], v[188:191], v[16:19]
	v_mfma_f32_16x16x32_bf16 v[12:15], v[214:217], v[198:201], v[12:15]
	v_mfma_f32_16x16x32_bf16 v[8:11], v[222:225], v[198:201], v[8:11]
	v_mfma_f32_16x16x32_bf16 v[4:7], v[214:217], v[206:209], v[4:7]
	v_mfma_f32_16x16x32_bf16 v[0:3], v[222:225], v[206:209], v[0:3]
	v_mfma_f32_16x16x32_bf16 v[28:31], v[218:221], v[154:157], v[28:31]
	v_mfma_f32_16x16x32_bf16 v[24:27], v[236:239], v[154:157], v[24:27]
	v_mfma_f32_16x16x32_bf16 v[20:23], v[218:221], v[194:197], v[20:23]
	v_mfma_f32_16x16x32_bf16 v[16:19], v[236:239], v[194:197], v[16:19]
	v_mfma_f32_16x16x32_bf16 v[12:15], v[218:221], v[202:205], v[12:15]
	v_mfma_f32_16x16x32_bf16 v[8:11], v[236:239], v[202:205], v[8:11]
	v_mfma_f32_16x16x32_bf16 v[4:7], v[218:221], v[210:213], v[4:7]
	v_mfma_f32_16x16x32_bf16 v[0:3], v[236:239], v[210:213], v[0:3]
	s_setprio 0
	s_add_i32 s27, s27, 2
	s_add_u32 s22, s22, 0x100
	s_addc_u32 s23, s23, 0
	s_cmp_lt_u32 s27, 14
	s_barrier
	s_cbranch_scc1 .LBB0_196
	s_cmp_lt_i32 s97, 3
	s_cbranch_scc0 .Lrope_pre_skip
	s_and_b32 s0, s96, 31
	s_lshl_b32 s0, s0, 14
	s_cmpk_lt_i32 s96, 0x80
	s_cselect_b32 s0, s0, 0x80000
	s_add_u32 s0, s82, s0
	s_addc_u32 s1, s83, 0
	v_lshl_add_u32 v216, v229, 4, s6
	v_mov_b32_e32 v217, 0
	v_lshl_add_u64 v[214:215], s[0:1], 0, v[216:217]
	s_add_i32 m0, s6, 0xc000
	s_add_u32 s0, s0, 0x2000
	s_addc_u32 s1, s1, 0
	global_load_lds_dwordx4 v[214:215], off
	v_lshl_add_u64 v[214:215], s[0:1], 0, v[216:217]
	s_add_i32 m0, s6, 0xe000
	s_nop 0
	global_load_lds_dwordx4 v[214:215], off
	s_waitcnt vmcnt(0)
	s_barrier
	s_barrier
; #define LAS __attribute__((address_space(3)))
;     DI void operator()(f32x4 (&acc)[2][2][4][2], const Unit& u, int wr, int wc, int fr, int fq, LAS unsigned char* lds) const {
;     ...
;         { const LAS float* tab = (const LAS float*)(lds + RS_OFF) + u.rk * 256 + wr * 64 + fr;
; #pragma unroll
;           for (int i = 0; i < 8; ++i) rsv[i] = tab[(i >> 2) * 128 + (i & 3) * 16]; }
; #pragma unroll
;         for (int ai = 0; ai < 2; ++ai)
; #pragma unroll
;             for (int m = 0; m < 4; ++m) {
;                 const int row = row0 + ai * 128 + m * 16; const float rs = rsv[ai * 4 + m];
;                 int posidx; long offA, offB;
;                 const bool prm = row < TP;
;                 if (prm) { const int b = row >> 13, t = row & 8191; posidx = t;
;                     offA = t >= 8064 ? ((long)(layer * 4 + b) * 128 + (t - 8064)) * 128 : -1;
;                     offB = t >= 7680 ? ((long)(layer * 4 + b) * 512 + (t - 7680)) * 512 : -1;
;                 } else { const int sb = (row - TP) >> 6, t = (row - TP) & 63; posidx = 8192 + t;
;                     offA = ((long)(layer * 32 + sb) * 128 + 64 + t) * 128;
;                     offB = ((long)(layer * 32 + sb) * 512 + 448 + t) * 512; }
; #pragma unroll
;                 for (int bj = 0; bj < 2; ++bj) {
;                     const int gcol = u.pn * 256 + bj * 128;
;                     f32x4 v0 = acc[ai][bj][m][0] * rs, v1 = acc[ai][bj][m][1] * rs;
;                     if (gcol < 768 && gcol != 640) {
;                         if (rope_wave) {
;                             const float* rp = ROPE + (size_t)posidx * 16;
;                             const f32x4 cs0 = *(const f32x4*)rp, cs1 = *(const f32x4*)(rp + 4), sn0 = *(const f32x4*)(rp + 8), sn1 = *(const f32x4*)(rp + 12);
;                             f32x4 p0, p1;
; #pragma unroll
;                             for (int j = 0; j < 4; ++j) { p0[j] = __shfl_xor(v0[j], 16); p1[j] = __shfl_xor(v1[j], 16); }
;                             if (fq == 0) { v0 = v0 * cs0 - p0 * sn0; v1 = v1 * cs1 - p1 * sn1; }
;                             else if (fq == 1) { v0 = v0 * cs0 + p0 * sn0; v1 = v1 * cs1 + p1 * sn1; }
;                         }
.Lrope_pre_skip:
	v_lshl_add_u32 v96, s4, 10, v175
	ds_read2_b32 v[220:221], v96 offset1:16
	ds_read2_b32 v[204:205], v96 offset0:32 offset1:48
	ds_read2_b32 v[198:199], v96 offset0:128 offset1:144
	ds_read2_b32 v[194:195], v96 offset0:160 offset1:176
	v_lshl_add_u32 v192, s96, 8, v171
	v_add_u32_e32 v96, 0xffff8000, v192
	s_movk_i32 s0, 0x7fff
	v_lshrrev_b32_e32 v96, 6, v96
	v_cmp_lt_i32_e32 vcc, s0, v192
	v_readlane_b32 s0, v246, 32
	s_waitcnt lgkmcnt(0)
	v_mov_b32_e32 v206, v221
	v_mov_b32_e32 v200, v205
	v_mov_b32_e32 v196, v199
	v_mov_b32_e32 v188, v195
	v_add_u32_e32 v202, s0, v96
	s_and_saveexec_b64 s[0:1], vcc
	s_xor_b64 s[22:23], exec, s[0:1]
	v_mov_b32_e32 v203, v97
	v_lshlrev_b64 v[208:209], 14, v[202:203]
	v_lshlrev_b64 v[214:215], 18, v[202:203]
	v_or_b32_e32 v208, v208, v168
	v_or_b32_e32 v214, v214, v170
	s_or_saveexec_b64 s[22:23], s[22:23]
	v_ashrrev_i32_e32 v189, 13, v192
	v_mov_b64_e32 v[210:211], 0x2640000
	v_mov_b64_e32 v[212:213], 0x2740000
	v_mov_b64_e32 v[216:217], 0x2840000
	v_mov_b64_e32 v[218:219], 0x3840000
	v_mov_b32_e32 v130, v177
	s_xor_b64 exec, exec, s[22:23]
	s_cbranch_execz .LBB0_205
	v_and_b32_e32 v130, 0x1fcf, v192
	s_movk_i32 s0, 0x1f7f
	v_cmp_lt_u32_e32 vcc, s0, v130
	v_mov_b64_e32 v[214:215], -1
	v_mov_b64_e32 v[208:209], -1
	s_and_saveexec_b64 s[24:25], vcc
	v_add_u32_e32 v132, s92, v189
	v_ashrrev_i32_e32 v133, 31, v132
	v_add_u32_e32 v96, 0xffffe080, v130
	v_lshlrev_b64 v[132:133], 14, v[132:133]
	v_lshlrev_b64 v[134:135], 7, v[96:97]
	v_lshl_add_u64 v[208:209], v[132:133], 0, v[134:135]
	s_or_b64 exec, exec, s[24:25]
	s_movk_i32 s0, 0x1dff
	v_cmp_lt_u32_e32 vcc, s0, v130
	s_and_saveexec_b64 s[24:25], vcc
	v_add_u32_e32 v132, s92, v189
	v_ashrrev_i32_e32 v133, 31, v132
	v_add_u32_e32 v96, 0xffffe200, v130
	v_lshlrev_b64 v[132:133], 18, v[132:133]
	v_lshlrev_b64 v[134:135], 9, v[96:97]
	v_lshl_add_u64 v[214:215], v[132:133], 0, v[134:135]
	s_or_b64 exec, exec, s[24:25]
	v_mov_b64_e32 v[210:211], 0x2200000
	v_mov_b64_e32 v[212:213], 0x2220000
	v_mov_b64_e32 v[216:217], 0x2240000
	v_mov_b64_e32 v[218:219], 0x2440000
.LBB0_205:
	s_or_b64 exec, exec, s[22:23]
	s_cmp_lt_i32 s97, 3
	s_cselect_b64 s[0:1], -1, 0
	v_lshlrev_b32_e32 v96, 6, v130
	s_and_b64 s[0:1], s[52:53], s[0:1]
	v_lshl_add_u64 v[222:223], s[82:83], 0, v[96:97]
	v_cndmask_b32_e64 v96, 0, 1, s[0:1]
	v_pk_mul_f32 v[136:137], v[128:129], v[220:221] op_sel_hi:[1,0]
	v_pk_mul_f32 v[134:135], v[126:127], v[220:221] op_sel_hi:[1,0]
	v_pk_mul_f32 v[132:133], v[124:125], v[220:221] op_sel_hi:[1,0]
	v_cmp_ne_u32_e64 s[38:39], 1, v96
	s_andn2_b64 vcc, exec, s[0:1]
	v_pk_mul_f32 v[130:131], v[122:123], v[220:221] op_sel_hi:[1,0]
	s_cbranch_vccnz .LBB0_213
	v_and_b32_e32 v138, 64, v229
	v_xor_b32_e32 v96, 16, v229
	v_add_u32_e32 v138, 64, v138
	v_cmp_lt_i32_e32 vcc, v96, v138
	v_subrev_u32_e32 v148, s82, v222
	v_and_b32_e32 v148, 0x3fff, v148
	ds_read_b128 v[144:147], v148 offset:49200
	ds_read_b128 v[154:157], v148 offset:49184
	ds_read_b128 v[138:141], v148 offset:49168
	ds_read_b128 v[148:151], v148 offset:49152
	v_cndmask_b32_e32 v96, v229, v96, vcc
	v_lshlrev_b32_e32 v96, 2, v96
	ds_bpermute_b32 v152, v96, v134
	ds_bpermute_b32 v142, v96, v130
	ds_bpermute_b32 v153, v96, v135
	ds_bpermute_b32 v143, v96, v131
	ds_bpermute_b32 v224, v96, v136
	ds_bpermute_b32 v190, v96, v132
	ds_bpermute_b32 v225, v96, v137
	ds_bpermute_b32 v191, v96, v133
	v_cmp_lt_i32_e32 vcc, 0, v169
	s_and_saveexec_b64 s[0:1], vcc
	s_xor_b64 s[22:23], exec, s[0:1]
	s_cbranch_execz .LBB0_210
	v_cmp_eq_u32_e32 vcc, 1, v169
	s_and_saveexec_b64 s[24:25], vcc
	s_cbranch_execz .LBB0_209
	s_waitcnt lgkmcnt(0)
	v_pk_mul_f32 v[156:157], v[156:157], v[224:225]
	v_pk_mul_f32 v[152:153], v[154:155], v[152:153]
	v_pk_mul_f32 v[146:147], v[146:147], v[190:191]
	v_pk_mul_f32 v[142:143], v[144:145], v[142:143]
	v_pk_fma_f32 v[136:137], v[136:137], v[150:151], v[156:157]
	v_pk_fma_f32 v[134:135], v[134:135], v[148:149], v[152:153]
	v_pk_fma_f32 v[132:133], v[132:133], v[140:141], v[146:147]
	v_pk_fma_f32 v[130:131], v[130:131], v[138:139], v[142:143]

;     DI void operator()(f32x4 (&acc)[2][2][4][2], const Unit& u, int wr, int wc, int fr, int fq, LAS unsigned char* lds) const {
;     ...
;                             if (fq == 0) { v0 = v0 * cs0 - p0 * sn0; v1 = v1 * cs1 - p1 * sn1; }
;                             else if (fq == 1) { v0 = v0 * cs0 + p0 * sn0; v1 = v1 * cs1 + p1 * sn1; }
.LBB0_210:
	s_andn2_saveexec_b64 s[22:23], s[22:23]
	s_cbranch_execz .LBB0_212
	s_waitcnt lgkmcnt(0)
	v_pk_mul_f32 v[156:157], v[156:157], v[224:225]
	v_pk_mul_f32 v[152:153], v[154:155], v[152:153]
	v_pk_mul_f32 v[146:147], v[146:147], v[190:191]
	v_pk_mul_f32 v[142:143], v[144:145], v[142:143]
	v_pk_fma_f32 v[136:137], v[136:137], v[150:151], v[156:157] neg_lo:[0,0,1] neg_hi:[0,0,1]
	v_pk_fma_f32 v[134:135], v[134:135], v[148:149], v[152:153] neg_lo:[0,0,1] neg_hi:[0,0,1]
	v_pk_fma_f32 v[132:133], v[132:133], v[140:141], v[146:147] neg_lo:[0,0,1] neg_hi:[0,0,1]
	v_pk_fma_f32 v[130:131], v[130:131], v[138:139], v[142:143] neg_lo:[0,0,1] neg_hi:[0,0,1]

; #define LAS __attribute__((address_space(3)))
; DI float sigmoidf_(float a) { return fast_rcp(1.0f + fast_exp2(-a * LOG2E)); }
;     DI void operator()(f32x4 (&acc)[2][2][4][2], const Unit& u, int wr, int wc, int fr, int fq, LAS unsigned char* lds) const {
;     ...
;                     bf16_t* dst; int ld, c0; float* of = nullptr; long orow = -1;
;                     if (gcol < 512) { dst = QA; ld = 512; c0 = gcol; v0 = v0 * QSCALE; v1 = v1 * QSCALE; }
;                     else if (gcol < 640) { dst = KA; ld = 128; c0 = gcol - 512; of = out + (prm ? O_KWP : O_KWS); orow = offA; }
;                     else if (gcol < 768) { dst = VA; ld = 128; c0 = gcol - 640; of = out + (prm ? O_VWP : O_VWS); orow = offA; }
;                     else if (gcol < 1280) { dst = QB; ld = 512; c0 = gcol - 768; v0 = v0 * QSCALE; v1 = v1 * QSCALE; }
;                     else if (gcol < 1792) { dst = KB; ld = 512; c0 = gcol - 1280; of = out + (prm ? O_KBP : O_KBS); orow = offB; }
;                     else if (gcol < 2304) { dst = VB; ld = 512; c0 = gcol - 1792; of = out + (prm ? O_VBP : O_VBS); orow = offB; }
;                     else { dst = GATES; ld = 2048; c0 = gcol - 2304;
;                         const f32x4 g0 = *(const LAS f32x4*)(lds + BG_OFF + (c0 + cw) * 4), g1 = *(const LAS f32x4*)(lds + BG_OFF + (c0 + cw + 4) * 4);
; #pragma unroll
;                         for (int j = 0; j < 4; ++j) { v0[j] = sigmoidf_(v0[j] + g0[j]); v1[j] = sigmoidf_(v1[j] + g1[j]); } }
.LBB0_213:
	s_lshl_b32 s11, s97, 8
	s_cmp_gt_i32 s97, 1
	s_cselect_b64 s[44:45], -1, 0
	v_mov_b32_e32 v221, v220
	s_mov_b64 s[24:25], -1
	s_and_b64 vcc, exec, s[44:45]
	s_cbranch_vccz .LBB0_232
	s_cmpk_gt_u32 s11, 0x27f
	s_cbranch_scc0 .LBB0_229
	s_cmpk_gt_u32 s11, 0x4ff
	s_cbranch_scc0 .LBB0_226
	s_cmpk_gt_u32 s11, 0x6ff
	s_cbranch_scc0 .LBB0_223
	s_cmpk_gt_u32 s11, 0x8ff
	s_cbranch_scc0 .LBB0_219
	s_add_i32 s22, s11, 0xfffff700
	v_or_b32_e32 v96, s22, v166
	v_lshl_add_u32 v96, v96, 2, 0
	v_add_u32_e32 v96, 0x23040, v96
	s_waitcnt lgkmcnt(0)
	ds_read_b128 v[138:141], v96
	s_waitcnt lgkmcnt(5)
	ds_read_b128 v[142:145], v96 offset:16
	s_mov_b64 s[24:25], 0
	s_waitcnt lgkmcnt(1)
	v_add_f32_e32 v96, v134, v138
	s_waitcnt lgkmcnt(0)
	v_add_f32_e32 v138, v130, v142
	v_mul_f32_e32 v96, 0xbfb8aa3b, v96
	v_mul_f32_e32 v138, 0xbfb8aa3b, v138
	v_exp_f32_e32 v96, v96
	v_exp_f32_e32 v138, v138
	v_add_f32_e32 v139, v135, v139
	v_mul_f32_e32 v139, 0xbfb8aa3b, v139
	v_add_f32_e32 v96, 1.0, v96
	v_add_f32_e32 v142, 1.0, v138
	v_rcp_f32_e32 v138, v96
	v_exp_f32_e32 v96, v139
	v_add_f32_e32 v139, v131, v143
	v_mul_f32_e32 v139, 0xbfb8aa3b, v139
	v_exp_f32_e32 v143, v139
	v_add_f32_e32 v96, 1.0, v96
	v_add_f32_e32 v140, v136, v140
	v_rcp_f32_e32 v139, v96
	v_add_f32_e32 v96, 1.0, v143
	v_mul_f32_e32 v140, 0xbfb8aa3b, v140
	v_add_f32_e32 v143, v132, v144
	v_exp_f32_e32 v140, v140
	v_mul_f32_e32 v143, 0xbfb8aa3b, v143
	v_exp_f32_e32 v144, v143
	v_rcp_f32_e32 v143, v96
	v_add_f32_e32 v96, 1.0, v140
	v_add_f32_e32 v141, v137, v141
	v_rcp_f32_e32 v140, v96
	v_add_f32_e32 v96, 1.0, v144
	v_mul_f32_e32 v141, 0xbfb8aa3b, v141
	v_add_f32_e32 v144, v133, v145
	v_exp_f32_e32 v141, v141
	v_mul_f32_e32 v144, 0xbfb8aa3b, v144
	v_exp_f32_e32 v145, v144
	v_rcp_f32_e32 v144, v96
	v_add_f32_e32 v96, 1.0, v141
	v_rcp_f32_e32 v141, v96
	v_add_f32_e32 v96, 1.0, v145
	v_rcp_f32_e32 v142, v142
	v_rcp_f32_e32 v145, v96
.LBB0_219:
	s_andn2_b64 vcc, exec, s[24:25]
	s_cbranch_vccnz .LBB0_221
	v_lshlrev_b32_e32 v96, 2, v218
	v_readlane_b32 s28, v250, 42
	s_waitcnt lgkmcnt(0)
	v_mov_b64_e32 v[144:145], v[132:133]
	v_mov_b64_e32 v[140:141], v[136:137]
	s_add_i32 s22, s11, 0xfffff900
	v_lshl_add_u64 v[146:147], s[90:91], 0, v[96:97]
	s_mov_b64 s[26:27], 0x200
	v_mov_b64_e32 v[148:149], v[214:215]
	v_readlane_b32 s29, v250, 43
	v_mov_b64_e32 v[142:143], v[130:131]
	v_mov_b64_e32 v[138:139], v[134:135]
	s_branch .LBB0_222
.LBB0_221:
	v_readlane_b32 s28, v250, 38
	s_mov_b64 s[26:27], 0x800
	s_waitcnt lgkmcnt(0)
	v_mov_b64_e32 v[146:147], 0
	v_mov_b64_e32 v[148:149], -1
	v_readlane_b32 s29, v250, 39

;     DI void operator()(f32x4 (&acc)[2][2][4][2], const Unit& u, int wr, int wc, int fr, int fq, LAS unsigned char* lds) const {
;     ...
;                     if (gcol < 512) { dst = QA; ld = 512; c0 = gcol; v0 = v0 * QSCALE; v1 = v1 * QSCALE; }
;                     else if (gcol < 640) { dst = KA; ld = 128; c0 = gcol - 512; of = out + (prm ? O_KWP : O_KWS); orow = offA; }
;                     else if (gcol < 768) { dst = VA; ld = 128; c0 = gcol - 640; of = out + (prm ? O_VWP : O_VWS); orow = offA; }
;                     else if (gcol < 1280) { dst = QB; ld = 512; c0 = gcol - 768; v0 = v0 * QSCALE; v1 = v1 * QSCALE; }
;                     else if (gcol < 1792) { dst = KB; ld = 512; c0 = gcol - 1280; of = out + (prm ? O_KBP : O_KBS); orow = offB; }
;                     else if (gcol < 2304) { dst = VB; ld = 512; c0 = gcol - 1792; of = out + (prm ? O_VBP : O_VBS); orow = offB; }
.LBB0_223:
	s_andn2_b64 vcc, exec, s[24:25]
	s_cbranch_vccnz .LBB0_225
	v_readlane_b32 s0, v250, 46
	v_lshlrev_b32_e32 v96, 2, v216
	v_readlane_b32 s1, v250, 47
	s_waitcnt lgkmcnt(0)
	v_mov_b64_e32 v[144:145], v[132:133]
	v_mov_b64_e32 v[140:141], v[136:137]
	s_add_i32 s22, s11, 0xfffffb00
	v_lshl_add_u64 v[146:147], s[90:91], 0, v[96:97]
	v_mov_b64_e32 v[150:151], s[0:1]
	v_mov_b64_e32 v[152:153], 0x200
	v_mov_b64_e32 v[148:149], v[214:215]
	v_mov_b64_e32 v[142:143], v[130:131]
	v_mov_b64_e32 v[138:139], v[134:135]

;     DI void operator()(f32x4 (&acc)[2][2][4][2], const Unit& u, int wr, int wc, int fr, int fq, LAS unsigned char* lds) const {
;     ...
;                     if (gcol < 512) { dst = QA; ld = 512; c0 = gcol; v0 = v0 * QSCALE; v1 = v1 * QSCALE; }
;                     else if (gcol < 640) { dst = KA; ld = 128; c0 = gcol - 512; of = out + (prm ? O_KWP : O_KWS); orow = offA; }
;                     else if (gcol < 768) { dst = VA; ld = 128; c0 = gcol - 640; of = out + (prm ? O_VWP : O_VWS); orow = offA; }
;                     else if (gcol < 1280) { dst = QB; ld = 512; c0 = gcol - 768; v0 = v0 * QSCALE; v1 = v1 * QSCALE; }
.LBB0_226:
	s_andn2_b64 vcc, exec, s[24:25]
	s_cbranch_vccnz .LBB0_228
	v_readlane_b32 s0, v250, 44
	v_readlane_b32 s1, v250, 45
	s_add_i32 s22, s11, 0xfffffd00
	s_waitcnt lgkmcnt(0)
	v_pk_mul_f32 v[140:141], v[136:137], s[66:67] op_sel_hi:[1,0]
	v_pk_mul_f32 v[138:139], v[134:135], s[66:67] op_sel_hi:[1,0]
	v_pk_mul_f32 v[144:145], v[132:133], s[66:67] op_sel_hi:[1,0]
	s_waitcnt lgkmcnt(4)
	v_pk_mul_f32 v[142:143], v[130:131], s[66:67] op_sel_hi:[1,0]
	v_mov_b64_e32 v[146:147], 0
	v_mov_b64_e32 v[148:149], -1
	v_mov_b64_e32 v[150:151], s[0:1]
	v_mov_b64_e32 v[152:153], 0x200

;     DI void operator()(f32x4 (&acc)[2][2][4][2], const Unit& u, int wr, int wc, int fr, int fq, LAS unsigned char* lds) const {
;     ...
;                     if (gcol < 512) { dst = QA; ld = 512; c0 = gcol; v0 = v0 * QSCALE; v1 = v1 * QSCALE; }
;                     else if (gcol < 640) { dst = KA; ld = 128; c0 = gcol - 512; of = out + (prm ? O_KWP : O_KWS); orow = offA; }
;                     else if (gcol < 768) { dst = VA; ld = 128; c0 = gcol - 640; of = out + (prm ? O_VWP : O_VWS); orow = offA; }
.LBB0_229:
	s_andn2_b64 vcc, exec, s[24:25]
	s_cbranch_vccnz .LBB0_231
	v_lshlrev_b32_e32 v96, 2, v210
	s_waitcnt lgkmcnt(0)
	v_mov_b64_e32 v[144:145], v[132:133]
	v_mov_b64_e32 v[140:141], v[136:137]
	s_add_i32 s22, s11, 0xfffffe00
	v_lshl_add_u64 v[146:147], s[90:91], 0, v[96:97]
	v_mov_b64_e32 v[150:151], s[78:79]
	v_mov_b64_e32 v[152:153], 0x80
	v_mov_b64_e32 v[148:149], v[208:209]
	v_mov_b64_e32 v[142:143], v[130:131]
	v_mov_b64_e32 v[138:139], v[134:135]

; #define LAS __attribute__((address_space(3)))
;     DI void operator()(f32x4 (&acc)[2][2][4][2], const Unit& u, int wr, int wc, int fr, int fq, LAS unsigned char* lds) const {
;     ...
;                 for (int bj = 0; bj < 2; ++bj) {
;                     const int gcol = u.pn * 256 + bj * 128;
;                     f32x4 v0 = acc[ai][bj][m][0] * rs, v1 = acc[ai][bj][m][1] * rs;
;                     if (gcol < 768 && gcol != 640) {
;                         if (rope_wave) {
;                             const float* rp = ROPE + (size_t)posidx * 16;
;                             const f32x4 cs0 = *(const f32x4*)rp, cs1 = *(const f32x4*)(rp + 4), sn0 = *(const f32x4*)(rp + 8), sn1 = *(const f32x4*)(rp + 12);
;                             f32x4 p0, p1;
; #pragma unroll
;                             for (int j = 0; j < 4; ++j) { p0[j] = __shfl_xor(v0[j], 16); p1[j] = __shfl_xor(v1[j], 16); }
;                             if (fq == 0) { v0 = v0 * cs0 - p0 * sn0; v1 = v1 * cs1 - p1 * sn1; }
;                             else if (fq == 1) { v0 = v0 * cs0 + p0 * sn0; v1 = v1 * cs1 + p1 * sn1; }
;                         }
;                     }
;                     bf16_t* dst; int ld, c0; float* of = nullptr; long orow = -1;
;                     if (gcol < 512) { dst = QA; ld = 512; c0 = gcol; v0 = v0 * QSCALE; v1 = v1 * QSCALE; }
;                     else if (gcol < 640) { dst = KA; ld = 128; c0 = gcol - 512; of = out + (prm ? O_KWP : O_KWS); orow = offA; }
;                     else if (gcol < 768) { dst = VA; ld = 128; c0 = gcol - 640; of = out + (prm ? O_VWP : O_VWS); orow = offA; }
;                     else if (gcol < 1280) { dst = QB; ld = 512; c0 = gcol - 768; v0 = v0 * QSCALE; v1 = v1 * QSCALE; }
;                     else if (gcol < 1792) { dst = KB; ld = 512; c0 = gcol - 1280; of = out + (prm ? O_KBP : O_KBS); orow = offB; }
;                     else if (gcol < 2304) { dst = VB; ld = 512; c0 = gcol - 1792; of = out + (prm ? O_VBP : O_VBS); orow = offB; }
;                     else { dst = GATES; ld = 2048; c0 = gcol - 2304;
;                         const f32x4 g0 = *(const LAS f32x4*)(lds + BG_OFF + (c0 + cw) * 4), g1 = *(const LAS f32x4*)(lds + BG_OFF + (c0 + cw + 4) * 4);
; #pragma unroll
;                         for (int j = 0; j < 4; ++j) { v0[j] = sigmoidf_(v0[j] + g0[j]); v1[j] = sigmoidf_(v1[j] + g1[j]); } }
.LBB0_232:
	s_andn2_b64 vcc, exec, s[24:25]
	s_cbranch_vccnz .LBB0_234
	s_waitcnt lgkmcnt(0)
	v_pk_mul_f32 v[140:141], v[136:137], s[66:67] op_sel_hi:[1,0]
	v_pk_mul_f32 v[138:139], v[134:135], s[66:67] op_sel_hi:[1,0]
	v_pk_mul_f32 v[144:145], v[132:133], s[66:67] op_sel_hi:[1,0]
	s_waitcnt lgkmcnt(4)
	v_pk_mul_f32 v[142:143], v[130:131], s[66:67] op_sel_hi:[1,0]
	v_mov_b64_e32 v[148:149], -1
	v_mov_b64_e32 v[146:147], 0
	v_mov_b64_e32 v[150:151], s[74:75]
	v_mov_b64_e32 v[152:153], 0x200
	s_mov_b32 s22, s11
.LBB0_234:
	v_ashrrev_i32_e32 v167, 31, v192
	s_waitcnt lgkmcnt(0)
	v_mul_lo_u32 v96, v153, v192
	v_mul_lo_u32 v136, v152, v167
	v_mad_u64_u32 v[134:135], s[0:1], v152, v192, 0
	v_add3_u32 v135, v135, v136, v96
	s_waitcnt lgkmcnt(0)
	v_lshl_add_u64 v[134:135], v[134:135], 1, v[150:151]
	s_ashr_i32 s23, s22, 31
	v_lshl_add_u64 v[134:135], s[22:23], 1, v[134:135]
	v_lshlrev_b32_e32 v96, 1, v166
	v_cmp_ne_u64_e32 vcc, 0, v[146:147]
	v_cmp_lt_i64_e64 s[40:41], -1, v[148:149]
	v_cvt_pk_bf16_f32 v130, v138, v139
	v_cvt_pk_bf16_f32 v131, v140, v141
	v_cvt_pk_bf16_f32 v132, v142, v143
	v_cvt_pk_bf16_f32 v133, v144, v145
	v_lshl_add_u64 v[134:135], v[134:135], 0, v[96:97]
	s_and_b64 s[0:1], vcc, s[40:41]
	v_lshlrev_b32_e32 v190, 2, v166
	global_store_dwordx4 v[134:135], v[130:133], off
	s_and_saveexec_b64 s[24:25], s[0:1]
	s_cbranch_execz .LBB0_236
	v_lshl_add_u64 v[130:131], v[148:149], 2, v[146:147]
	v_lshl_add_u64 v[130:131], s[22:23], 2, v[130:131]
	v_mov_b32_e32 v191, v97
	v_lshl_add_u64 v[130:131], v[130:131], 0, v[190:191]
	global_store_dwordx4 v[130:131], v[138:141], off
	global_store_dwordx4 v[130:131], v[142:145], off offset:16
.LBB0_236:
	s_or_b64 exec, exec, s[24:25]
	s_or_b32 s13, s11, 0x80
	s_cmpk_gt_i32 s13, 0x2ff
	s_cselect_b64 s[22:23], -1, 0
	s_cmpk_lt_i32 s13, 0x300
	s_cselect_b64 s[0:1], -1, 0
	s_cmp_lg_u32 s97, 2
	s_cselect_b64 s[24:25], -1, 0
	s_and_b64 s[24:25], s[52:53], s[24:25]
	v_mov_b32_e32 v130, v220
	v_mov_b32_e32 v131, v220
	s_and_b64 s[0:1], s[24:25], s[0:1]
	v_pk_mul_f32 v[136:137], v[94:95], v[130:131]
	v_pk_mul_f32 v[132:133], v[90:91], v[130:131]
	v_cndmask_b32_e64 v130, 0, 1, s[0:1]
	v_pk_mul_f32 v[134:135], v[92:93], v[220:221]
	v_cmp_ne_u32_e64 s[40:41], 1, v130
	s_andn2_b64 vcc, exec, s[0:1]
	v_pk_mul_f32 v[130:131], v[88:89], v[220:221]
	s_cbranch_vccnz .LBB0_244
	v_and_b32_e32 v139, 64, v229
	v_xor_b32_e32 v138, 16, v229
	v_add_u32_e32 v139, 64, v139
	v_cmp_lt_i32_e32 vcc, v138, v139
	s_nop 1
	v_cndmask_b32_e32 v138, v229, v138, vcc
	v_lshlrev_b32_e32 v138, 2, v138
	ds_bpermute_b32 v152, v138, v134
	ds_bpermute_b32 v142, v138, v130
	ds_bpermute_b32 v153, v138, v135
	ds_bpermute_b32 v143, v138, v131
	ds_bpermute_b32 v224, v138, v136
	ds_bpermute_b32 v220, v138, v132
	ds_bpermute_b32 v225, v138, v137
	ds_bpermute_b32 v221, v138, v133
	v_subrev_u32_e32 v148, s82, v222
	v_and_b32_e32 v148, 0x3fff, v148
	ds_read_b128 v[144:147], v148 offset:49200
	ds_read_b128 v[154:157], v148 offset:49184
	ds_read_b128 v[138:141], v148 offset:49168
	ds_read_b128 v[148:151], v148 offset:49152
	v_cmp_lt_i32_e32 vcc, 0, v169
	s_and_saveexec_b64 s[0:1], vcc
	s_xor_b64 s[24:25], exec, s[0:1]
	s_cbranch_execz .LBB0_241
	v_cmp_eq_u32_e32 vcc, 1, v169
	s_and_saveexec_b64 s[26:27], vcc
	s_cbranch_execz .LBB0_240
	s_waitcnt lgkmcnt(0)
	v_pk_mul_f32 v[156:157], v[156:157], v[224:225]
	v_pk_mul_f32 v[152:153], v[154:155], v[152:153]
	s_waitcnt lgkmcnt(0)
	v_pk_mul_f32 v[146:147], v[146:147], v[220:221]
	v_pk_mul_f32 v[142:143], v[144:145], v[142:143]
	s_waitcnt lgkmcnt(0)
	v_pk_fma_f32 v[136:137], v[136:137], v[150:151], v[156:157]
	v_pk_fma_f32 v[134:135], v[134:135], v[148:149], v[152:153]
	v_pk_fma_f32 v[132:133], v[132:133], v[140:141], v[146:147]
	v_pk_fma_f32 v[130:131], v[130:131], v[138:139], v[142:143]

;     DI void operator()(f32x4 (&acc)[2][2][4][2], const Unit& u, int wr, int wc, int fr, int fq, LAS unsigned char* lds) const {
;     ...
;                             if (fq == 0) { v0 = v0 * cs0 - p0 * sn0; v1 = v1 * cs1 - p1 * sn1; }
;                             else if (fq == 1) { v0 = v0 * cs0 + p0 * sn0; v1 = v1 * cs1 + p1 * sn1; }
.LBB0_241:
	s_andn2_saveexec_b64 s[24:25], s[24:25]
	s_cbranch_execz .LBB0_243
	s_waitcnt lgkmcnt(0)
	v_pk_mul_f32 v[156:157], v[156:157], v[224:225]
	v_pk_mul_f32 v[152:153], v[154:155], v[152:153]
	s_waitcnt lgkmcnt(0)
	v_pk_mul_f32 v[146:147], v[146:147], v[220:221]
	v_pk_mul_f32 v[142:143], v[144:145], v[142:143]
	s_waitcnt lgkmcnt(0)
	v_pk_fma_f32 v[136:137], v[136:137], v[150:151], v[156:157] neg_lo:[0,0,1] neg_hi:[0,0,1]
	v_pk_fma_f32 v[134:135], v[134:135], v[148:149], v[152:153] neg_lo:[0,0,1] neg_hi:[0,0,1]
	v_pk_fma_f32 v[132:133], v[132:133], v[140:141], v[146:147] neg_lo:[0,0,1] neg_hi:[0,0,1]
	v_pk_fma_f32 v[130:131], v[130:131], v[138:139], v[142:143] neg_lo:[0,0,1] neg_hi:[0,0,1]

; #define LAS __attribute__((address_space(3)))
; DI float sigmoidf_(float a) { return fast_rcp(1.0f + fast_exp2(-a * LOG2E)); }
;     DI void operator()(f32x4 (&acc)[2][2][4][2], const Unit& u, int wr, int wc, int fr, int fq, LAS unsigned char* lds) const {
;     ...
;                     bf16_t* dst; int ld, c0; float* of = nullptr; long orow = -1;
;                     if (gcol < 512) { dst = QA; ld = 512; c0 = gcol; v0 = v0 * QSCALE; v1 = v1 * QSCALE; }
;                     else if (gcol < 640) { dst = KA; ld = 128; c0 = gcol - 512; of = out + (prm ? O_KWP : O_KWS); orow = offA; }
;                     else if (gcol < 768) { dst = VA; ld = 128; c0 = gcol - 640; of = out + (prm ? O_VWP : O_VWS); orow = offA; }
;                     else if (gcol < 1280) { dst = QB; ld = 512; c0 = gcol - 768; v0 = v0 * QSCALE; v1 = v1 * QSCALE; }
;                     else if (gcol < 1792) { dst = KB; ld = 512; c0 = gcol - 1280; of = out + (prm ? O_KBP : O_KBS); orow = offB; }
;                     else if (gcol < 2304) { dst = VB; ld = 512; c0 = gcol - 1792; of = out + (prm ? O_VBP : O_VBS); orow = offB; }
;                     else { dst = GATES; ld = 2048; c0 = gcol - 2304;
;                         const f32x4 g0 = *(const LAS f32x4*)(lds + BG_OFF + (c0 + cw) * 4), g1 = *(const LAS f32x4*)(lds + BG_OFF + (c0 + cw + 4) * 4);
; #pragma unroll
;                         for (int j = 0; j < 4; ++j) { v0[j] = sigmoidf_(v0[j] + g0[j]); v1[j] = sigmoidf_(v1[j] + g1[j]); } }
.LBB0_244:
	s_cmpk_gt_i32 s13, 0x1ff
	s_cselect_b64 s[46:47], -1, 0
	s_cmpk_lt_i32 s13, 0x200
	s_mov_b64 s[26:27], -1
	s_cbranch_scc1 .LBB0_267
	s_cmpk_lt_u32 s13, 0x280
	s_cbranch_scc1 .LBB0_264
	s_andn2_b64 vcc, exec, s[22:23]
	s_cbranch_vccnz .LBB0_261
	s_cmpk_lt_u32 s11, 0x500
	s_cbranch_scc1 .LBB0_258
	s_cmpk_lt_u32 s11, 0x700
	s_cbranch_scc1 .LBB0_255
	s_cmpk_lt_u32 s11, 0x900
	s_cbranch_scc1 .LBB0_251
	s_add_i32 s24, s11, 0xfffff780
	s_waitcnt lgkmcnt(0)
	v_or_b32_e32 v138, s24, v166
	v_lshl_add_u32 v138, v138, 2, 0
	s_waitcnt lgkmcnt(6)
	v_add_u32_e32 v142, 0x23040, v138
	ds_read_b128 v[138:141], v142
	s_waitcnt lgkmcnt(5)
	ds_read_b128 v[142:145], v142 offset:16
	s_mov_b64 s[26:27], 0
	s_waitcnt lgkmcnt(1)
	v_add_f32_e32 v138, v134, v138
	s_waitcnt lgkmcnt(0)
	v_add_f32_e32 v142, v130, v142
	v_add_f32_e32 v139, v135, v139
	v_add_f32_e32 v143, v131, v143
	v_add_f32_e32 v140, v136, v140
	v_add_f32_e32 v144, v132, v144
	v_add_f32_e32 v141, v137, v141
	v_add_f32_e32 v145, v133, v145
	v_mul_f32_e32 v138, 0xbfb8aa3b, v138
	v_mul_f32_e32 v142, 0xbfb8aa3b, v142
	v_mul_f32_e32 v139, 0xbfb8aa3b, v139
	v_mul_f32_e32 v143, 0xbfb8aa3b, v143
	v_mul_f32_e32 v140, 0xbfb8aa3b, v140
	v_mul_f32_e32 v144, 0xbfb8aa3b, v144
	v_mul_f32_e32 v141, 0xbfb8aa3b, v141
	v_mul_f32_e32 v145, 0xbfb8aa3b, v145
	v_exp_f32_e32 v138, v138
	v_exp_f32_e32 v142, v142
	v_exp_f32_e32 v139, v139
	v_exp_f32_e32 v143, v143
	v_exp_f32_e32 v140, v140
	v_exp_f32_e32 v144, v144
	v_exp_f32_e32 v141, v141
	v_exp_f32_e32 v145, v145
	v_add_f32_e32 v138, 1.0, v138
	v_add_f32_e32 v142, 1.0, v142
	v_add_f32_e32 v139, 1.0, v139
	v_add_f32_e32 v143, 1.0, v143
	v_add_f32_e32 v140, 1.0, v140
	v_add_f32_e32 v144, 1.0, v144
	v_add_f32_e32 v141, 1.0, v141
	v_add_f32_e32 v145, 1.0, v145
	v_rcp_f32_e32 v138, v138
	v_rcp_f32_e32 v142, v142
	v_rcp_f32_e32 v139, v139
	v_rcp_f32_e32 v143, v143
	v_rcp_f32_e32 v140, v140
	v_rcp_f32_e32 v144, v144
	v_rcp_f32_e32 v141, v141
	v_rcp_f32_e32 v145, v145
.LBB0_251:
	s_andn2_b64 vcc, exec, s[26:27]
	s_cbranch_vccnz .LBB0_253
	s_waitcnt lgkmcnt(0)
	v_lshlrev_b32_e32 v138, 2, v218
	v_mov_b32_e32 v139, v97
	v_lshl_add_u64 v[146:147], s[90:91], 0, v[138:139]
	v_readlane_b32 s30, v250, 42
	s_waitcnt lgkmcnt(4)
	v_mov_b64_e32 v[144:145], v[132:133]
	v_mov_b64_e32 v[140:141], v[136:137]
	s_add_i32 s24, s11, 0xfffff980
	s_mov_b64 s[28:29], 0x200
	s_waitcnt lgkmcnt(0)
	v_mov_b64_e32 v[148:149], v[214:215]
	v_readlane_b32 s31, v250, 43
	v_mov_b64_e32 v[142:143], v[130:131]
	v_mov_b64_e32 v[138:139], v[134:135]
	s_branch .LBB0_254
.LBB0_253:
	v_readlane_b32 s30, v250, 38
	s_mov_b64 s[28:29], 0x800
	s_waitcnt lgkmcnt(0)
	v_mov_b64_e32 v[146:147], 0
	s_waitcnt lgkmcnt(0)
	v_mov_b64_e32 v[148:149], -1
	v_readlane_b32 s31, v250, 39

;     DI void operator()(f32x4 (&acc)[2][2][4][2], const Unit& u, int wr, int wc, int fr, int fq, LAS unsigned char* lds) const {
;     ...
;                     if (gcol < 512) { dst = QA; ld = 512; c0 = gcol; v0 = v0 * QSCALE; v1 = v1 * QSCALE; }
;                     else if (gcol < 640) { dst = KA; ld = 128; c0 = gcol - 512; of = out + (prm ? O_KWP : O_KWS); orow = offA; }
;                     else if (gcol < 768) { dst = VA; ld = 128; c0 = gcol - 640; of = out + (prm ? O_VWP : O_VWS); orow = offA; }
;                     else if (gcol < 1280) { dst = QB; ld = 512; c0 = gcol - 768; v0 = v0 * QSCALE; v1 = v1 * QSCALE; }
;                     else if (gcol < 1792) { dst = KB; ld = 512; c0 = gcol - 1280; of = out + (prm ? O_KBP : O_KBS); orow = offB; }
;                     else if (gcol < 2304) { dst = VB; ld = 512; c0 = gcol - 1792; of = out + (prm ? O_VBP : O_VBS); orow = offB; }
.LBB0_255:
	s_andn2_b64 vcc, exec, s[26:27]
	s_cbranch_vccnz .LBB0_257
	s_waitcnt lgkmcnt(0)
	v_lshlrev_b32_e32 v138, 2, v216
	v_mov_b32_e32 v139, v97
	v_readlane_b32 s0, v250, 46
	v_lshl_add_u64 v[146:147], s[90:91], 0, v[138:139]
	v_readlane_b32 s1, v250, 47
	s_waitcnt lgkmcnt(4)
	v_mov_b64_e32 v[144:145], v[132:133]
	v_mov_b64_e32 v[140:141], v[136:137]
	s_add_i32 s24, s11, 0xfffffb80
	s_waitcnt lgkmcnt(0)
	v_mov_b64_e32 v[150:151], s[0:1]
	v_mov_b64_e32 v[152:153], 0x200
	v_mov_b64_e32 v[148:149], v[214:215]
	v_mov_b64_e32 v[142:143], v[130:131]
	v_mov_b64_e32 v[138:139], v[134:135]

;     DI void operator()(f32x4 (&acc)[2][2][4][2], const Unit& u, int wr, int wc, int fr, int fq, LAS unsigned char* lds) const {
;     ...
;                     if (gcol < 512) { dst = QA; ld = 512; c0 = gcol; v0 = v0 * QSCALE; v1 = v1 * QSCALE; }
;                     else if (gcol < 640) { dst = KA; ld = 128; c0 = gcol - 512; of = out + (prm ? O_KWP : O_KWS); orow = offA; }
;                     else if (gcol < 768) { dst = VA; ld = 128; c0 = gcol - 640; of = out + (prm ? O_VWP : O_VWS); orow = offA; }
;                     else if (gcol < 1280) { dst = QB; ld = 512; c0 = gcol - 768; v0 = v0 * QSCALE; v1 = v1 * QSCALE; }
.LBB0_258:
	s_andn2_b64 vcc, exec, s[26:27]
	s_cbranch_vccnz .LBB0_260
	v_readlane_b32 s0, v250, 44
	v_readlane_b32 s1, v250, 45
	s_add_i32 s24, s11, 0xfffffd80
	s_waitcnt lgkmcnt(0)
	v_pk_mul_f32 v[140:141], v[136:137], s[66:67] op_sel_hi:[1,0]
	v_pk_mul_f32 v[138:139], v[134:135], s[66:67] op_sel_hi:[1,0]
	v_pk_mul_f32 v[144:145], v[132:133], s[66:67] op_sel_hi:[1,0]
	s_waitcnt lgkmcnt(4)
	v_pk_mul_f32 v[142:143], v[130:131], s[66:67] op_sel_hi:[1,0]
	v_mov_b64_e32 v[146:147], 0
	s_waitcnt lgkmcnt(0)
	v_mov_b64_e32 v[148:149], -1
	v_mov_b64_e32 v[150:151], s[0:1]
	v_mov_b64_e32 v[152:153], 0x200

;     DI void operator()(f32x4 (&acc)[2][2][4][2], const Unit& u, int wr, int wc, int fr, int fq, LAS unsigned char* lds) const {
;     ...
;                     if (gcol < 512) { dst = QA; ld = 512; c0 = gcol; v0 = v0 * QSCALE; v1 = v1 * QSCALE; }
;                     else if (gcol < 640) { dst = KA; ld = 128; c0 = gcol - 512; of = out + (prm ? O_KWP : O_KWS); orow = offA; }
;                     else if (gcol < 768) { dst = VA; ld = 128; c0 = gcol - 640; of = out + (prm ? O_VWP : O_VWS); orow = offA; }
.LBB0_261:
	s_andn2_b64 vcc, exec, s[26:27]
	s_cbranch_vccnz .LBB0_263
	s_waitcnt lgkmcnt(0)
	v_lshlrev_b32_e32 v138, 2, v212
	v_mov_b32_e32 v139, v97
	v_readlane_b32 s0, v250, 40
	v_lshl_add_u64 v[146:147], s[90:91], 0, v[138:139]
	v_readlane_b32 s1, v250, 41
	s_waitcnt lgkmcnt(4)
	v_mov_b64_e32 v[144:145], v[132:133]
	v_mov_b64_e32 v[140:141], v[136:137]
	s_add_i32 s24, s11, 0xfffffe00
	s_waitcnt lgkmcnt(0)
	v_mov_b64_e32 v[150:151], s[0:1]
	v_mov_b64_e32 v[152:153], 0x80
	v_mov_b64_e32 v[148:149], v[208:209]
	v_mov_b64_e32 v[142:143], v[130:131]
	v_mov_b64_e32 v[138:139], v[134:135]

;     DI void operator()(f32x4 (&acc)[2][2][4][2], const Unit& u, int wr, int wc, int fr, int fq, LAS unsigned char* lds) const {
;     ...
;                     if (gcol < 512) { dst = QA; ld = 512; c0 = gcol; v0 = v0 * QSCALE; v1 = v1 * QSCALE; }
;                     else if (gcol < 640) { dst = KA; ld = 128; c0 = gcol - 512; of = out + (prm ? O_KWP : O_KWS); orow = offA; }
.LBB0_264:
	s_andn2_b64 vcc, exec, s[26:27]
	s_cbranch_vccnz .LBB0_266
	s_waitcnt lgkmcnt(0)
	v_lshlrev_b32_e32 v138, 2, v210
	v_mov_b32_e32 v139, v97
	v_lshl_add_u64 v[146:147], s[90:91], 0, v[138:139]
	s_waitcnt lgkmcnt(4)
	v_mov_b64_e32 v[144:145], v[132:133]
	v_mov_b64_e32 v[140:141], v[136:137]
	s_add_i32 s24, s11, 0xfffffe80
	s_waitcnt lgkmcnt(0)
	v_mov_b64_e32 v[150:151], s[78:79]
	v_mov_b64_e32 v[152:153], 0x80
	v_mov_b64_e32 v[148:149], v[208:209]
	v_mov_b64_e32 v[142:143], v[130:131]
	v_mov_b64_e32 v[138:139], v[134:135]

; #define LAS __attribute__((address_space(3)))
; DI unsigned pk2(float lo, float hi) { f32x2 v = {lo, hi}; hbf2 r = __builtin_convertvector(v, hbf2); return __builtin_bit_cast(unsigned, r); }
; DI float sigmoidf_(float a) { return fast_rcp(1.0f + fast_exp2(-a * LOG2E)); }
;     DI void operator()(f32x4 (&acc)[2][2][4][2], const Unit& u, int wr, int wc, int fr, int fq, LAS unsigned char* lds) const {
;     ...
;                     if (gcol < 512) { dst = QA; ld = 512; c0 = gcol; v0 = v0 * QSCALE; v1 = v1 * QSCALE; }
;                     else if (gcol < 640) { dst = KA; ld = 128; c0 = gcol - 512; of = out + (prm ? O_KWP : O_KWS); orow = offA; }
;                     else if (gcol < 768) { dst = VA; ld = 128; c0 = gcol - 640; of = out + (prm ? O_VWP : O_VWS); orow = offA; }
;                     else if (gcol < 1280) { dst = QB; ld = 512; c0 = gcol - 768; v0 = v0 * QSCALE; v1 = v1 * QSCALE; }
;                     else if (gcol < 1792) { dst = KB; ld = 512; c0 = gcol - 1280; of = out + (prm ? O_KBP : O_KBS); orow = offB; }
;                     else if (gcol < 2304) { dst = VB; ld = 512; c0 = gcol - 1792; of = out + (prm ? O_VBP : O_VBS); orow = offB; }
;                     else { dst = GATES; ld = 2048; c0 = gcol - 2304;
;                         const f32x4 g0 = *(const LAS f32x4*)(lds + BG_OFF + (c0 + cw) * 4), g1 = *(const LAS f32x4*)(lds + BG_OFF + (c0 + cw + 4) * 4);
; #pragma unroll
;                         for (int j = 0; j < 4; ++j) { v0[j] = sigmoidf_(v0[j] + g0[j]); v1[j] = sigmoidf_(v1[j] + g1[j]); } }
;                     u32x4 w; w.x = pk2(v0[0], v0[1]); w.y = pk2(v0[2], v0[3]); w.z = pk2(v1[0], v1[1]); w.w = pk2(v1[2], v1[3]);
;                     *(u32x4*)(dst + (size_t)row * ld + c0 + cw) = w;
;                     if (of != nullptr && orow >= 0) { float* op = of + orow + c0 + cw; *(f32x4*)op = v0; *(f32x4*)(op + 4) = v1; }
.LBB0_267:
	s_andn2_b64 vcc, exec, s[26:27]
	s_cbranch_vccnz .LBB0_269
	s_waitcnt lgkmcnt(0)
	v_pk_mul_f32 v[140:141], v[136:137], s[66:67] op_sel_hi:[1,0]
	v_pk_mul_f32 v[138:139], v[134:135], s[66:67] op_sel_hi:[1,0]
	v_pk_mul_f32 v[144:145], v[132:133], s[66:67] op_sel_hi:[1,0]
	s_waitcnt lgkmcnt(4)
	v_pk_mul_f32 v[142:143], v[130:131], s[66:67] op_sel_hi:[1,0]
	s_waitcnt lgkmcnt(0)
	v_mov_b64_e32 v[148:149], -1
	v_mov_b64_e32 v[146:147], 0
	v_mov_b64_e32 v[150:151], s[74:75]
	v_mov_b64_e32 v[152:153], 0x200
	s_mov_b32 s24, s13
.LBB0_269:
	s_waitcnt lgkmcnt(5)
	v_mul_lo_u32 v136, v153, v192
	v_mul_lo_u32 v137, v152, v167
	v_mad_u64_u32 v[134:135], s[0:1], v152, v192, 0
	v_add3_u32 v135, v135, v137, v136
	s_waitcnt lgkmcnt(0)
	v_lshl_add_u64 v[134:135], v[134:135], 1, v[150:151]
	s_ashr_i32 s25, s24, 31
	v_lshl_add_u64 v[134:135], s[24:25], 1, v[134:135]
	v_cmp_ne_u64_e32 vcc, 0, v[146:147]
	v_cmp_lt_i64_e64 s[42:43], -1, v[148:149]
	v_cvt_pk_bf16_f32 v130, v138, v139
	v_cvt_pk_bf16_f32 v131, v140, v141
	s_waitcnt lgkmcnt(4)
	v_cvt_pk_bf16_f32 v132, v142, v143
	v_cvt_pk_bf16_f32 v133, v144, v145
	v_lshl_add_u64 v[134:135], v[134:135], 0, v[96:97]
	s_and_b64 s[0:1], vcc, s[42:43]
	global_store_dwordx4 v[134:135], v[130:133], off
	s_and_saveexec_b64 s[26:27], s[0:1]
	s_cbranch_execz .LBB0_271
	v_lshl_add_u64 v[130:131], v[148:149], 2, v[146:147]
	v_lshl_add_u64 v[130:131], s[24:25], 2, v[130:131]
	v_mov_b32_e32 v191, v97
	v_lshl_add_u64 v[130:131], v[130:131], 0, v[190:191]
	global_store_dwordx4 v[130:131], v[138:141], off
	global_store_dwordx4 v[130:131], v[142:145], off offset:16

;     DI void operator()(f32x4 (&acc)[2][2][4][2], const Unit& u, int wr, int wc, int fr, int fq, LAS unsigned char* lds) const {
;     ...
;                 const int row = row0 + ai * 128 + m * 16; const float rs = rsv[ai * 4 + m];
;                 int posidx; long offA, offB;
;                 const bool prm = row < TP;
;                 if (prm) { const int b = row >> 13, t = row & 8191; posidx = t;
;                     offA = t >= 8064 ? ((long)(layer * 4 + b) * 128 + (t - 8064)) * 128 : -1;
;                     offB = t >= 7680 ? ((long)(layer * 4 + b) * 512 + (t - 7680)) * 512 : -1;
;                 } else { const int sb = (row - TP) >> 6, t = (row - TP) & 63; posidx = 8192 + t;
;                     offA = ((long)(layer * 32 + sb) * 128 + 64 + t) * 128;
;                     offB = ((long)(layer * 32 + sb) * 512 + 448 + t) * 512; }
; #pragma unroll
;                 for (int bj = 0; bj < 2; ++bj) {
;                     const int gcol = u.pn * 256 + bj * 128;
;                     f32x4 v0 = acc[ai][bj][m][0] * rs, v1 = acc[ai][bj][m][1] * rs;
;                     if (gcol < 768 && gcol != 640) {
;                         if (rope_wave) {
;                             const float* rp = ROPE + (size_t)posidx * 16;
;                             const f32x4 cs0 = *(const f32x4*)rp, cs1 = *(const f32x4*)(rp + 4), sn0 = *(const f32x4*)(rp + 8), sn1 = *(const f32x4*)(rp + 12);
;                             f32x4 p0, p1;
; #pragma unroll
;                             for (int j = 0; j < 4; ++j) { p0[j] = __shfl_xor(v0[j], 16); p1[j] = __shfl_xor(v1[j], 16); }
;                             if (fq == 0) { v0 = v0 * cs0 - p0 * sn0; v1 = v1 * cs1 - p1 * sn1; }
;                             else if (fq == 1) { v0 = v0 * cs0 + p0 * sn0; v1 = v1 * cs1 + p1 * sn1; }
;                         }
.LBB0_279:
	s_or_b64 exec, exec, s[24:25]
	v_lshlrev_b32_e32 v130, 6, v130
	v_mov_b32_e32 v131, v97
	v_lshl_add_u64 v[222:223], s[82:83], 0, v[130:131]
	v_pk_mul_f32 v[136:137], v[120:121], v[206:207] op_sel_hi:[1,0]
	v_pk_mul_f32 v[134:135], v[118:119], v[206:207] op_sel_hi:[1,0]
	v_pk_mul_f32 v[132:133], v[116:117], v[206:207] op_sel_hi:[1,0]
	s_and_b64 vcc, exec, s[38:39]
	v_pk_mul_f32 v[130:131], v[114:115], v[206:207] op_sel_hi:[1,0]
	s_cbranch_vccnz .LBB0_287
	v_and_b32_e32 v139, 64, v229
	v_xor_b32_e32 v138, 16, v229
	v_add_u32_e32 v139, 64, v139
	v_cmp_lt_i32_e32 vcc, v138, v139
	s_nop 1
	v_cndmask_b32_e32 v138, v229, v138, vcc
	v_lshlrev_b32_e32 v138, 2, v138
	ds_bpermute_b32 v152, v138, v134
	ds_bpermute_b32 v142, v138, v130
	ds_bpermute_b32 v153, v138, v135
	ds_bpermute_b32 v143, v138, v131
	ds_bpermute_b32 v226, v138, v136
	ds_bpermute_b32 v224, v138, v132
	ds_bpermute_b32 v227, v138, v137
	ds_bpermute_b32 v225, v138, v133
	v_subrev_u32_e32 v148, s82, v222
	v_and_b32_e32 v148, 0x3fff, v148
	ds_read_b128 v[144:147], v148 offset:49200
	ds_read_b128 v[154:157], v148 offset:49184
	ds_read_b128 v[138:141], v148 offset:49168
	ds_read_b128 v[148:151], v148 offset:49152
	v_cmp_lt_i32_e32 vcc, 0, v169
	s_and_saveexec_b64 s[0:1], vcc
	s_xor_b64 s[24:25], exec, s[0:1]
	s_cbranch_execz .LBB0_284
	v_cmp_eq_u32_e32 vcc, 1, v169
	s_and_saveexec_b64 s[26:27], vcc
	s_cbranch_execz .LBB0_283
	s_waitcnt lgkmcnt(0)
	v_pk_mul_f32 v[156:157], v[156:157], v[226:227]
	v_pk_mul_f32 v[152:153], v[154:155], v[152:153]
	s_waitcnt lgkmcnt(0)
	v_pk_mul_f32 v[146:147], v[146:147], v[224:225]
	v_pk_mul_f32 v[142:143], v[144:145], v[142:143]
	s_waitcnt lgkmcnt(0)
	v_pk_fma_f32 v[136:137], v[136:137], v[150:151], v[156:157]
	v_pk_fma_f32 v[134:135], v[134:135], v[148:149], v[152:153]
	v_pk_fma_f32 v[132:133], v[132:133], v[140:141], v[146:147]
	v_pk_fma_f32 v[130:131], v[130:131], v[138:139], v[142:143]

;     DI void operator()(f32x4 (&acc)[2][2][4][2], const Unit& u, int wr, int wc, int fr, int fq, LAS unsigned char* lds) const {
;     ...
;                             if (fq == 0) { v0 = v0 * cs0 - p0 * sn0; v1 = v1 * cs1 - p1 * sn1; }
;                             else if (fq == 1) { v0 = v0 * cs0 + p0 * sn0; v1 = v1 * cs1 + p1 * sn1; }
.LBB0_284:
	s_andn2_saveexec_b64 s[24:25], s[24:25]
	s_cbranch_execz .LBB0_286
	s_waitcnt lgkmcnt(0)
	v_pk_mul_f32 v[156:157], v[156:157], v[226:227]
	v_pk_mul_f32 v[152:153], v[154:155], v[152:153]
	s_waitcnt lgkmcnt(0)
	v_pk_mul_f32 v[146:147], v[146:147], v[224:225]
	v_pk_mul_f32 v[142:143], v[144:145], v[142:143]
	s_waitcnt lgkmcnt(0)
	v_pk_fma_f32 v[136:137], v[136:137], v[150:151], v[156:157] neg_lo:[0,0,1] neg_hi:[0,0,1]
	v_pk_fma_f32 v[134:135], v[134:135], v[148:149], v[152:153] neg_lo:[0,0,1] neg_hi:[0,0,1]
	v_pk_fma_f32 v[132:133], v[132:133], v[140:141], v[146:147] neg_lo:[0,0,1] neg_hi:[0,0,1]
	v_pk_fma_f32 v[130:131], v[130:131], v[138:139], v[142:143] neg_lo:[0,0,1] neg_hi:[0,0,1]

; #define LAS __attribute__((address_space(3)))
; DI float sigmoidf_(float a) { return fast_rcp(1.0f + fast_exp2(-a * LOG2E)); }
;     DI void operator()(f32x4 (&acc)[2][2][4][2], const Unit& u, int wr, int wc, int fr, int fq, LAS unsigned char* lds) const {
;     ...
;                     if (gcol < 768 && gcol != 640) {
;                         if (rope_wave) {
;                             const float* rp = ROPE + (size_t)posidx * 16;
;                             const f32x4 cs0 = *(const f32x4*)rp, cs1 = *(const f32x4*)(rp + 4), sn0 = *(const f32x4*)(rp + 8), sn1 = *(const f32x4*)(rp + 12);
;                             f32x4 p0, p1;
; #pragma unroll
;                             for (int j = 0; j < 4; ++j) { p0[j] = __shfl_xor(v0[j], 16); p1[j] = __shfl_xor(v1[j], 16); }
;                             if (fq == 0) { v0 = v0 * cs0 - p0 * sn0; v1 = v1 * cs1 - p1 * sn1; }
;                             else if (fq == 1) { v0 = v0 * cs0 + p0 * sn0; v1 = v1 * cs1 + p1 * sn1; }
;                         }
;                     }
;                     bf16_t* dst; int ld, c0; float* of = nullptr; long orow = -1;
;                     if (gcol < 512) { dst = QA; ld = 512; c0 = gcol; v0 = v0 * QSCALE; v1 = v1 * QSCALE; }
;                     else if (gcol < 640) { dst = KA; ld = 128; c0 = gcol - 512; of = out + (prm ? O_KWP : O_KWS); orow = offA; }
;                     else if (gcol < 768) { dst = VA; ld = 128; c0 = gcol - 640; of = out + (prm ? O_VWP : O_VWS); orow = offA; }
;                     else if (gcol < 1280) { dst = QB; ld = 512; c0 = gcol - 768; v0 = v0 * QSCALE; v1 = v1 * QSCALE; }
;                     else if (gcol < 1792) { dst = KB; ld = 512; c0 = gcol - 1280; of = out + (prm ? O_KBP : O_KBS); orow = offB; }
;                     else if (gcol < 2304) { dst = VB; ld = 512; c0 = gcol - 1792; of = out + (prm ? O_VBP : O_VBS); orow = offB; }
;                     else { dst = GATES; ld = 2048; c0 = gcol - 2304;
;                         const f32x4 g0 = *(const LAS f32x4*)(lds + BG_OFF + (c0 + cw) * 4), g1 = *(const LAS f32x4*)(lds + BG_OFF + (c0 + cw + 4) * 4);
; #pragma unroll
;                         for (int j = 0; j < 4; ++j) { v0[j] = sigmoidf_(v0[j] + g0[j]); v1[j] = sigmoidf_(v1[j] + g1[j]); } }
.LBB0_287:
	s_waitcnt lgkmcnt(0)
	v_cndmask_b32_e64 v138, 0, 1, s[44:45]
	v_mov_b32_e32 v207, v206
	v_cmp_ne_u32_e64 s[42:43], 1, v138
	s_andn2_b64 vcc, exec, s[44:45]
	s_mov_b64 s[26:27], -1
	s_cbranch_vccnz .LBB0_306
	s_cmpk_lt_u32 s11, 0x280
	s_cbranch_scc1 .LBB0_303
	s_cmpk_lt_u32 s11, 0x500
	s_cbranch_scc1 .LBB0_300
	s_cmpk_lt_u32 s11, 0x700
	s_cbranch_scc1 .LBB0_297
	s_cmpk_lt_u32 s11, 0x900
	s_cbranch_scc1 .LBB0_293
	s_add_i32 s24, s11, 0xfffff700
	v_or_b32_e32 v138, s24, v166
	v_lshl_add_u32 v138, v138, 2, 0
	s_waitcnt lgkmcnt(6)
	v_add_u32_e32 v142, 0x23040, v138
	ds_read_b128 v[138:141], v142
	s_waitcnt lgkmcnt(5)
	ds_read_b128 v[142:145], v142 offset:16
	s_mov_b64 s[26:27], 0
	s_waitcnt lgkmcnt(1)
	v_add_f32_e32 v138, v134, v138
	s_waitcnt lgkmcnt(0)
	v_add_f32_e32 v142, v130, v142
	v_add_f32_e32 v139, v135, v139
	v_add_f32_e32 v143, v131, v143
	v_add_f32_e32 v140, v136, v140
	v_add_f32_e32 v144, v132, v144
	v_add_f32_e32 v141, v137, v141
	v_add_f32_e32 v145, v133, v145
	v_mul_f32_e32 v138, 0xbfb8aa3b, v138
	v_mul_f32_e32 v142, 0xbfb8aa3b, v142
	v_mul_f32_e32 v139, 0xbfb8aa3b, v139
	v_mul_f32_e32 v143, 0xbfb8aa3b, v143
	v_mul_f32_e32 v140, 0xbfb8aa3b, v140
	v_mul_f32_e32 v144, 0xbfb8aa3b, v144
	v_mul_f32_e32 v141, 0xbfb8aa3b, v141
	v_mul_f32_e32 v145, 0xbfb8aa3b, v145
	v_exp_f32_e32 v138, v138
	v_exp_f32_e32 v142, v142
	v_exp_f32_e32 v139, v139
	v_exp_f32_e32 v143, v143
	v_exp_f32_e32 v140, v140
	v_exp_f32_e32 v144, v144
	v_exp_f32_e32 v141, v141
	v_exp_f32_e32 v145, v145
	v_add_f32_e32 v138, 1.0, v138
	v_add_f32_e32 v142, 1.0, v142
	v_add_f32_e32 v139, 1.0, v139
	v_add_f32_e32 v143, 1.0, v143
	v_add_f32_e32 v140, 1.0, v140
	v_add_f32_e32 v144, 1.0, v144
	v_add_f32_e32 v141, 1.0, v141
	v_add_f32_e32 v145, 1.0, v145
	v_rcp_f32_e32 v138, v138
	v_rcp_f32_e32 v142, v142
	v_rcp_f32_e32 v139, v139
	v_rcp_f32_e32 v143, v143
	v_rcp_f32_e32 v140, v140
	v_rcp_f32_e32 v144, v144
	v_rcp_f32_e32 v141, v141
	v_rcp_f32_e32 v145, v145
.LBB0_293:
	s_andn2_b64 vcc, exec, s[26:27]
	s_cbranch_vccnz .LBB0_295
	v_lshlrev_b32_e32 v138, 2, v220
	v_mov_b32_e32 v139, v97
	v_lshl_add_u64 v[146:147], s[90:91], 0, v[138:139]
	v_readlane_b32 s30, v250, 42
	s_waitcnt lgkmcnt(4)
	v_mov_b64_e32 v[144:145], v[132:133]
	v_mov_b64_e32 v[140:141], v[136:137]
	s_add_i32 s24, s11, 0xfffff900
	s_mov_b64 s[28:29], 0x200
	s_waitcnt lgkmcnt(0)
	v_mov_b64_e32 v[148:149], v[216:217]
	v_readlane_b32 s31, v250, 43
	v_mov_b64_e32 v[142:143], v[130:131]
	v_mov_b64_e32 v[138:139], v[134:135]
	s_branch .LBB0_296
.LBB0_295:
	v_readlane_b32 s30, v250, 38
	s_mov_b64 s[28:29], 0x800
	v_mov_b64_e32 v[146:147], 0
	s_waitcnt lgkmcnt(0)
	v_mov_b64_e32 v[148:149], -1
	v_readlane_b32 s31, v250, 39

;     DI void operator()(f32x4 (&acc)[2][2][4][2], const Unit& u, int wr, int wc, int fr, int fq, LAS unsigned char* lds) const {
;     ...
;                     if (gcol < 512) { dst = QA; ld = 512; c0 = gcol; v0 = v0 * QSCALE; v1 = v1 * QSCALE; }
;                     else if (gcol < 640) { dst = KA; ld = 128; c0 = gcol - 512; of = out + (prm ? O_KWP : O_KWS); orow = offA; }
;                     else if (gcol < 768) { dst = VA; ld = 128; c0 = gcol - 640; of = out + (prm ? O_VWP : O_VWS); orow = offA; }
;                     else if (gcol < 1280) { dst = QB; ld = 512; c0 = gcol - 768; v0 = v0 * QSCALE; v1 = v1 * QSCALE; }
;                     else if (gcol < 1792) { dst = KB; ld = 512; c0 = gcol - 1280; of = out + (prm ? O_KBP : O_KBS); orow = offB; }
;                     else if (gcol < 2304) { dst = VB; ld = 512; c0 = gcol - 1792; of = out + (prm ? O_VBP : O_VBS); orow = offB; }
.LBB0_297:
	s_andn2_b64 vcc, exec, s[26:27]
	s_cbranch_vccnz .LBB0_299
	v_lshlrev_b32_e32 v138, 2, v218
	v_mov_b32_e32 v139, v97
	v_readlane_b32 s0, v250, 46
	v_lshl_add_u64 v[146:147], s[90:91], 0, v[138:139]
	v_readlane_b32 s1, v250, 47
	s_waitcnt lgkmcnt(4)
	v_mov_b64_e32 v[144:145], v[132:133]
	v_mov_b64_e32 v[140:141], v[136:137]
	s_add_i32 s24, s11, 0xfffffb00
	s_waitcnt lgkmcnt(0)
	v_mov_b64_e32 v[150:151], s[0:1]
	v_mov_b64_e32 v[152:153], 0x200
	v_mov_b64_e32 v[148:149], v[216:217]
	v_mov_b64_e32 v[142:143], v[130:131]
	v_mov_b64_e32 v[138:139], v[134:135]

;     DI void operator()(f32x4 (&acc)[2][2][4][2], const Unit& u, int wr, int wc, int fr, int fq, LAS unsigned char* lds) const {
;     ...
;                     if (gcol < 512) { dst = QA; ld = 512; c0 = gcol; v0 = v0 * QSCALE; v1 = v1 * QSCALE; }
;                     else if (gcol < 640) { dst = KA; ld = 128; c0 = gcol - 512; of = out + (prm ? O_KWP : O_KWS); orow = offA; }
;                     else if (gcol < 768) { dst = VA; ld = 128; c0 = gcol - 640; of = out + (prm ? O_VWP : O_VWS); orow = offA; }
;                     else if (gcol < 1280) { dst = QB; ld = 512; c0 = gcol - 768; v0 = v0 * QSCALE; v1 = v1 * QSCALE; }
.LBB0_300:
	s_andn2_b64 vcc, exec, s[26:27]
	s_cbranch_vccnz .LBB0_302
	v_readlane_b32 s0, v250, 44
	v_readlane_b32 s1, v250, 45
	s_add_i32 s24, s11, 0xfffffd00
	v_pk_mul_f32 v[140:141], v[136:137], s[66:67] op_sel_hi:[1,0]
	v_pk_mul_f32 v[138:139], v[134:135], s[66:67] op_sel_hi:[1,0]
	v_pk_mul_f32 v[144:145], v[132:133], s[66:67] op_sel_hi:[1,0]
	s_waitcnt lgkmcnt(4)
	v_pk_mul_f32 v[142:143], v[130:131], s[66:67] op_sel_hi:[1,0]
	v_mov_b64_e32 v[146:147], 0
	s_waitcnt lgkmcnt(0)
	v_mov_b64_e32 v[148:149], -1
	v_mov_b64_e32 v[150:151], s[0:1]
	v_mov_b64_e32 v[152:153], 0x200

;     DI void operator()(f32x4 (&acc)[2][2][4][2], const Unit& u, int wr, int wc, int fr, int fq, LAS unsigned char* lds) const {
;     ...
;                     if (gcol < 512) { dst = QA; ld = 512; c0 = gcol; v0 = v0 * QSCALE; v1 = v1 * QSCALE; }
;                     else if (gcol < 640) { dst = KA; ld = 128; c0 = gcol - 512; of = out + (prm ? O_KWP : O_KWS); orow = offA; }
;                     else if (gcol < 768) { dst = VA; ld = 128; c0 = gcol - 640; of = out + (prm ? O_VWP : O_VWS); orow = offA; }
.LBB0_303:
	s_andn2_b64 vcc, exec, s[26:27]
	s_cbranch_vccnz .LBB0_305
	v_lshlrev_b32_e32 v138, 2, v212
	v_mov_b32_e32 v139, v97
	v_lshl_add_u64 v[146:147], s[90:91], 0, v[138:139]
	s_waitcnt lgkmcnt(4)
	v_mov_b64_e32 v[144:145], v[132:133]
	v_mov_b64_e32 v[140:141], v[136:137]
	s_add_i32 s24, s11, 0xfffffe00
	s_waitcnt lgkmcnt(0)
	v_mov_b64_e32 v[150:151], s[78:79]
	v_mov_b64_e32 v[152:153], 0x80
	v_mov_b64_e32 v[148:149], v[210:211]
	v_mov_b64_e32 v[142:143], v[130:131]
	v_mov_b64_e32 v[138:139], v[134:135]

; #define LAS __attribute__((address_space(3)))
;     DI void operator()(f32x4 (&acc)[2][2][4][2], const Unit& u, int wr, int wc, int fr, int fq, LAS unsigned char* lds) const {
;     ...
;                 for (int bj = 0; bj < 2; ++bj) {
;                     const int gcol = u.pn * 256 + bj * 128;
;                     f32x4 v0 = acc[ai][bj][m][0] * rs, v1 = acc[ai][bj][m][1] * rs;
;                     if (gcol < 768 && gcol != 640) {
;                         if (rope_wave) {
;                             const float* rp = ROPE + (size_t)posidx * 16;
;                             const f32x4 cs0 = *(const f32x4*)rp, cs1 = *(const f32x4*)(rp + 4), sn0 = *(const f32x4*)(rp + 8), sn1 = *(const f32x4*)(rp + 12);
;                             f32x4 p0, p1;
; #pragma unroll
;                             for (int j = 0; j < 4; ++j) { p0[j] = __shfl_xor(v0[j], 16); p1[j] = __shfl_xor(v1[j], 16); }
;                             if (fq == 0) { v0 = v0 * cs0 - p0 * sn0; v1 = v1 * cs1 - p1 * sn1; }
;                             else if (fq == 1) { v0 = v0 * cs0 + p0 * sn0; v1 = v1 * cs1 + p1 * sn1; }
;                         }
;                     }
;                     bf16_t* dst; int ld, c0; float* of = nullptr; long orow = -1;
;                     if (gcol < 512) { dst = QA; ld = 512; c0 = gcol; v0 = v0 * QSCALE; v1 = v1 * QSCALE; }
;                     else if (gcol < 640) { dst = KA; ld = 128; c0 = gcol - 512; of = out + (prm ? O_KWP : O_KWS); orow = offA; }
;                     else if (gcol < 768) { dst = VA; ld = 128; c0 = gcol - 640; of = out + (prm ? O_VWP : O_VWS); orow = offA; }
;                     else if (gcol < 1280) { dst = QB; ld = 512; c0 = gcol - 768; v0 = v0 * QSCALE; v1 = v1 * QSCALE; }
;                     else if (gcol < 1792) { dst = KB; ld = 512; c0 = gcol - 1280; of = out + (prm ? O_KBP : O_KBS); orow = offB; }
;                     else if (gcol < 2304) { dst = VB; ld = 512; c0 = gcol - 1792; of = out + (prm ? O_VBP : O_VBS); orow = offB; }
;                     else { dst = GATES; ld = 2048; c0 = gcol - 2304;
;                         const f32x4 g0 = *(const LAS f32x4*)(lds + BG_OFF + (c0 + cw) * 4), g1 = *(const LAS f32x4*)(lds + BG_OFF + (c0 + cw + 4) * 4);
; #pragma unroll
;                         for (int j = 0; j < 4; ++j) { v0[j] = sigmoidf_(v0[j] + g0[j]); v1[j] = sigmoidf_(v1[j] + g1[j]); } }
.LBB0_306:
	s_andn2_b64 vcc, exec, s[26:27]
	s_cbranch_vccnz .LBB0_308
	v_pk_mul_f32 v[140:141], v[136:137], s[66:67] op_sel_hi:[1,0]
	v_pk_mul_f32 v[138:139], v[134:135], s[66:67] op_sel_hi:[1,0]
	v_pk_mul_f32 v[144:145], v[132:133], s[66:67] op_sel_hi:[1,0]
	s_waitcnt lgkmcnt(4)
	v_pk_mul_f32 v[142:143], v[130:131], s[66:67] op_sel_hi:[1,0]
	s_waitcnt lgkmcnt(0)
	v_mov_b64_e32 v[148:149], -1
	v_mov_b64_e32 v[146:147], 0
	v_mov_b64_e32 v[150:151], s[74:75]
	v_mov_b64_e32 v[152:153], 0x200
	s_mov_b32 s24, s11
.LBB0_308:
	v_ashrrev_i32_e32 v167, 31, v208
	s_waitcnt lgkmcnt(5)
	v_mul_lo_u32 v136, v153, v208
	v_mul_lo_u32 v137, v152, v167
	v_mad_u64_u32 v[134:135], s[0:1], v152, v208, 0
	v_add3_u32 v135, v135, v137, v136
	s_waitcnt lgkmcnt(0)
	v_lshl_add_u64 v[134:135], v[134:135], 1, v[150:151]
	s_ashr_i32 s25, s24, 31
	v_lshl_add_u64 v[134:135], s[24:25], 1, v[134:135]
	v_cmp_ne_u64_e32 vcc, 0, v[146:147]
	v_cmp_lt_i64_e64 s[44:45], -1, v[148:149]
	v_cvt_pk_bf16_f32 v130, v138, v139
	v_cvt_pk_bf16_f32 v131, v140, v141
	s_waitcnt lgkmcnt(4)
	v_cvt_pk_bf16_f32 v132, v142, v143
	v_cvt_pk_bf16_f32 v133, v144, v145
	v_lshl_add_u64 v[134:135], v[134:135], 0, v[96:97]
	s_and_b64 s[0:1], vcc, s[44:45]
	global_store_dwordx4 v[134:135], v[130:133], off
	s_and_saveexec_b64 s[26:27], s[0:1]
	s_cbranch_execz .LBB0_310
	v_lshl_add_u64 v[130:131], v[148:149], 2, v[146:147]
	v_lshl_add_u64 v[130:131], s[24:25], 2, v[130:131]
	v_mov_b32_e32 v191, v97
	v_lshl_add_u64 v[130:131], v[130:131], 0, v[190:191]
	global_store_dwordx4 v[130:131], v[138:141], off
	global_store_dwordx4 v[130:131], v[142:145], off offset:16
.LBB0_310:
	s_or_b64 exec, exec, s[26:27]
	v_mov_b32_e32 v130, v206
	v_mov_b32_e32 v131, v206
	v_pk_mul_f32 v[136:137], v[86:87], v[130:131]
	v_pk_mul_f32 v[134:135], v[84:85], v[206:207]
	v_pk_mul_f32 v[132:133], v[82:83], v[130:131]
	s_and_b64 vcc, exec, s[40:41]
	v_pk_mul_f32 v[130:131], v[80:81], v[206:207]
	s_cbranch_vccnz .LBB0_318
	v_and_b32_e32 v139, 64, v229
	v_xor_b32_e32 v138, 16, v229
	v_add_u32_e32 v139, 64, v139
	v_cmp_lt_i32_e32 vcc, v138, v139
	s_nop 1
	v_cndmask_b32_e32 v138, v229, v138, vcc
	v_lshlrev_b32_e32 v138, 2, v138
	ds_bpermute_b32 v152, v138, v134
	ds_bpermute_b32 v142, v138, v130
	ds_bpermute_b32 v153, v138, v135
	ds_bpermute_b32 v143, v138, v131
	s_waitcnt lgkmcnt(6)
	ds_bpermute_b32 v224, v138, v136
	ds_bpermute_b32 v206, v138, v132
	s_waitcnt lgkmcnt(6)
	ds_bpermute_b32 v225, v138, v137
	ds_bpermute_b32 v207, v138, v133
	v_subrev_u32_e32 v148, s82, v222
	v_and_b32_e32 v148, 0x3fff, v148
	ds_read_b128 v[144:147], v148 offset:49200
	ds_read_b128 v[154:157], v148 offset:49184
	ds_read_b128 v[138:141], v148 offset:49168
	ds_read_b128 v[148:151], v148 offset:49152
	v_cmp_lt_i32_e32 vcc, 0, v169
	s_and_saveexec_b64 s[0:1], vcc
	s_xor_b64 s[24:25], exec, s[0:1]
	s_cbranch_execz .LBB0_315
	v_cmp_eq_u32_e32 vcc, 1, v169
	s_and_saveexec_b64 s[26:27], vcc
	s_cbranch_execz .LBB0_314
	s_waitcnt lgkmcnt(0)
	v_pk_mul_f32 v[156:157], v[156:157], v[224:225]
	v_pk_mul_f32 v[152:153], v[154:155], v[152:153]
	s_waitcnt lgkmcnt(0)
	v_pk_mul_f32 v[146:147], v[146:147], v[206:207]
	v_pk_mul_f32 v[142:143], v[144:145], v[142:143]
	s_waitcnt lgkmcnt(0)
	v_pk_fma_f32 v[136:137], v[136:137], v[150:151], v[156:157]
	v_pk_fma_f32 v[134:135], v[134:135], v[148:149], v[152:153]
	v_pk_fma_f32 v[132:133], v[132:133], v[140:141], v[146:147]
	v_pk_fma_f32 v[130:131], v[130:131], v[138:139], v[142:143]

;     DI void operator()(f32x4 (&acc)[2][2][4][2], const Unit& u, int wr, int wc, int fr, int fq, LAS unsigned char* lds) const {
;     ...
;                             if (fq == 0) { v0 = v0 * cs0 - p0 * sn0; v1 = v1 * cs1 - p1 * sn1; }
;                             else if (fq == 1) { v0 = v0 * cs0 + p0 * sn0; v1 = v1 * cs1 + p1 * sn1; }
.LBB0_315:
	s_andn2_saveexec_b64 s[24:25], s[24:25]
	s_cbranch_execz .LBB0_317
	s_waitcnt lgkmcnt(0)
	v_pk_mul_f32 v[156:157], v[156:157], v[224:225]
	v_pk_mul_f32 v[152:153], v[154:155], v[152:153]
	s_waitcnt lgkmcnt(0)
	v_pk_mul_f32 v[146:147], v[146:147], v[206:207]
	v_pk_mul_f32 v[142:143], v[144:145], v[142:143]
	s_waitcnt lgkmcnt(0)
	v_pk_fma_f32 v[136:137], v[136:137], v[150:151], v[156:157] neg_lo:[0,0,1] neg_hi:[0,0,1]
	v_pk_fma_f32 v[134:135], v[134:135], v[148:149], v[152:153] neg_lo:[0,0,1] neg_hi:[0,0,1]
	v_pk_fma_f32 v[132:133], v[132:133], v[140:141], v[146:147] neg_lo:[0,0,1] neg_hi:[0,0,1]
	v_pk_fma_f32 v[130:131], v[130:131], v[138:139], v[142:143] neg_lo:[0,0,1] neg_hi:[0,0,1]

; #define LAS __attribute__((address_space(3)))
; DI float sigmoidf_(float a) { return fast_rcp(1.0f + fast_exp2(-a * LOG2E)); }
;     DI void operator()(f32x4 (&acc)[2][2][4][2], const Unit& u, int wr, int wc, int fr, int fq, LAS unsigned char* lds) const {
;     ...
;                     bf16_t* dst; int ld, c0; float* of = nullptr; long orow = -1;
;                     if (gcol < 512) { dst = QA; ld = 512; c0 = gcol; v0 = v0 * QSCALE; v1 = v1 * QSCALE; }
;                     else if (gcol < 640) { dst = KA; ld = 128; c0 = gcol - 512; of = out + (prm ? O_KWP : O_KWS); orow = offA; }
;                     else if (gcol < 768) { dst = VA; ld = 128; c0 = gcol - 640; of = out + (prm ? O_VWP : O_VWS); orow = offA; }
;                     else if (gcol < 1280) { dst = QB; ld = 512; c0 = gcol - 768; v0 = v0 * QSCALE; v1 = v1 * QSCALE; }
;                     else if (gcol < 1792) { dst = KB; ld = 512; c0 = gcol - 1280; of = out + (prm ? O_KBP : O_KBS); orow = offB; }
;                     else if (gcol < 2304) { dst = VB; ld = 512; c0 = gcol - 1792; of = out + (prm ? O_VBP : O_VBS); orow = offB; }
;                     else { dst = GATES; ld = 2048; c0 = gcol - 2304;
;                         const f32x4 g0 = *(const LAS f32x4*)(lds + BG_OFF + (c0 + cw) * 4), g1 = *(const LAS f32x4*)(lds + BG_OFF + (c0 + cw + 4) * 4);
; #pragma unroll
;                         for (int j = 0; j < 4; ++j) { v0[j] = sigmoidf_(v0[j] + g0[j]); v1[j] = sigmoidf_(v1[j] + g1[j]); } }
.LBB0_318:
	s_waitcnt lgkmcnt(0)
	v_cndmask_b32_e64 v138, 0, 1, s[46:47]
	v_cmp_ne_u32_e64 s[44:45], 1, v138
	s_andn2_b64 vcc, exec, s[46:47]
	s_mov_b64 s[26:27], -1
	s_cbranch_vccnz .LBB0_341
	s_cmpk_lt_u32 s13, 0x280
	s_cbranch_scc1 .LBB0_338
	s_andn2_b64 vcc, exec, s[22:23]
	s_cbranch_vccnz .LBB0_335
	s_cmpk_lt_u32 s11, 0x500
	s_cbranch_scc1 .LBB0_332
	s_cmpk_lt_u32 s11, 0x700
	s_cbranch_scc1 .LBB0_329
	s_cmpk_lt_u32 s11, 0x900
	s_cbranch_scc1 .LBB0_325
	s_add_i32 s24, s11, 0xfffff780
	v_or_b32_e32 v138, s24, v166
	v_lshl_add_u32 v138, v138, 2, 0
	s_waitcnt lgkmcnt(6)
	v_add_u32_e32 v142, 0x23040, v138
	ds_read_b128 v[138:141], v142
	s_waitcnt lgkmcnt(5)
	ds_read_b128 v[142:145], v142 offset:16
	s_mov_b64 s[26:27], 0
	s_waitcnt lgkmcnt(1)
	v_add_f32_e32 v138, v134, v138
	s_waitcnt lgkmcnt(0)
	v_add_f32_e32 v142, v130, v142
	v_add_f32_e32 v139, v135, v139
	v_add_f32_e32 v143, v131, v143
	v_add_f32_e32 v140, v136, v140
	v_add_f32_e32 v144, v132, v144
	v_add_f32_e32 v141, v137, v141
	v_add_f32_e32 v145, v133, v145
	v_mul_f32_e32 v138, 0xbfb8aa3b, v138
	v_mul_f32_e32 v142, 0xbfb8aa3b, v142
	v_mul_f32_e32 v139, 0xbfb8aa3b, v139
	v_mul_f32_e32 v143, 0xbfb8aa3b, v143
	v_mul_f32_e32 v140, 0xbfb8aa3b, v140
	v_mul_f32_e32 v144, 0xbfb8aa3b, v144
	v_mul_f32_e32 v141, 0xbfb8aa3b, v141
	v_mul_f32_e32 v145, 0xbfb8aa3b, v145
	v_exp_f32_e32 v138, v138
	v_exp_f32_e32 v142, v142
	v_exp_f32_e32 v139, v139
	v_exp_f32_e32 v143, v143
	v_exp_f32_e32 v140, v140
	v_exp_f32_e32 v144, v144
	v_exp_f32_e32 v141, v141
	v_exp_f32_e32 v145, v145
	v_add_f32_e32 v138, 1.0, v138
	v_add_f32_e32 v142, 1.0, v142
	v_add_f32_e32 v139, 1.0, v139
	v_add_f32_e32 v143, 1.0, v143
	v_add_f32_e32 v140, 1.0, v140
	v_add_f32_e32 v144, 1.0, v144
	v_add_f32_e32 v141, 1.0, v141
	v_add_f32_e32 v145, 1.0, v145
	v_rcp_f32_e32 v138, v138
	v_rcp_f32_e32 v142, v142
	v_rcp_f32_e32 v139, v139
	v_rcp_f32_e32 v143, v143
	v_rcp_f32_e32 v140, v140
	v_rcp_f32_e32 v144, v144
	v_rcp_f32_e32 v141, v141
	v_rcp_f32_e32 v145, v145
.LBB0_325:
	s_andn2_b64 vcc, exec, s[26:27]
	s_cbranch_vccnz .LBB0_327
	v_lshlrev_b32_e32 v138, 2, v220
	v_mov_b32_e32 v139, v97
	v_lshl_add_u64 v[146:147], s[90:91], 0, v[138:139]
	v_readlane_b32 s30, v250, 42
	s_waitcnt lgkmcnt(4)
	v_mov_b64_e32 v[144:145], v[132:133]
	v_mov_b64_e32 v[140:141], v[136:137]
	s_add_i32 s24, s11, 0xfffff980
	s_mov_b64 s[28:29], 0x200
	s_waitcnt lgkmcnt(0)
	v_mov_b64_e32 v[148:149], v[216:217]
	v_readlane_b32 s31, v250, 43
	v_mov_b64_e32 v[142:143], v[130:131]
	v_mov_b64_e32 v[138:139], v[134:135]
	s_branch .LBB0_328

;     DI void operator()(f32x4 (&acc)[2][2][4][2], const Unit& u, int wr, int wc, int fr, int fq, LAS unsigned char* lds) const {
;     ...
;                     if (gcol < 512) { dst = QA; ld = 512; c0 = gcol; v0 = v0 * QSCALE; v1 = v1 * QSCALE; }
;                     else if (gcol < 640) { dst = KA; ld = 128; c0 = gcol - 512; of = out + (prm ? O_KWP : O_KWS); orow = offA; }
;                     else if (gcol < 768) { dst = VA; ld = 128; c0 = gcol - 640; of = out + (prm ? O_VWP : O_VWS); orow = offA; }
;                     else if (gcol < 1280) { dst = QB; ld = 512; c0 = gcol - 768; v0 = v0 * QSCALE; v1 = v1 * QSCALE; }
;                     else if (gcol < 1792) { dst = KB; ld = 512; c0 = gcol - 1280; of = out + (prm ? O_KBP : O_KBS); orow = offB; }
;                     else if (gcol < 2304) { dst = VB; ld = 512; c0 = gcol - 1792; of = out + (prm ? O_VBP : O_VBS); orow = offB; }
.LBB0_329:
	s_andn2_b64 vcc, exec, s[26:27]
	s_cbranch_vccnz .LBB0_331
	v_lshlrev_b32_e32 v138, 2, v218
	v_mov_b32_e32 v139, v97
	v_readlane_b32 s0, v250, 46
	v_lshl_add_u64 v[146:147], s[90:91], 0, v[138:139]
	v_readlane_b32 s1, v250, 47
	s_waitcnt lgkmcnt(4)
	v_mov_b64_e32 v[144:145], v[132:133]
	v_mov_b64_e32 v[140:141], v[136:137]
	s_add_i32 s24, s11, 0xfffffb80
	s_waitcnt lgkmcnt(0)
	v_mov_b64_e32 v[150:151], s[0:1]
	v_mov_b64_e32 v[152:153], 0x200
	v_mov_b64_e32 v[148:149], v[216:217]
	v_mov_b64_e32 v[142:143], v[130:131]
	v_mov_b64_e32 v[138:139], v[134:135]

;     DI void operator()(f32x4 (&acc)[2][2][4][2], const Unit& u, int wr, int wc, int fr, int fq, LAS unsigned char* lds) const {
;     ...
;                     if (gcol < 512) { dst = QA; ld = 512; c0 = gcol; v0 = v0 * QSCALE; v1 = v1 * QSCALE; }
;                     else if (gcol < 640) { dst = KA; ld = 128; c0 = gcol - 512; of = out + (prm ? O_KWP : O_KWS); orow = offA; }
;                     else if (gcol < 768) { dst = VA; ld = 128; c0 = gcol - 640; of = out + (prm ? O_VWP : O_VWS); orow = offA; }
;                     else if (gcol < 1280) { dst = QB; ld = 512; c0 = gcol - 768; v0 = v0 * QSCALE; v1 = v1 * QSCALE; }
.LBB0_332:
	s_andn2_b64 vcc, exec, s[26:27]
	s_cbranch_vccnz .LBB0_334
	v_readlane_b32 s0, v250, 44
	v_readlane_b32 s1, v250, 45
	s_add_i32 s24, s11, 0xfffffd80
	v_pk_mul_f32 v[140:141], v[136:137], s[66:67] op_sel_hi:[1,0]
	v_pk_mul_f32 v[138:139], v[134:135], s[66:67] op_sel_hi:[1,0]
	v_pk_mul_f32 v[144:145], v[132:133], s[66:67] op_sel_hi:[1,0]
	s_waitcnt lgkmcnt(4)
	v_pk_mul_f32 v[142:143], v[130:131], s[66:67] op_sel_hi:[1,0]
	v_mov_b64_e32 v[146:147], 0
	s_waitcnt lgkmcnt(0)
	v_mov_b64_e32 v[148:149], -1
	v_mov_b64_e32 v[150:151], s[0:1]
	v_mov_b64_e32 v[152:153], 0x200

;     DI void operator()(f32x4 (&acc)[2][2][4][2], const Unit& u, int wr, int wc, int fr, int fq, LAS unsigned char* lds) const {
;     ...
;                     if (gcol < 512) { dst = QA; ld = 512; c0 = gcol; v0 = v0 * QSCALE; v1 = v1 * QSCALE; }
;                     else if (gcol < 640) { dst = KA; ld = 128; c0 = gcol - 512; of = out + (prm ? O_KWP : O_KWS); orow = offA; }
;                     else if (gcol < 768) { dst = VA; ld = 128; c0 = gcol - 640; of = out + (prm ? O_VWP : O_VWS); orow = offA; }
.LBB0_335:
	s_andn2_b64 vcc, exec, s[26:27]
	s_cbranch_vccnz .LBB0_337
	v_lshlrev_b32_e32 v138, 2, v214
	v_mov_b32_e32 v139, v97
	v_readlane_b32 s0, v250, 40
	v_lshl_add_u64 v[146:147], s[90:91], 0, v[138:139]
	v_readlane_b32 s1, v250, 41
	s_waitcnt lgkmcnt(4)
	v_mov_b64_e32 v[144:145], v[132:133]
	v_mov_b64_e32 v[140:141], v[136:137]
	s_add_i32 s24, s11, 0xfffffe00
	s_waitcnt lgkmcnt(0)
	v_mov_b64_e32 v[150:151], s[0:1]
	v_mov_b64_e32 v[152:153], 0x80
	v_mov_b64_e32 v[148:149], v[210:211]
	v_mov_b64_e32 v[142:143], v[130:131]
	v_mov_b64_e32 v[138:139], v[134:135]

;     DI void operator()(f32x4 (&acc)[2][2][4][2], const Unit& u, int wr, int wc, int fr, int fq, LAS unsigned char* lds) const {
;     ...
;                     if (gcol < 512) { dst = QA; ld = 512; c0 = gcol; v0 = v0 * QSCALE; v1 = v1 * QSCALE; }
;                     else if (gcol < 640) { dst = KA; ld = 128; c0 = gcol - 512; of = out + (prm ? O_KWP : O_KWS); orow = offA; }
.LBB0_338:
	s_andn2_b64 vcc, exec, s[26:27]
	s_cbranch_vccnz .LBB0_340
	v_lshlrev_b32_e32 v138, 2, v212
	v_mov_b32_e32 v139, v97
	v_lshl_add_u64 v[146:147], s[90:91], 0, v[138:139]
	s_waitcnt lgkmcnt(4)
	v_mov_b64_e32 v[144:145], v[132:133]
	v_mov_b64_e32 v[140:141], v[136:137]
	s_add_i32 s24, s11, 0xfffffe80
	s_waitcnt lgkmcnt(0)
	v_mov_b64_e32 v[150:151], s[78:79]
	v_mov_b64_e32 v[152:153], 0x80
	v_mov_b64_e32 v[148:149], v[210:211]
	v_mov_b64_e32 v[142:143], v[130:131]
	v_mov_b64_e32 v[138:139], v[134:135]

; #define LAS __attribute__((address_space(3)))
; DI unsigned pk2(float lo, float hi) { f32x2 v = {lo, hi}; hbf2 r = __builtin_convertvector(v, hbf2); return __builtin_bit_cast(unsigned, r); }
; DI float sigmoidf_(float a) { return fast_rcp(1.0f + fast_exp2(-a * LOG2E)); }
;     DI void operator()(f32x4 (&acc)[2][2][4][2], const Unit& u, int wr, int wc, int fr, int fq, LAS unsigned char* lds) const {
;     ...
;                     if (gcol < 512) { dst = QA; ld = 512; c0 = gcol; v0 = v0 * QSCALE; v1 = v1 * QSCALE; }
;                     else if (gcol < 640) { dst = KA; ld = 128; c0 = gcol - 512; of = out + (prm ? O_KWP : O_KWS); orow = offA; }
;                     else if (gcol < 768) { dst = VA; ld = 128; c0 = gcol - 640; of = out + (prm ? O_VWP : O_VWS); orow = offA; }
;                     else if (gcol < 1280) { dst = QB; ld = 512; c0 = gcol - 768; v0 = v0 * QSCALE; v1 = v1 * QSCALE; }
;                     else if (gcol < 1792) { dst = KB; ld = 512; c0 = gcol - 1280; of = out + (prm ? O_KBP : O_KBS); orow = offB; }
;                     else if (gcol < 2304) { dst = VB; ld = 512; c0 = gcol - 1792; of = out + (prm ? O_VBP : O_VBS); orow = offB; }
;                     else { dst = GATES; ld = 2048; c0 = gcol - 2304;
;                         const f32x4 g0 = *(const LAS f32x4*)(lds + BG_OFF + (c0 + cw) * 4), g1 = *(const LAS f32x4*)(lds + BG_OFF + (c0 + cw + 4) * 4);
; #pragma unroll
;                         for (int j = 0; j < 4; ++j) { v0[j] = sigmoidf_(v0[j] + g0[j]); v1[j] = sigmoidf_(v1[j] + g1[j]); } }
;                     u32x4 w; w.x = pk2(v0[0], v0[1]); w.y = pk2(v0[2], v0[3]); w.z = pk2(v1[0], v1[1]); w.w = pk2(v1[2], v1[3]);
;                     *(u32x4*)(dst + (size_t)row * ld + c0 + cw) = w;
;                     if (of != nullptr && orow >= 0) { float* op = of + orow + c0 + cw; *(f32x4*)op = v0; *(f32x4*)(op + 4) = v1; }
.LBB0_341:
	s_andn2_b64 vcc, exec, s[26:27]
	s_cbranch_vccnz .LBB0_343
	v_pk_mul_f32 v[140:141], v[136:137], s[66:67] op_sel_hi:[1,0]
	v_pk_mul_f32 v[138:139], v[134:135], s[66:67] op_sel_hi:[1,0]
	v_pk_mul_f32 v[144:145], v[132:133], s[66:67] op_sel_hi:[1,0]
	s_waitcnt lgkmcnt(4)
	v_pk_mul_f32 v[142:143], v[130:131], s[66:67] op_sel_hi:[1,0]
	s_waitcnt lgkmcnt(0)
	v_mov_b64_e32 v[148:149], -1
	v_mov_b64_e32 v[146:147], 0
	v_mov_b64_e32 v[150:151], s[74:75]
	v_mov_b64_e32 v[152:153], 0x200
	s_mov_b32 s24, s13
.LBB0_343:
	s_waitcnt lgkmcnt(5)
	v_mul_lo_u32 v136, v153, v208
	v_mul_lo_u32 v137, v152, v167
	v_mad_u64_u32 v[134:135], s[0:1], v152, v208, 0
	v_add3_u32 v135, v135, v137, v136
	s_waitcnt lgkmcnt(0)
	v_lshl_add_u64 v[134:135], v[134:135], 1, v[150:151]
	s_ashr_i32 s25, s24, 31
	v_lshl_add_u64 v[134:135], s[24:25], 1, v[134:135]
	v_cmp_ne_u64_e32 vcc, 0, v[146:147]
	v_cmp_lt_i64_e64 s[46:47], -1, v[148:149]
	v_cvt_pk_bf16_f32 v130, v138, v139
	v_cvt_pk_bf16_f32 v131, v140, v141
	s_waitcnt lgkmcnt(4)
	v_cvt_pk_bf16_f32 v132, v142, v143
	v_cvt_pk_bf16_f32 v133, v144, v145
	v_lshl_add_u64 v[134:135], v[134:135], 0, v[96:97]
	s_and_b64 s[0:1], vcc, s[46:47]
	global_store_dwordx4 v[134:135], v[130:133], off
	s_and_saveexec_b64 s[26:27], s[0:1]
	s_cbranch_execz .LBB0_345
	v_lshl_add_u64 v[130:131], v[148:149], 2, v[146:147]
	v_lshl_add_u64 v[130:131], s[24:25], 2, v[130:131]
	v_mov_b32_e32 v191, v97
	v_lshl_add_u64 v[130:131], v[130:131], 0, v[190:191]
	global_store_dwordx4 v[130:131], v[138:141], off
	global_store_dwordx4 v[130:131], v[142:145], off offset:16

;     DI void operator()(f32x4 (&acc)[2][2][4][2], const Unit& u, int wr, int wc, int fr, int fq, LAS unsigned char* lds) const {
;     ...
;                 const int row = row0 + ai * 128 + m * 16; const float rs = rsv[ai * 4 + m];
;                 int posidx; long offA, offB;
;                 const bool prm = row < TP;
;                 if (prm) { const int b = row >> 13, t = row & 8191; posidx = t;
;                     offA = t >= 8064 ? ((long)(layer * 4 + b) * 128 + (t - 8064)) * 128 : -1;
;                     offB = t >= 7680 ? ((long)(layer * 4 + b) * 512 + (t - 7680)) * 512 : -1;
;                 } else { const int sb = (row - TP) >> 6, t = (row - TP) & 63; posidx = 8192 + t;
;                     offA = ((long)(layer * 32 + sb) * 128 + 64 + t) * 128;
;                     offB = ((long)(layer * 32 + sb) * 512 + 448 + t) * 512; }
; #pragma unroll
;                 for (int bj = 0; bj < 2; ++bj) {
;                     const int gcol = u.pn * 256 + bj * 128;
;                     f32x4 v0 = acc[ai][bj][m][0] * rs, v1 = acc[ai][bj][m][1] * rs;
;                     if (gcol < 768 && gcol != 640) {
;                         if (rope_wave) {
;                             const float* rp = ROPE + (size_t)posidx * 16;
;                             const f32x4 cs0 = *(const f32x4*)rp, cs1 = *(const f32x4*)(rp + 4), sn0 = *(const f32x4*)(rp + 8), sn1 = *(const f32x4*)(rp + 12);
;                             f32x4 p0, p1;
; #pragma unroll
;                             for (int j = 0; j < 4; ++j) { p0[j] = __shfl_xor(v0[j], 16); p1[j] = __shfl_xor(v1[j], 16); }
;                             if (fq == 0) { v0 = v0 * cs0 - p0 * sn0; v1 = v1 * cs1 - p1 * sn1; }
;                             else if (fq == 1) { v0 = v0 * cs0 + p0 * sn0; v1 = v1 * cs1 + p1 * sn1; }
;                         }
.LBB0_353:
	s_or_b64 exec, exec, s[24:25]
	v_lshlrev_b32_e32 v130, 6, v130
	v_mov_b32_e32 v131, v97
	v_lshl_add_u64 v[220:221], s[82:83], 0, v[130:131]
	v_pk_mul_f32 v[136:137], v[112:113], v[204:205] op_sel_hi:[1,0]
	v_pk_mul_f32 v[134:135], v[110:111], v[204:205] op_sel_hi:[1,0]
	v_pk_mul_f32 v[132:133], v[108:109], v[204:205] op_sel_hi:[1,0]
	s_and_b64 vcc, exec, s[38:39]
	v_pk_mul_f32 v[130:131], v[106:107], v[204:205] op_sel_hi:[1,0]
	s_cbranch_vccnz .LBB0_361
	v_and_b32_e32 v139, 64, v229
	v_xor_b32_e32 v138, 16, v229
	v_add_u32_e32 v139, 64, v139
	v_cmp_lt_i32_e32 vcc, v138, v139
	s_nop 1
	v_cndmask_b32_e32 v138, v229, v138, vcc
	v_lshlrev_b32_e32 v138, 2, v138
	ds_bpermute_b32 v152, v138, v134
	ds_bpermute_b32 v142, v138, v130
	ds_bpermute_b32 v153, v138, v135
	ds_bpermute_b32 v143, v138, v131
	ds_bpermute_b32 v224, v138, v136
	ds_bpermute_b32 v222, v138, v132
	s_waitcnt lgkmcnt(6)
	ds_bpermute_b32 v225, v138, v137
	ds_bpermute_b32 v223, v138, v133
	v_subrev_u32_e32 v148, s82, v220
	v_and_b32_e32 v148, 0x3fff, v148
	ds_read_b128 v[144:147], v148 offset:49200
	ds_read_b128 v[154:157], v148 offset:49184
	ds_read_b128 v[138:141], v148 offset:49168
	ds_read_b128 v[148:151], v148 offset:49152
	v_cmp_lt_i32_e32 vcc, 0, v169
	s_and_saveexec_b64 s[0:1], vcc
	s_xor_b64 s[24:25], exec, s[0:1]
	s_cbranch_execz .LBB0_358
	v_cmp_eq_u32_e32 vcc, 1, v169
	s_and_saveexec_b64 s[26:27], vcc
	s_cbranch_execz .LBB0_357
	s_waitcnt lgkmcnt(0)
	v_pk_mul_f32 v[156:157], v[156:157], v[224:225]
	v_pk_mul_f32 v[152:153], v[154:155], v[152:153]
	s_waitcnt lgkmcnt(0)
	v_pk_mul_f32 v[146:147], v[146:147], v[222:223]
	v_pk_mul_f32 v[142:143], v[144:145], v[142:143]
	s_waitcnt lgkmcnt(0)
	v_pk_fma_f32 v[136:137], v[136:137], v[150:151], v[156:157]
	v_pk_fma_f32 v[134:135], v[134:135], v[148:149], v[152:153]
	v_pk_fma_f32 v[132:133], v[132:133], v[140:141], v[146:147]
	v_pk_fma_f32 v[130:131], v[130:131], v[138:139], v[142:143]

;     DI void operator()(f32x4 (&acc)[2][2][4][2], const Unit& u, int wr, int wc, int fr, int fq, LAS unsigned char* lds) const {
;     ...
;                             if (fq == 0) { v0 = v0 * cs0 - p0 * sn0; v1 = v1 * cs1 - p1 * sn1; }
;                             else if (fq == 1) { v0 = v0 * cs0 + p0 * sn0; v1 = v1 * cs1 + p1 * sn1; }
.LBB0_358:
	s_andn2_saveexec_b64 s[24:25], s[24:25]
	s_cbranch_execz .LBB0_360
	s_waitcnt lgkmcnt(0)
	v_pk_mul_f32 v[156:157], v[156:157], v[224:225]
	v_pk_mul_f32 v[152:153], v[154:155], v[152:153]
	s_waitcnt lgkmcnt(0)
	v_pk_mul_f32 v[146:147], v[146:147], v[222:223]
	v_pk_mul_f32 v[142:143], v[144:145], v[142:143]
	s_waitcnt lgkmcnt(0)
	v_pk_fma_f32 v[136:137], v[136:137], v[150:151], v[156:157] neg_lo:[0,0,1] neg_hi:[0,0,1]
	v_pk_fma_f32 v[134:135], v[134:135], v[148:149], v[152:153] neg_lo:[0,0,1] neg_hi:[0,0,1]
	v_pk_fma_f32 v[132:133], v[132:133], v[140:141], v[146:147] neg_lo:[0,0,1] neg_hi:[0,0,1]
	v_pk_fma_f32 v[130:131], v[130:131], v[138:139], v[142:143] neg_lo:[0,0,1] neg_hi:[0,0,1]

; #define LAS __attribute__((address_space(3)))
; DI float sigmoidf_(float a) { return fast_rcp(1.0f + fast_exp2(-a * LOG2E)); }
;     DI void operator()(f32x4 (&acc)[2][2][4][2], const Unit& u, int wr, int wc, int fr, int fq, LAS unsigned char* lds) const {
;     ...
;                     bf16_t* dst; int ld, c0; float* of = nullptr; long orow = -1;
;                     if (gcol < 512) { dst = QA; ld = 512; c0 = gcol; v0 = v0 * QSCALE; v1 = v1 * QSCALE; }
;                     else if (gcol < 640) { dst = KA; ld = 128; c0 = gcol - 512; of = out + (prm ? O_KWP : O_KWS); orow = offA; }
;                     else if (gcol < 768) { dst = VA; ld = 128; c0 = gcol - 640; of = out + (prm ? O_VWP : O_VWS); orow = offA; }
;                     else if (gcol < 1280) { dst = QB; ld = 512; c0 = gcol - 768; v0 = v0 * QSCALE; v1 = v1 * QSCALE; }
;                     else if (gcol < 1792) { dst = KB; ld = 512; c0 = gcol - 1280; of = out + (prm ? O_KBP : O_KBS); orow = offB; }
;                     else if (gcol < 2304) { dst = VB; ld = 512; c0 = gcol - 1792; of = out + (prm ? O_VBP : O_VBS); orow = offB; }
;                     else { dst = GATES; ld = 2048; c0 = gcol - 2304;
;                         const f32x4 g0 = *(const LAS f32x4*)(lds + BG_OFF + (c0 + cw) * 4), g1 = *(const LAS f32x4*)(lds + BG_OFF + (c0 + cw + 4) * 4);
; #pragma unroll
;                         for (int j = 0; j < 4; ++j) { v0[j] = sigmoidf_(v0[j] + g0[j]); v1[j] = sigmoidf_(v1[j] + g1[j]); } }
.LBB0_361:
	v_mov_b32_e32 v205, v204
	s_and_b64 vcc, exec, s[42:43]
	s_mov_b64 s[26:27], -1
	s_cbranch_vccnz .LBB0_369
	s_cmpk_lt_u32 s11, 0x280
	s_cbranch_scc1 .LBB0_649
	s_cmpk_lt_u32 s11, 0x500
	s_cbranch_scc1 .LBB0_646
	s_cmpk_lt_u32 s11, 0x700
	s_cbranch_scc1 .LBB0_643
	s_cmpk_lt_u32 s11, 0x900
	s_cbranch_scc1 .LBB0_367
	s_add_i32 s24, s11, 0xfffff700
	s_waitcnt lgkmcnt(0)
	v_or_b32_e32 v138, s24, v166
	v_lshl_add_u32 v138, v138, 2, 0
	s_waitcnt lgkmcnt(6)
	v_add_u32_e32 v142, 0x23040, v138
	ds_read_b128 v[138:141], v142
	s_waitcnt lgkmcnt(5)
	ds_read_b128 v[142:145], v142 offset:16
	s_mov_b64 s[26:27], 0
	s_waitcnt lgkmcnt(1)
	v_add_f32_e32 v138, v134, v138
	s_waitcnt lgkmcnt(0)
	v_add_f32_e32 v142, v130, v142
	v_add_f32_e32 v139, v135, v139
	v_add_f32_e32 v143, v131, v143
	v_add_f32_e32 v140, v136, v140
	v_add_f32_e32 v144, v132, v144
	v_add_f32_e32 v141, v137, v141
	v_add_f32_e32 v145, v133, v145
	v_mul_f32_e32 v138, 0xbfb8aa3b, v138
	v_mul_f32_e32 v142, 0xbfb8aa3b, v142
	v_mul_f32_e32 v139, 0xbfb8aa3b, v139
	v_mul_f32_e32 v143, 0xbfb8aa3b, v143
	v_mul_f32_e32 v140, 0xbfb8aa3b, v140
	v_mul_f32_e32 v144, 0xbfb8aa3b, v144
	v_mul_f32_e32 v141, 0xbfb8aa3b, v141
	v_mul_f32_e32 v145, 0xbfb8aa3b, v145
	v_exp_f32_e32 v138, v138
	v_exp_f32_e32 v142, v142
	v_exp_f32_e32 v139, v139
	v_exp_f32_e32 v143, v143
	v_exp_f32_e32 v140, v140
	v_exp_f32_e32 v144, v144
	v_exp_f32_e32 v141, v141
	v_exp_f32_e32 v145, v145
	v_add_f32_e32 v138, 1.0, v138
	v_add_f32_e32 v142, 1.0, v142
	v_add_f32_e32 v139, 1.0, v139
	v_add_f32_e32 v143, 1.0, v143
	v_add_f32_e32 v140, 1.0, v140
	v_add_f32_e32 v144, 1.0, v144
	v_add_f32_e32 v141, 1.0, v141
	v_add_f32_e32 v145, 1.0, v145
	v_rcp_f32_e32 v138, v138
	v_rcp_f32_e32 v142, v142
	v_rcp_f32_e32 v139, v139
	v_rcp_f32_e32 v143, v143
	v_rcp_f32_e32 v140, v140
	v_rcp_f32_e32 v144, v144
	v_rcp_f32_e32 v141, v141
	v_rcp_f32_e32 v145, v145
.LBB0_367:
	s_andn2_b64 vcc, exec, s[26:27]
	s_cbranch_vccnz .LBB0_641
	s_waitcnt lgkmcnt(0)
	v_lshlrev_b32_e32 v138, 2, v218
	v_mov_b32_e32 v139, v97
	v_lshl_add_u64 v[146:147], s[90:91], 0, v[138:139]
	v_readlane_b32 s30, v250, 42
	s_waitcnt lgkmcnt(4)
	v_mov_b64_e32 v[144:145], v[132:133]
	v_mov_b64_e32 v[140:141], v[136:137]
	s_add_i32 s24, s11, 0xfffff900
	s_mov_b64 s[28:29], 0x200
	s_waitcnt lgkmcnt(0)
	v_mov_b64_e32 v[148:149], v[214:215]
	v_readlane_b32 s31, v250, 43
	v_mov_b64_e32 v[142:143], v[130:131]
	v_mov_b64_e32 v[138:139], v[134:135]
	s_branch .LBB0_642

; #define LAS __attribute__((address_space(3)))
;     DI void operator()(f32x4 (&acc)[2][2][4][2], const Unit& u, int wr, int wc, int fr, int fq, LAS unsigned char* lds) const {
;     ...
;                 for (int bj = 0; bj < 2; ++bj) {
;                     const int gcol = u.pn * 256 + bj * 128;
;                     f32x4 v0 = acc[ai][bj][m][0] * rs, v1 = acc[ai][bj][m][1] * rs;
;                     if (gcol < 768 && gcol != 640) {
;                         if (rope_wave) {
;                             const float* rp = ROPE + (size_t)posidx * 16;
;                             const f32x4 cs0 = *(const f32x4*)rp, cs1 = *(const f32x4*)(rp + 4), sn0 = *(const f32x4*)(rp + 8), sn1 = *(const f32x4*)(rp + 12);
;                             f32x4 p0, p1;
; #pragma unroll
;                             for (int j = 0; j < 4; ++j) { p0[j] = __shfl_xor(v0[j], 16); p1[j] = __shfl_xor(v1[j], 16); }
;                             if (fq == 0) { v0 = v0 * cs0 - p0 * sn0; v1 = v1 * cs1 - p1 * sn1; }
;                             else if (fq == 1) { v0 = v0 * cs0 + p0 * sn0; v1 = v1 * cs1 + p1 * sn1; }
;                         }
;                     }
;                     bf16_t* dst; int ld, c0; float* of = nullptr; long orow = -1;
;                     if (gcol < 512) { dst = QA; ld = 512; c0 = gcol; v0 = v0 * QSCALE; v1 = v1 * QSCALE; }
;                     else if (gcol < 640) { dst = KA; ld = 128; c0 = gcol - 512; of = out + (prm ? O_KWP : O_KWS); orow = offA; }
;                     else if (gcol < 768) { dst = VA; ld = 128; c0 = gcol - 640; of = out + (prm ? O_VWP : O_VWS); orow = offA; }
;                     else if (gcol < 1280) { dst = QB; ld = 512; c0 = gcol - 768; v0 = v0 * QSCALE; v1 = v1 * QSCALE; }
;                     else if (gcol < 1792) { dst = KB; ld = 512; c0 = gcol - 1280; of = out + (prm ? O_KBP : O_KBS); orow = offB; }
;                     else if (gcol < 2304) { dst = VB; ld = 512; c0 = gcol - 1792; of = out + (prm ? O_VBP : O_VBS); orow = offB; }
;                     else { dst = GATES; ld = 2048; c0 = gcol - 2304;
;                         const f32x4 g0 = *(const LAS f32x4*)(lds + BG_OFF + (c0 + cw) * 4), g1 = *(const LAS f32x4*)(lds + BG_OFF + (c0 + cw + 4) * 4);
; #pragma unroll
;                         for (int j = 0; j < 4; ++j) { v0[j] = sigmoidf_(v0[j] + g0[j]); v1[j] = sigmoidf_(v1[j] + g1[j]); } }
.LBB0_370:
	s_waitcnt lgkmcnt(0)
	v_pk_mul_f32 v[140:141], v[136:137], s[66:67] op_sel_hi:[1,0]
	v_pk_mul_f32 v[138:139], v[134:135], s[66:67] op_sel_hi:[1,0]
	v_pk_mul_f32 v[144:145], v[132:133], s[66:67] op_sel_hi:[1,0]
	s_waitcnt lgkmcnt(4)
	v_pk_mul_f32 v[142:143], v[130:131], s[66:67] op_sel_hi:[1,0]
	s_waitcnt lgkmcnt(0)
	v_mov_b64_e32 v[148:149], -1
	v_mov_b64_e32 v[146:147], 0
	v_mov_b64_e32 v[150:151], s[74:75]
	v_mov_b64_e32 v[152:153], 0x200
	s_mov_b32 s24, s11
.LBB0_371:
	v_ashrrev_i32_e32 v167, 31, v206
	s_waitcnt lgkmcnt(5)
	v_mul_lo_u32 v136, v153, v206
	v_mul_lo_u32 v137, v152, v167
	v_mad_u64_u32 v[134:135], s[0:1], v152, v206, 0
	v_add3_u32 v135, v135, v137, v136
	s_waitcnt lgkmcnt(0)
	v_lshl_add_u64 v[134:135], v[134:135], 1, v[150:151]
	s_ashr_i32 s25, s24, 31
	v_lshl_add_u64 v[134:135], s[24:25], 1, v[134:135]
	v_cmp_ne_u64_e32 vcc, 0, v[146:147]
	v_cmp_lt_i64_e64 s[46:47], -1, v[148:149]
	v_cvt_pk_bf16_f32 v130, v138, v139
	v_cvt_pk_bf16_f32 v131, v140, v141
	s_waitcnt lgkmcnt(4)
	v_cvt_pk_bf16_f32 v132, v142, v143
	v_cvt_pk_bf16_f32 v133, v144, v145
	v_lshl_add_u64 v[134:135], v[134:135], 0, v[96:97]
	s_and_b64 s[0:1], vcc, s[46:47]
	global_store_dwordx4 v[134:135], v[130:133], off
	s_and_saveexec_b64 s[26:27], s[0:1]
	s_cbranch_execz .LBB0_373
	v_lshl_add_u64 v[130:131], v[148:149], 2, v[146:147]
	v_lshl_add_u64 v[130:131], s[24:25], 2, v[130:131]
	v_mov_b32_e32 v191, v97
	v_lshl_add_u64 v[130:131], v[130:131], 0, v[190:191]
	global_store_dwordx4 v[130:131], v[138:141], off
	global_store_dwordx4 v[130:131], v[142:145], off offset:16
.LBB0_373:
	s_or_b64 exec, exec, s[26:27]
	v_mov_b32_e32 v130, v204
	v_mov_b32_e32 v131, v204
	v_pk_mul_f32 v[136:137], v[78:79], v[130:131]
	v_pk_mul_f32 v[134:135], v[76:77], v[204:205]
	v_pk_mul_f32 v[132:133], v[74:75], v[130:131]
	s_and_b64 vcc, exec, s[40:41]
	v_pk_mul_f32 v[130:131], v[72:73], v[204:205]
	s_cbranch_vccnz .LBB0_381
	v_and_b32_e32 v139, 64, v229
	v_xor_b32_e32 v138, 16, v229
	v_add_u32_e32 v139, 64, v139
	v_cmp_lt_i32_e32 vcc, v138, v139
	s_nop 1
	v_cndmask_b32_e32 v138, v229, v138, vcc
	v_lshlrev_b32_e32 v138, 2, v138
	ds_bpermute_b32 v152, v138, v134
	ds_bpermute_b32 v142, v138, v130
	ds_bpermute_b32 v153, v138, v135
	ds_bpermute_b32 v143, v138, v131
	s_waitcnt lgkmcnt(6)
	ds_bpermute_b32 v222, v138, v136
	ds_bpermute_b32 v204, v138, v132
	s_waitcnt lgkmcnt(6)
	ds_bpermute_b32 v223, v138, v137
	ds_bpermute_b32 v205, v138, v133
	v_subrev_u32_e32 v148, s82, v220
	v_and_b32_e32 v148, 0x3fff, v148
	ds_read_b128 v[144:147], v148 offset:49200
	ds_read_b128 v[154:157], v148 offset:49184
	ds_read_b128 v[138:141], v148 offset:49168
	ds_read_b128 v[148:151], v148 offset:49152
	v_cmp_lt_i32_e32 vcc, 0, v169
	s_and_saveexec_b64 s[0:1], vcc
	s_xor_b64 s[24:25], exec, s[0:1]
	s_cbranch_execz .LBB0_378
	v_cmp_eq_u32_e32 vcc, 1, v169
	s_and_saveexec_b64 s[26:27], vcc
	s_cbranch_execz .LBB0_377
	s_waitcnt lgkmcnt(0)
	v_pk_mul_f32 v[156:157], v[156:157], v[222:223]
	v_pk_mul_f32 v[152:153], v[154:155], v[152:153]
	s_waitcnt lgkmcnt(0)
	v_pk_mul_f32 v[146:147], v[146:147], v[204:205]
	v_pk_mul_f32 v[142:143], v[144:145], v[142:143]
	s_waitcnt lgkmcnt(0)
	v_pk_fma_f32 v[136:137], v[136:137], v[150:151], v[156:157]
	v_pk_fma_f32 v[134:135], v[134:135], v[148:149], v[152:153]
	v_pk_fma_f32 v[132:133], v[132:133], v[140:141], v[146:147]
	v_pk_fma_f32 v[130:131], v[130:131], v[138:139], v[142:143]

;     DI void operator()(f32x4 (&acc)[2][2][4][2], const Unit& u, int wr, int wc, int fr, int fq, LAS unsigned char* lds) const {
;     ...
;                             if (fq == 0) { v0 = v0 * cs0 - p0 * sn0; v1 = v1 * cs1 - p1 * sn1; }
;                             else if (fq == 1) { v0 = v0 * cs0 + p0 * sn0; v1 = v1 * cs1 + p1 * sn1; }
.LBB0_378:
	s_andn2_saveexec_b64 s[24:25], s[24:25]
	s_cbranch_execz .LBB0_380
	s_waitcnt lgkmcnt(0)
	v_pk_mul_f32 v[156:157], v[156:157], v[222:223]
	v_pk_mul_f32 v[152:153], v[154:155], v[152:153]
	s_waitcnt lgkmcnt(0)
	v_pk_mul_f32 v[146:147], v[146:147], v[204:205]
	v_pk_mul_f32 v[142:143], v[144:145], v[142:143]
	s_waitcnt lgkmcnt(0)
	v_pk_fma_f32 v[136:137], v[136:137], v[150:151], v[156:157] neg_lo:[0,0,1] neg_hi:[0,0,1]
	v_pk_fma_f32 v[134:135], v[134:135], v[148:149], v[152:153] neg_lo:[0,0,1] neg_hi:[0,0,1]
	v_pk_fma_f32 v[132:133], v[132:133], v[140:141], v[146:147] neg_lo:[0,0,1] neg_hi:[0,0,1]
	v_pk_fma_f32 v[130:131], v[130:131], v[138:139], v[142:143] neg_lo:[0,0,1] neg_hi:[0,0,1]

; #define LAS __attribute__((address_space(3)))
; DI float sigmoidf_(float a) { return fast_rcp(1.0f + fast_exp2(-a * LOG2E)); }
;     DI void operator()(f32x4 (&acc)[2][2][4][2], const Unit& u, int wr, int wc, int fr, int fq, LAS unsigned char* lds) const {
;     ...
;                     bf16_t* dst; int ld, c0; float* of = nullptr; long orow = -1;
;                     if (gcol < 512) { dst = QA; ld = 512; c0 = gcol; v0 = v0 * QSCALE; v1 = v1 * QSCALE; }
;                     else if (gcol < 640) { dst = KA; ld = 128; c0 = gcol - 512; of = out + (prm ? O_KWP : O_KWS); orow = offA; }
;                     else if (gcol < 768) { dst = VA; ld = 128; c0 = gcol - 640; of = out + (prm ? O_VWP : O_VWS); orow = offA; }
;                     else if (gcol < 1280) { dst = QB; ld = 512; c0 = gcol - 768; v0 = v0 * QSCALE; v1 = v1 * QSCALE; }
;                     else if (gcol < 1792) { dst = KB; ld = 512; c0 = gcol - 1280; of = out + (prm ? O_KBP : O_KBS); orow = offB; }
;                     else if (gcol < 2304) { dst = VB; ld = 512; c0 = gcol - 1792; of = out + (prm ? O_VBP : O_VBS); orow = offB; }
;                     else { dst = GATES; ld = 2048; c0 = gcol - 2304;
;                         const f32x4 g0 = *(const LAS f32x4*)(lds + BG_OFF + (c0 + cw) * 4), g1 = *(const LAS f32x4*)(lds + BG_OFF + (c0 + cw + 4) * 4);
; #pragma unroll
;                         for (int j = 0; j < 4; ++j) { v0[j] = sigmoidf_(v0[j] + g0[j]); v1[j] = sigmoidf_(v1[j] + g1[j]); } }
.LBB0_381:
	s_and_b64 vcc, exec, s[44:45]
	s_mov_b64 s[26:27], -1
	s_cbranch_vccnz .LBB0_390
	s_cmpk_lt_u32 s13, 0x280
	s_cbranch_scc1 .LBB0_718
	s_andn2_b64 vcc, exec, s[22:23]
	s_cbranch_vccnz .LBB0_715
	s_cmpk_lt_u32 s11, 0x500
	s_cbranch_scc1 .LBB0_712
	s_cmpk_lt_u32 s11, 0x700
	s_cbranch_scc1 .LBB0_709
	s_cmpk_lt_u32 s11, 0x900
	s_cbranch_scc1 .LBB0_388
	s_add_i32 s24, s11, 0xfffff780
	s_waitcnt lgkmcnt(0)
	v_or_b32_e32 v138, s24, v166
	v_lshl_add_u32 v138, v138, 2, 0
	s_waitcnt lgkmcnt(6)
	v_add_u32_e32 v142, 0x23040, v138
	ds_read_b128 v[138:141], v142
	s_waitcnt lgkmcnt(5)
	ds_read_b128 v[142:145], v142 offset:16
	s_mov_b64 s[26:27], 0
	s_waitcnt lgkmcnt(1)
	v_add_f32_e32 v138, v134, v138
	s_waitcnt lgkmcnt(0)
	v_add_f32_e32 v142, v130, v142
	v_add_f32_e32 v139, v135, v139
	v_add_f32_e32 v143, v131, v143
	v_add_f32_e32 v140, v136, v140
	v_add_f32_e32 v144, v132, v144
	v_add_f32_e32 v141, v137, v141
	v_add_f32_e32 v145, v133, v145
	v_mul_f32_e32 v138, 0xbfb8aa3b, v138
	v_mul_f32_e32 v142, 0xbfb8aa3b, v142
	v_mul_f32_e32 v139, 0xbfb8aa3b, v139
	v_mul_f32_e32 v143, 0xbfb8aa3b, v143
	v_mul_f32_e32 v140, 0xbfb8aa3b, v140
	v_mul_f32_e32 v144, 0xbfb8aa3b, v144
	v_mul_f32_e32 v141, 0xbfb8aa3b, v141
	v_mul_f32_e32 v145, 0xbfb8aa3b, v145
	v_exp_f32_e32 v138, v138
	v_exp_f32_e32 v142, v142
	v_exp_f32_e32 v139, v139
	v_exp_f32_e32 v143, v143
	v_exp_f32_e32 v140, v140
	v_exp_f32_e32 v144, v144
	v_exp_f32_e32 v141, v141
	v_exp_f32_e32 v145, v145
	v_add_f32_e32 v138, 1.0, v138
	v_add_f32_e32 v142, 1.0, v142
	v_add_f32_e32 v139, 1.0, v139
	v_add_f32_e32 v143, 1.0, v143
	v_add_f32_e32 v140, 1.0, v140
	v_add_f32_e32 v144, 1.0, v144
	v_add_f32_e32 v141, 1.0, v141
	v_add_f32_e32 v145, 1.0, v145
	v_rcp_f32_e32 v138, v138
	v_rcp_f32_e32 v142, v142
	v_rcp_f32_e32 v139, v139
	v_rcp_f32_e32 v143, v143
	v_rcp_f32_e32 v140, v140
	v_rcp_f32_e32 v144, v144
	v_rcp_f32_e32 v141, v141
	v_rcp_f32_e32 v145, v145

; #define LAS __attribute__((address_space(3)))
; DI unsigned pk2(float lo, float hi) { f32x2 v = {lo, hi}; hbf2 r = __builtin_convertvector(v, hbf2); return __builtin_bit_cast(unsigned, r); }
; DI float sigmoidf_(float a) { return fast_rcp(1.0f + fast_exp2(-a * LOG2E)); }
;     DI void operator()(f32x4 (&acc)[2][2][4][2], const Unit& u, int wr, int wc, int fr, int fq, LAS unsigned char* lds) const {
;     ...
;                     if (gcol < 512) { dst = QA; ld = 512; c0 = gcol; v0 = v0 * QSCALE; v1 = v1 * QSCALE; }
;                     else if (gcol < 640) { dst = KA; ld = 128; c0 = gcol - 512; of = out + (prm ? O_KWP : O_KWS); orow = offA; }
;                     else if (gcol < 768) { dst = VA; ld = 128; c0 = gcol - 640; of = out + (prm ? O_VWP : O_VWS); orow = offA; }
;                     else if (gcol < 1280) { dst = QB; ld = 512; c0 = gcol - 768; v0 = v0 * QSCALE; v1 = v1 * QSCALE; }
;                     else if (gcol < 1792) { dst = KB; ld = 512; c0 = gcol - 1280; of = out + (prm ? O_KBP : O_KBS); orow = offB; }
;                     else if (gcol < 2304) { dst = VB; ld = 512; c0 = gcol - 1792; of = out + (prm ? O_VBP : O_VBS); orow = offB; }
;                     else { dst = GATES; ld = 2048; c0 = gcol - 2304;
;                         const f32x4 g0 = *(const LAS f32x4*)(lds + BG_OFF + (c0 + cw) * 4), g1 = *(const LAS f32x4*)(lds + BG_OFF + (c0 + cw + 4) * 4);
; #pragma unroll
;                         for (int j = 0; j < 4; ++j) { v0[j] = sigmoidf_(v0[j] + g0[j]); v1[j] = sigmoidf_(v1[j] + g1[j]); } }
;                     u32x4 w; w.x = pk2(v0[0], v0[1]); w.y = pk2(v0[2], v0[3]); w.z = pk2(v1[0], v1[1]); w.w = pk2(v1[2], v1[3]);
;                     *(u32x4*)(dst + (size_t)row * ld + c0 + cw) = w;
;                     if (of != nullptr && orow >= 0) { float* op = of + orow + c0 + cw; *(f32x4*)op = v0; *(f32x4*)(op + 4) = v1; }
.LBB0_391:
	s_waitcnt lgkmcnt(0)
	v_pk_mul_f32 v[140:141], v[136:137], s[66:67] op_sel_hi:[1,0]
	v_pk_mul_f32 v[138:139], v[134:135], s[66:67] op_sel_hi:[1,0]
	v_pk_mul_f32 v[144:145], v[132:133], s[66:67] op_sel_hi:[1,0]
	s_waitcnt lgkmcnt(4)
	v_pk_mul_f32 v[142:143], v[130:131], s[66:67] op_sel_hi:[1,0]
	s_waitcnt lgkmcnt(0)
	v_mov_b64_e32 v[148:149], -1
	v_mov_b64_e32 v[146:147], 0
	v_mov_b64_e32 v[150:151], s[74:75]
	v_mov_b64_e32 v[152:153], 0x200
	s_mov_b32 s24, s13
.LBB0_392:
	s_waitcnt lgkmcnt(5)
	v_mul_lo_u32 v136, v153, v206
	v_mul_lo_u32 v137, v152, v167
	v_mad_u64_u32 v[134:135], s[0:1], v152, v206, 0
	v_add3_u32 v135, v135, v137, v136
	s_waitcnt lgkmcnt(0)
	v_lshl_add_u64 v[134:135], v[134:135], 1, v[150:151]
	s_ashr_i32 s25, s24, 31
	v_lshl_add_u64 v[134:135], s[24:25], 1, v[134:135]
	v_cmp_ne_u64_e32 vcc, 0, v[146:147]
	v_cmp_lt_i64_e64 s[46:47], -1, v[148:149]
	v_cvt_pk_bf16_f32 v130, v138, v139
	v_cvt_pk_bf16_f32 v131, v140, v141
	s_waitcnt lgkmcnt(4)
	v_cvt_pk_bf16_f32 v132, v142, v143
	v_cvt_pk_bf16_f32 v133, v144, v145
	v_lshl_add_u64 v[134:135], v[134:135], 0, v[96:97]
	s_and_b64 s[0:1], vcc, s[46:47]
	global_store_dwordx4 v[134:135], v[130:133], off
	s_and_saveexec_b64 s[26:27], s[0:1]
	s_cbranch_execz .LBB0_394
	v_lshl_add_u64 v[130:131], v[148:149], 2, v[146:147]
	v_lshl_add_u64 v[130:131], s[24:25], 2, v[130:131]
	v_mov_b32_e32 v191, v97
	v_lshl_add_u64 v[130:131], v[130:131], 0, v[190:191]
	global_store_dwordx4 v[130:131], v[138:141], off
	global_store_dwordx4 v[130:131], v[142:145], off offset:16

;     DI void operator()(f32x4 (&acc)[2][2][4][2], const Unit& u, int wr, int wc, int fr, int fq, LAS unsigned char* lds) const {
;     ...
;                 const int row = row0 + ai * 128 + m * 16; const float rs = rsv[ai * 4 + m];
;                 int posidx; long offA, offB;
;                 const bool prm = row < TP;
;                 if (prm) { const int b = row >> 13, t = row & 8191; posidx = t;
;                     offA = t >= 8064 ? ((long)(layer * 4 + b) * 128 + (t - 8064)) * 128 : -1;
;                     offB = t >= 7680 ? ((long)(layer * 4 + b) * 512 + (t - 7680)) * 512 : -1;
;                 } else { const int sb = (row - TP) >> 6, t = (row - TP) & 63; posidx = 8192 + t;
;                     offA = ((long)(layer * 32 + sb) * 128 + 64 + t) * 128;
;                     offB = ((long)(layer * 32 + sb) * 512 + 448 + t) * 512; }
; #pragma unroll
;                 for (int bj = 0; bj < 2; ++bj) {
;                     const int gcol = u.pn * 256 + bj * 128;
;                     f32x4 v0 = acc[ai][bj][m][0] * rs, v1 = acc[ai][bj][m][1] * rs;
;                     if (gcol < 768 && gcol != 640) {
;                         if (rope_wave) {
;                             const float* rp = ROPE + (size_t)posidx * 16;
;                             const f32x4 cs0 = *(const f32x4*)rp, cs1 = *(const f32x4*)(rp + 4), sn0 = *(const f32x4*)(rp + 8), sn1 = *(const f32x4*)(rp + 12);
;                             f32x4 p0, p1;
; #pragma unroll
;                             for (int j = 0; j < 4; ++j) { p0[j] = __shfl_xor(v0[j], 16); p1[j] = __shfl_xor(v1[j], 16); }
;                             if (fq == 0) { v0 = v0 * cs0 - p0 * sn0; v1 = v1 * cs1 - p1 * sn1; }
;                             else if (fq == 1) { v0 = v0 * cs0 + p0 * sn0; v1 = v1 * cs1 + p1 * sn1; }
;                         }
.LBB0_402:
	s_or_b64 exec, exec, s[24:25]
	v_lshlrev_b32_e32 v130, 6, v132
	v_mov_b32_e32 v131, v97
	v_lshl_add_u64 v[216:217], s[82:83], 0, v[130:131]
	v_pk_mul_f32 v[136:137], v[104:105], v[200:201] op_sel_hi:[1,0]
	v_pk_mul_f32 v[134:135], v[102:103], v[200:201] op_sel_hi:[1,0]
	v_pk_mul_f32 v[132:133], v[100:101], v[200:201] op_sel_hi:[1,0]
	s_and_b64 vcc, exec, s[38:39]
	v_pk_mul_f32 v[130:131], v[98:99], v[200:201] op_sel_hi:[1,0]
	s_cbranch_vccnz .LBB0_410
	v_and_b32_e32 v139, 64, v229
	v_xor_b32_e32 v138, 16, v229
	v_add_u32_e32 v139, 64, v139
	v_cmp_lt_i32_e32 vcc, v138, v139
	s_nop 1
	v_cndmask_b32_e32 v138, v229, v138, vcc
	v_lshlrev_b32_e32 v138, 2, v138
	ds_bpermute_b32 v152, v138, v134
	ds_bpermute_b32 v142, v138, v130
	ds_bpermute_b32 v153, v138, v135
	ds_bpermute_b32 v143, v138, v131
	ds_bpermute_b32 v220, v138, v136
	ds_bpermute_b32 v218, v138, v132
	ds_bpermute_b32 v221, v138, v137
	ds_bpermute_b32 v219, v138, v133
	v_subrev_u32_e32 v148, s82, v216
	v_and_b32_e32 v148, 0x3fff, v148
	ds_read_b128 v[144:147], v148 offset:49200
	ds_read_b128 v[154:157], v148 offset:49184
	ds_read_b128 v[138:141], v148 offset:49168
	ds_read_b128 v[148:151], v148 offset:49152
	v_cmp_lt_i32_e32 vcc, 0, v169
	s_and_saveexec_b64 s[0:1], vcc
	s_xor_b64 s[24:25], exec, s[0:1]
	s_cbranch_execz .LBB0_407
	v_cmp_eq_u32_e32 vcc, 1, v169
	s_and_saveexec_b64 s[26:27], vcc
	s_cbranch_execz .LBB0_406
	s_waitcnt lgkmcnt(0)
	v_pk_mul_f32 v[156:157], v[156:157], v[220:221]
	v_pk_mul_f32 v[152:153], v[154:155], v[152:153]
	s_waitcnt lgkmcnt(0)
	v_pk_mul_f32 v[146:147], v[146:147], v[218:219]
	v_pk_mul_f32 v[142:143], v[144:145], v[142:143]
	s_waitcnt lgkmcnt(0)
	v_pk_fma_f32 v[136:137], v[136:137], v[150:151], v[156:157]
	v_pk_fma_f32 v[134:135], v[134:135], v[148:149], v[152:153]
	v_pk_fma_f32 v[132:133], v[132:133], v[140:141], v[146:147]
	v_pk_fma_f32 v[130:131], v[130:131], v[138:139], v[142:143]

;     DI void operator()(f32x4 (&acc)[2][2][4][2], const Unit& u, int wr, int wc, int fr, int fq, LAS unsigned char* lds) const {
;     ...
;                             if (fq == 0) { v0 = v0 * cs0 - p0 * sn0; v1 = v1 * cs1 - p1 * sn1; }
;                             else if (fq == 1) { v0 = v0 * cs0 + p0 * sn0; v1 = v1 * cs1 + p1 * sn1; }
.LBB0_407:
	s_andn2_saveexec_b64 s[24:25], s[24:25]
	s_cbranch_execz .LBB0_409
	s_waitcnt lgkmcnt(0)
	v_pk_mul_f32 v[156:157], v[156:157], v[220:221]
	v_pk_mul_f32 v[152:153], v[154:155], v[152:153]
	s_waitcnt lgkmcnt(0)
	v_pk_mul_f32 v[146:147], v[146:147], v[218:219]
	v_pk_mul_f32 v[142:143], v[144:145], v[142:143]
	s_waitcnt lgkmcnt(0)
	v_pk_fma_f32 v[136:137], v[136:137], v[150:151], v[156:157] neg_lo:[0,0,1] neg_hi:[0,0,1]
	v_pk_fma_f32 v[134:135], v[134:135], v[148:149], v[152:153] neg_lo:[0,0,1] neg_hi:[0,0,1]
	v_pk_fma_f32 v[132:133], v[132:133], v[140:141], v[146:147] neg_lo:[0,0,1] neg_hi:[0,0,1]
	v_pk_fma_f32 v[130:131], v[130:131], v[138:139], v[142:143] neg_lo:[0,0,1] neg_hi:[0,0,1]

; #define LAS __attribute__((address_space(3)))
; DI float sigmoidf_(float a) { return fast_rcp(1.0f + fast_exp2(-a * LOG2E)); }
;     DI void operator()(f32x4 (&acc)[2][2][4][2], const Unit& u, int wr, int wc, int fr, int fq, LAS unsigned char* lds) const {
;     ...
;                     bf16_t* dst; int ld, c0; float* of = nullptr; long orow = -1;
;                     if (gcol < 512) { dst = QA; ld = 512; c0 = gcol; v0 = v0 * QSCALE; v1 = v1 * QSCALE; }
;                     else if (gcol < 640) { dst = KA; ld = 128; c0 = gcol - 512; of = out + (prm ? O_KWP : O_KWS); orow = offA; }
;                     else if (gcol < 768) { dst = VA; ld = 128; c0 = gcol - 640; of = out + (prm ? O_VWP : O_VWS); orow = offA; }
;                     else if (gcol < 1280) { dst = QB; ld = 512; c0 = gcol - 768; v0 = v0 * QSCALE; v1 = v1 * QSCALE; }
;                     else if (gcol < 1792) { dst = KB; ld = 512; c0 = gcol - 1280; of = out + (prm ? O_KBP : O_KBS); orow = offB; }
;                     else if (gcol < 2304) { dst = VB; ld = 512; c0 = gcol - 1792; of = out + (prm ? O_VBP : O_VBS); orow = offB; }
;                     else { dst = GATES; ld = 2048; c0 = gcol - 2304;
;                         const f32x4 g0 = *(const LAS f32x4*)(lds + BG_OFF + (c0 + cw) * 4), g1 = *(const LAS f32x4*)(lds + BG_OFF + (c0 + cw + 4) * 4);
; #pragma unroll
;                         for (int j = 0; j < 4; ++j) { v0[j] = sigmoidf_(v0[j] + g0[j]); v1[j] = sigmoidf_(v1[j] + g1[j]); } }
.LBB0_410:
	v_mov_b32_e32 v201, v200
	s_and_b64 vcc, exec, s[42:43]
	s_mov_b64 s[26:27], -1
	s_cbranch_vccnz .LBB0_418
	s_cmpk_lt_u32 s11, 0x280
	s_cbranch_scc1 .LBB0_660
	s_cmpk_lt_u32 s11, 0x500
	s_cbranch_scc1 .LBB0_657
	s_cmpk_lt_u32 s11, 0x700
	s_cbranch_scc1 .LBB0_654
	s_cmpk_lt_u32 s11, 0x900
	s_cbranch_scc1 .LBB0_416
	s_add_i32 s24, s11, 0xfffff700
	s_waitcnt lgkmcnt(0)
	v_or_b32_e32 v138, s24, v166
	v_lshl_add_u32 v138, v138, 2, 0
	s_waitcnt lgkmcnt(6)
	v_add_u32_e32 v142, 0x23040, v138
	ds_read_b128 v[138:141], v142
	s_waitcnt lgkmcnt(5)
	ds_read_b128 v[142:145], v142 offset:16
	s_mov_b64 s[26:27], 0
	s_waitcnt lgkmcnt(1)
	v_add_f32_e32 v138, v134, v138
	s_waitcnt lgkmcnt(0)
	v_add_f32_e32 v142, v130, v142
	v_add_f32_e32 v139, v135, v139
	v_add_f32_e32 v143, v131, v143
	v_add_f32_e32 v140, v136, v140
	v_add_f32_e32 v144, v132, v144
	v_add_f32_e32 v141, v137, v141
	v_add_f32_e32 v145, v133, v145
	v_mul_f32_e32 v138, 0xbfb8aa3b, v138
	v_mul_f32_e32 v142, 0xbfb8aa3b, v142
	v_mul_f32_e32 v139, 0xbfb8aa3b, v139
	v_mul_f32_e32 v143, 0xbfb8aa3b, v143
	v_mul_f32_e32 v140, 0xbfb8aa3b, v140
	v_mul_f32_e32 v144, 0xbfb8aa3b, v144
	v_mul_f32_e32 v141, 0xbfb8aa3b, v141
	v_mul_f32_e32 v145, 0xbfb8aa3b, v145
	v_exp_f32_e32 v138, v138
	v_exp_f32_e32 v142, v142
	v_exp_f32_e32 v139, v139
	v_exp_f32_e32 v143, v143
	v_exp_f32_e32 v140, v140
	v_exp_f32_e32 v144, v144
	v_exp_f32_e32 v141, v141
	v_exp_f32_e32 v145, v145
	v_add_f32_e32 v138, 1.0, v138
	v_add_f32_e32 v142, 1.0, v142
	v_add_f32_e32 v139, 1.0, v139
	v_add_f32_e32 v143, 1.0, v143
	v_add_f32_e32 v140, 1.0, v140
	v_add_f32_e32 v144, 1.0, v144
	v_add_f32_e32 v141, 1.0, v141
	v_add_f32_e32 v145, 1.0, v145
	v_rcp_f32_e32 v138, v138
	v_rcp_f32_e32 v142, v142
	v_rcp_f32_e32 v139, v139
	v_rcp_f32_e32 v143, v143
	v_rcp_f32_e32 v140, v140
	v_rcp_f32_e32 v144, v144
	v_rcp_f32_e32 v141, v141
	v_rcp_f32_e32 v145, v145
.LBB0_416:
	s_andn2_b64 vcc, exec, s[26:27]
	s_cbranch_vccnz .LBB0_652
	s_waitcnt lgkmcnt(0)
	v_lshlrev_b32_e32 v138, 2, v214
	v_mov_b32_e32 v139, v97
	v_lshl_add_u64 v[146:147], s[90:91], 0, v[138:139]
	v_readlane_b32 s30, v250, 42
	s_waitcnt lgkmcnt(4)
	v_mov_b64_e32 v[144:145], v[132:133]
	v_mov_b64_e32 v[140:141], v[136:137]
	s_add_i32 s24, s11, 0xfffff900
	s_mov_b64 s[28:29], 0x200
	s_waitcnt lgkmcnt(0)
	v_mov_b64_e32 v[148:149], v[210:211]
	v_readlane_b32 s31, v250, 43
	v_mov_b64_e32 v[142:143], v[130:131]
	v_mov_b64_e32 v[138:139], v[134:135]
	s_branch .LBB0_653

; DI unsigned pk2(float lo, float hi) { f32x2 v = {lo, hi}; hbf2 r = __builtin_convertvector(v, hbf2); return __builtin_bit_cast(unsigned, r); }
;     DI void operator()(f32x4 (&acc)[2][2][4][2], const Unit& u, int wr, int wc, int fr, int fq, LAS unsigned char* lds) const {
;     ...
;                 for (int bj = 0; bj < 2; ++bj) {
;                     const int gcol = u.pn * 256 + bj * 128;
;                     f32x4 v0 = acc[ai][bj][m][0] * rs, v1 = acc[ai][bj][m][1] * rs;
;                     if (gcol < 768 && gcol != 640) {
;                         if (rope_wave) {
;                             const float* rp = ROPE + (size_t)posidx * 16;
;                             const f32x4 cs0 = *(const f32x4*)rp, cs1 = *(const f32x4*)(rp + 4), sn0 = *(const f32x4*)(rp + 8), sn1 = *(const f32x4*)(rp + 12);
;                             f32x4 p0, p1;
; #pragma unroll
;                             for (int j = 0; j < 4; ++j) { p0[j] = __shfl_xor(v0[j], 16); p1[j] = __shfl_xor(v1[j], 16); }
;                             if (fq == 0) { v0 = v0 * cs0 - p0 * sn0; v1 = v1 * cs1 - p1 * sn1; }
;                             else if (fq == 1) { v0 = v0 * cs0 + p0 * sn0; v1 = v1 * cs1 + p1 * sn1; }
;                         }
;     ...
;                     u32x4 w; w.x = pk2(v0[0], v0[1]); w.y = pk2(v0[2], v0[3]); w.z = pk2(v1[0], v1[1]); w.w = pk2(v1[2], v1[3]);
;                     *(u32x4*)(dst + (size_t)row * ld + c0 + cw) = w;
;                     if (of != nullptr && orow >= 0) { float* op = of + orow + c0 + cw; *(f32x4*)op = v0; *(f32x4*)(op + 4) = v1; }
.LBB0_420:
	v_ashrrev_i32_e32 v167, 31, v204
	s_waitcnt lgkmcnt(5)
	v_mul_lo_u32 v136, v153, v204
	v_mul_lo_u32 v137, v152, v167
	v_mad_u64_u32 v[134:135], s[0:1], v152, v204, 0
	v_add3_u32 v135, v135, v137, v136
	s_waitcnt lgkmcnt(0)
	v_lshl_add_u64 v[134:135], v[134:135], 1, v[150:151]
	s_ashr_i32 s25, s24, 31
	v_lshl_add_u64 v[134:135], s[24:25], 1, v[134:135]
	v_cmp_ne_u64_e32 vcc, 0, v[146:147]
	v_cmp_lt_i64_e64 s[46:47], -1, v[148:149]
	v_cvt_pk_bf16_f32 v130, v138, v139
	v_cvt_pk_bf16_f32 v131, v140, v141
	s_waitcnt lgkmcnt(4)
	v_cvt_pk_bf16_f32 v132, v142, v143
	v_cvt_pk_bf16_f32 v133, v144, v145
	v_lshl_add_u64 v[134:135], v[134:135], 0, v[96:97]
	s_and_b64 s[0:1], vcc, s[46:47]
	global_store_dwordx4 v[134:135], v[130:133], off
	s_and_saveexec_b64 s[26:27], s[0:1]
	s_cbranch_execz .LBB0_422
	v_lshl_add_u64 v[130:131], v[148:149], 2, v[146:147]
	v_lshl_add_u64 v[130:131], s[24:25], 2, v[130:131]
	v_mov_b32_e32 v191, v97
	v_lshl_add_u64 v[130:131], v[130:131], 0, v[190:191]
	global_store_dwordx4 v[130:131], v[138:141], off
	global_store_dwordx4 v[130:131], v[142:145], off offset:16
.LBB0_422:
	s_or_b64 exec, exec, s[26:27]
	v_mov_b32_e32 v130, v200
	v_mov_b32_e32 v131, v200
	v_pk_mul_f32 v[136:137], v[70:71], v[130:131]
	v_pk_mul_f32 v[134:135], v[68:69], v[200:201]
	v_pk_mul_f32 v[132:133], v[66:67], v[130:131]
	s_and_b64 vcc, exec, s[40:41]
	v_pk_mul_f32 v[130:131], v[64:65], v[200:201]
	s_cbranch_vccnz .LBB0_430
	v_and_b32_e32 v139, 64, v229
	v_xor_b32_e32 v138, 16, v229
	v_add_u32_e32 v139, 64, v139
	v_cmp_lt_i32_e32 vcc, v138, v139
	s_nop 1
	v_cndmask_b32_e32 v138, v229, v138, vcc
	v_lshlrev_b32_e32 v138, 2, v138
	ds_bpermute_b32 v152, v138, v134
	ds_bpermute_b32 v142, v138, v130
	ds_bpermute_b32 v153, v138, v135
	ds_bpermute_b32 v143, v138, v131
	s_waitcnt lgkmcnt(6)
	ds_bpermute_b32 v218, v138, v136
	ds_bpermute_b32 v200, v138, v132
	s_waitcnt lgkmcnt(6)
	ds_bpermute_b32 v219, v138, v137
	ds_bpermute_b32 v201, v138, v133
	v_subrev_u32_e32 v148, s82, v216
	v_and_b32_e32 v148, 0x3fff, v148
	ds_read_b128 v[144:147], v148 offset:49200
	ds_read_b128 v[154:157], v148 offset:49184
	ds_read_b128 v[138:141], v148 offset:49168
	ds_read_b128 v[148:151], v148 offset:49152
	v_cmp_lt_i32_e32 vcc, 0, v169
	s_and_saveexec_b64 s[0:1], vcc
	s_xor_b64 s[24:25], exec, s[0:1]
	s_cbranch_execz .LBB0_427
	v_cmp_eq_u32_e32 vcc, 1, v169
	s_and_saveexec_b64 s[26:27], vcc
	s_cbranch_execz .LBB0_426
	s_waitcnt lgkmcnt(0)
	v_pk_mul_f32 v[156:157], v[156:157], v[218:219]
	v_pk_mul_f32 v[152:153], v[154:155], v[152:153]
	s_waitcnt lgkmcnt(0)
	v_pk_mul_f32 v[146:147], v[146:147], v[200:201]
	v_pk_mul_f32 v[142:143], v[144:145], v[142:143]
	s_waitcnt lgkmcnt(0)
	v_pk_fma_f32 v[136:137], v[136:137], v[150:151], v[156:157]
	v_pk_fma_f32 v[134:135], v[134:135], v[148:149], v[152:153]
	v_pk_fma_f32 v[132:133], v[132:133], v[140:141], v[146:147]
	v_pk_fma_f32 v[130:131], v[130:131], v[138:139], v[142:143]

;     DI void operator()(f32x4 (&acc)[2][2][4][2], const Unit& u, int wr, int wc, int fr, int fq, LAS unsigned char* lds) const {
;     ...
;                             if (fq == 0) { v0 = v0 * cs0 - p0 * sn0; v1 = v1 * cs1 - p1 * sn1; }
;                             else if (fq == 1) { v0 = v0 * cs0 + p0 * sn0; v1 = v1 * cs1 + p1 * sn1; }
.LBB0_427:
	s_andn2_saveexec_b64 s[24:25], s[24:25]
	s_cbranch_execz .LBB0_429
	s_waitcnt lgkmcnt(0)
	v_pk_mul_f32 v[156:157], v[156:157], v[218:219]
	v_pk_mul_f32 v[152:153], v[154:155], v[152:153]
	s_waitcnt lgkmcnt(0)
	v_pk_mul_f32 v[146:147], v[146:147], v[200:201]
	v_pk_mul_f32 v[142:143], v[144:145], v[142:143]
	s_waitcnt lgkmcnt(0)
	v_pk_fma_f32 v[136:137], v[136:137], v[150:151], v[156:157] neg_lo:[0,0,1] neg_hi:[0,0,1]
	v_pk_fma_f32 v[134:135], v[134:135], v[148:149], v[152:153] neg_lo:[0,0,1] neg_hi:[0,0,1]
	v_pk_fma_f32 v[132:133], v[132:133], v[140:141], v[146:147] neg_lo:[0,0,1] neg_hi:[0,0,1]
	v_pk_fma_f32 v[130:131], v[130:131], v[138:139], v[142:143] neg_lo:[0,0,1] neg_hi:[0,0,1]

;     DI void operator()(f32x4 (&acc)[2][2][4][2], const Unit& u, int wr, int wc, int fr, int fq, LAS unsigned char* lds) const {
;     ...
;                     if (gcol < 512) { dst = QA; ld = 512; c0 = gcol; v0 = v0 * QSCALE; v1 = v1 * QSCALE; }
;                     else if (gcol < 640) { dst = KA; ld = 128; c0 = gcol - 512; of = out + (prm ? O_KWP : O_KWS); orow = offA; }
;                     else if (gcol < 768) { dst = VA; ld = 128; c0 = gcol - 640; of = out + (prm ? O_VWP : O_VWS); orow = offA; }
;                     else if (gcol < 1280) { dst = QB; ld = 512; c0 = gcol - 768; v0 = v0 * QSCALE; v1 = v1 * QSCALE; }
;                     else if (gcol < 1792) { dst = KB; ld = 512; c0 = gcol - 1280; of = out + (prm ? O_KBP : O_KBS); orow = offB; }
;                     else if (gcol < 2304) { dst = VB; ld = 512; c0 = gcol - 1792; of = out + (prm ? O_VBP : O_VBS); orow = offB; }
.LBB0_437:
	s_andn2_b64 vcc, exec, s[26:27]
	s_cbranch_vccnz .LBB0_721
	s_waitcnt lgkmcnt(0)
	v_lshlrev_b32_e32 v138, 2, v214
	v_mov_b32_e32 v139, v97
	v_lshl_add_u64 v[146:147], s[90:91], 0, v[138:139]
	v_readlane_b32 s30, v250, 42
	s_waitcnt lgkmcnt(4)
	v_mov_b64_e32 v[144:145], v[132:133]
	v_mov_b64_e32 v[140:141], v[136:137]
	s_add_i32 s24, s11, 0xfffff980
	s_mov_b64 s[28:29], 0x200
	s_waitcnt lgkmcnt(0)
	v_mov_b64_e32 v[148:149], v[210:211]
	v_readlane_b32 s31, v250, 43
	v_mov_b64_e32 v[142:143], v[130:131]
	v_mov_b64_e32 v[138:139], v[134:135]
	s_branch .LBB0_722

; DI unsigned pk2(float lo, float hi) { f32x2 v = {lo, hi}; hbf2 r = __builtin_convertvector(v, hbf2); return __builtin_bit_cast(unsigned, r); }
;     DI void operator()(f32x4 (&acc)[2][2][4][2], const Unit& u, int wr, int wc, int fr, int fq, LAS unsigned char* lds) const {
;     ...
;                     u32x4 w; w.x = pk2(v0[0], v0[1]); w.y = pk2(v0[2], v0[3]); w.z = pk2(v1[0], v1[1]); w.w = pk2(v1[2], v1[3]);
;                     *(u32x4*)(dst + (size_t)row * ld + c0 + cw) = w;
;                     if (of != nullptr && orow >= 0) { float* op = of + orow + c0 + cw; *(f32x4*)op = v0; *(f32x4*)(op + 4) = v1; }
.LBB0_441:
	s_waitcnt lgkmcnt(5)
	v_mul_lo_u32 v136, v153, v204
	v_mul_lo_u32 v137, v152, v167
	v_mad_u64_u32 v[134:135], s[0:1], v152, v204, 0
	v_add3_u32 v135, v135, v137, v136
	s_waitcnt lgkmcnt(0)
	v_lshl_add_u64 v[134:135], v[134:135], 1, v[150:151]
	s_ashr_i32 s25, s24, 31
	v_lshl_add_u64 v[134:135], s[24:25], 1, v[134:135]
	v_cmp_ne_u64_e32 vcc, 0, v[146:147]
	v_cmp_lt_i64_e64 s[46:47], -1, v[148:149]
	v_cvt_pk_bf16_f32 v130, v138, v139
	v_cvt_pk_bf16_f32 v131, v140, v141
	s_waitcnt lgkmcnt(4)
	v_cvt_pk_bf16_f32 v132, v142, v143
	v_cvt_pk_bf16_f32 v133, v144, v145
	v_lshl_add_u64 v[134:135], v[134:135], 0, v[96:97]
	s_and_b64 s[0:1], vcc, s[46:47]
	global_store_dwordx4 v[134:135], v[130:133], off
	s_and_saveexec_b64 s[26:27], s[0:1]
	s_cbranch_execz .LBB0_443
	v_lshl_add_u64 v[130:131], v[148:149], 2, v[146:147]
	v_lshl_add_u64 v[130:131], s[24:25], 2, v[130:131]
	v_mov_b32_e32 v191, v97
	v_lshl_add_u64 v[130:131], v[130:131], 0, v[190:191]
	global_store_dwordx4 v[130:131], v[138:141], off
	global_store_dwordx4 v[130:131], v[142:145], off offset:16

;     DI void operator()(f32x4 (&acc)[2][2][4][2], const Unit& u, int wr, int wc, int fr, int fq, LAS unsigned char* lds) const {
;     ...
;                 const int row = row0 + ai * 128 + m * 16; const float rs = rsv[ai * 4 + m];
;                 int posidx; long offA, offB;
;                 const bool prm = row < TP;
;                 if (prm) { const int b = row >> 13, t = row & 8191; posidx = t;
;                     offA = t >= 8064 ? ((long)(layer * 4 + b) * 128 + (t - 8064)) * 128 : -1;
;                     offB = t >= 7680 ? ((long)(layer * 4 + b) * 512 + (t - 7680)) * 512 : -1;
;                 } else { const int sb = (row - TP) >> 6, t = (row - TP) & 63; posidx = 8192 + t;
;                     offA = ((long)(layer * 32 + sb) * 128 + 64 + t) * 128;
;                     offB = ((long)(layer * 32 + sb) * 512 + 448 + t) * 512; }
; #pragma unroll
;                 for (int bj = 0; bj < 2; ++bj) {
;                     const int gcol = u.pn * 256 + bj * 128;
;                     f32x4 v0 = acc[ai][bj][m][0] * rs, v1 = acc[ai][bj][m][1] * rs;
;                     if (gcol < 768 && gcol != 640) {
;                         if (rope_wave) {
;                             const float* rp = ROPE + (size_t)posidx * 16;
;                             const f32x4 cs0 = *(const f32x4*)rp, cs1 = *(const f32x4*)(rp + 4), sn0 = *(const f32x4*)(rp + 8), sn1 = *(const f32x4*)(rp + 12);
;                             f32x4 p0, p1;
; #pragma unroll
;                             for (int j = 0; j < 4; ++j) { p0[j] = __shfl_xor(v0[j], 16); p1[j] = __shfl_xor(v1[j], 16); }
;                             if (fq == 0) { v0 = v0 * cs0 - p0 * sn0; v1 = v1 * cs1 - p1 * sn1; }
;                             else if (fq == 1) { v0 = v0 * cs0 + p0 * sn0; v1 = v1 * cs1 + p1 * sn1; }
;                         }
.LBB0_451:
	s_or_b64 exec, exec, s[24:25]
	v_lshlrev_b32_e32 v130, 6, v130
	v_mov_b32_e32 v131, v97
	v_lshl_add_u64 v[216:217], s[82:83], 0, v[130:131]
	v_pk_mul_f32 v[136:137], v[62:63], v[198:199] op_sel_hi:[1,0]
	v_pk_mul_f32 v[134:135], v[60:61], v[198:199] op_sel_hi:[1,0]
	v_pk_mul_f32 v[132:133], v[58:59], v[198:199] op_sel_hi:[1,0]
	s_and_b64 vcc, exec, s[38:39]
	v_pk_mul_f32 v[130:131], v[56:57], v[198:199] op_sel_hi:[1,0]
	s_cbranch_vccnz .LBB0_459
	v_and_b32_e32 v139, 64, v229
	v_xor_b32_e32 v138, 16, v229
	v_add_u32_e32 v139, 64, v139
	v_cmp_lt_i32_e32 vcc, v138, v139
	s_nop 1
	v_cndmask_b32_e32 v138, v229, v138, vcc
	v_lshlrev_b32_e32 v138, 2, v138
	ds_bpermute_b32 v152, v138, v134
	ds_bpermute_b32 v142, v138, v130
	ds_bpermute_b32 v153, v138, v135
	ds_bpermute_b32 v143, v138, v131
	ds_bpermute_b32 v220, v138, v136
	ds_bpermute_b32 v218, v138, v132
	ds_bpermute_b32 v221, v138, v137
	ds_bpermute_b32 v219, v138, v133
	v_subrev_u32_e32 v148, s82, v216
	v_and_b32_e32 v148, 0x3fff, v148
	ds_read_b128 v[144:147], v148 offset:49200
	ds_read_b128 v[154:157], v148 offset:49184
	ds_read_b128 v[138:141], v148 offset:49168
	ds_read_b128 v[148:151], v148 offset:49152
	v_cmp_lt_i32_e32 vcc, 0, v169
	s_and_saveexec_b64 s[0:1], vcc
	s_xor_b64 s[24:25], exec, s[0:1]
	s_cbranch_execz .LBB0_456
	v_cmp_eq_u32_e32 vcc, 1, v169
	s_and_saveexec_b64 s[26:27], vcc
	s_cbranch_execz .LBB0_455
	s_waitcnt lgkmcnt(0)
	v_pk_mul_f32 v[156:157], v[156:157], v[220:221]
	v_pk_mul_f32 v[152:153], v[154:155], v[152:153]
	s_waitcnt lgkmcnt(0)
	v_pk_mul_f32 v[146:147], v[146:147], v[218:219]
	v_pk_mul_f32 v[142:143], v[144:145], v[142:143]
	s_waitcnt lgkmcnt(0)
	v_pk_fma_f32 v[136:137], v[136:137], v[150:151], v[156:157]
	v_pk_fma_f32 v[134:135], v[134:135], v[148:149], v[152:153]
	v_pk_fma_f32 v[132:133], v[132:133], v[140:141], v[146:147]
	v_pk_fma_f32 v[130:131], v[130:131], v[138:139], v[142:143]

; #define LAS __attribute__((address_space(3)))
; DI float sigmoidf_(float a) { return fast_rcp(1.0f + fast_exp2(-a * LOG2E)); }
;     DI void operator()(f32x4 (&acc)[2][2][4][2], const Unit& u, int wr, int wc, int fr, int fq, LAS unsigned char* lds) const {
;     ...
;                     bf16_t* dst; int ld, c0; float* of = nullptr; long orow = -1;
;                     if (gcol < 512) { dst = QA; ld = 512; c0 = gcol; v0 = v0 * QSCALE; v1 = v1 * QSCALE; }
;                     else if (gcol < 640) { dst = KA; ld = 128; c0 = gcol - 512; of = out + (prm ? O_KWP : O_KWS); orow = offA; }
;                     else if (gcol < 768) { dst = VA; ld = 128; c0 = gcol - 640; of = out + (prm ? O_VWP : O_VWS); orow = offA; }
;                     else if (gcol < 1280) { dst = QB; ld = 512; c0 = gcol - 768; v0 = v0 * QSCALE; v1 = v1 * QSCALE; }
;                     else if (gcol < 1792) { dst = KB; ld = 512; c0 = gcol - 1280; of = out + (prm ? O_KBP : O_KBS); orow = offB; }
;                     else if (gcol < 2304) { dst = VB; ld = 512; c0 = gcol - 1792; of = out + (prm ? O_VBP : O_VBS); orow = offB; }
;                     else { dst = GATES; ld = 2048; c0 = gcol - 2304;
;                         const f32x4 g0 = *(const LAS f32x4*)(lds + BG_OFF + (c0 + cw) * 4), g1 = *(const LAS f32x4*)(lds + BG_OFF + (c0 + cw + 4) * 4);
; #pragma unroll
;                         for (int j = 0; j < 4; ++j) { v0[j] = sigmoidf_(v0[j] + g0[j]); v1[j] = sigmoidf_(v1[j] + g1[j]); } }
.LBB0_459:
	v_mov_b32_e32 v199, v198
	s_and_b64 vcc, exec, s[42:43]
	s_mov_b64 s[26:27], -1
	s_cbranch_vccnz .LBB0_467
	s_cmpk_lt_u32 s11, 0x280
	s_cbranch_scc1 .LBB0_671
	s_cmpk_lt_u32 s11, 0x500
	s_cbranch_scc1 .LBB0_668
	s_cmpk_lt_u32 s11, 0x700
	s_cbranch_scc1 .LBB0_665
	s_cmpk_lt_u32 s11, 0x900
	s_cbranch_scc1 .LBB0_465
	s_add_i32 s24, s11, 0xfffff700
	s_waitcnt lgkmcnt(0)
	v_or_b32_e32 v138, s24, v166
	v_lshl_add_u32 v138, v138, 2, 0
	s_waitcnt lgkmcnt(6)
	v_add_u32_e32 v142, 0x23040, v138
	ds_read_b128 v[138:141], v142
	s_waitcnt lgkmcnt(5)
	ds_read_b128 v[142:145], v142 offset:16
	s_mov_b64 s[26:27], 0
	s_waitcnt lgkmcnt(1)
	v_add_f32_e32 v138, v134, v138
	s_waitcnt lgkmcnt(0)
	v_add_f32_e32 v142, v130, v142
	v_add_f32_e32 v139, v135, v139
	v_add_f32_e32 v143, v131, v143
	v_add_f32_e32 v140, v136, v140
	v_add_f32_e32 v144, v132, v144
	v_add_f32_e32 v141, v137, v141
	v_add_f32_e32 v145, v133, v145
	v_mul_f32_e32 v138, 0xbfb8aa3b, v138
	v_mul_f32_e32 v142, 0xbfb8aa3b, v142
	v_mul_f32_e32 v139, 0xbfb8aa3b, v139
	v_mul_f32_e32 v143, 0xbfb8aa3b, v143
	v_mul_f32_e32 v140, 0xbfb8aa3b, v140
	v_mul_f32_e32 v144, 0xbfb8aa3b, v144
	v_mul_f32_e32 v141, 0xbfb8aa3b, v141
	v_mul_f32_e32 v145, 0xbfb8aa3b, v145
	v_exp_f32_e32 v138, v138
	v_exp_f32_e32 v142, v142
	v_exp_f32_e32 v139, v139
	v_exp_f32_e32 v143, v143
	v_exp_f32_e32 v140, v140
	v_exp_f32_e32 v144, v144
	v_exp_f32_e32 v141, v141
	v_exp_f32_e32 v145, v145
	v_add_f32_e32 v138, 1.0, v138
	v_add_f32_e32 v142, 1.0, v142
	v_add_f32_e32 v139, 1.0, v139
	v_add_f32_e32 v143, 1.0, v143
	v_add_f32_e32 v140, 1.0, v140
	v_add_f32_e32 v144, 1.0, v144
	v_add_f32_e32 v141, 1.0, v141
	v_add_f32_e32 v145, 1.0, v145
	v_rcp_f32_e32 v138, v138
	v_rcp_f32_e32 v142, v142
	v_rcp_f32_e32 v139, v139
	v_rcp_f32_e32 v143, v143
	v_rcp_f32_e32 v140, v140
	v_rcp_f32_e32 v144, v144
	v_rcp_f32_e32 v141, v141
	v_rcp_f32_e32 v145, v145

; DI unsigned pk2(float lo, float hi) { f32x2 v = {lo, hi}; hbf2 r = __builtin_convertvector(v, hbf2); return __builtin_bit_cast(unsigned, r); }
;     DI void operator()(f32x4 (&acc)[2][2][4][2], const Unit& u, int wr, int wc, int fr, int fq, LAS unsigned char* lds) const {
;     ...
;                 for (int bj = 0; bj < 2; ++bj) {
;                     const int gcol = u.pn * 256 + bj * 128;
;                     f32x4 v0 = acc[ai][bj][m][0] * rs, v1 = acc[ai][bj][m][1] * rs;
;                     if (gcol < 768 && gcol != 640) {
;                         if (rope_wave) {
;                             const float* rp = ROPE + (size_t)posidx * 16;
;                             const f32x4 cs0 = *(const f32x4*)rp, cs1 = *(const f32x4*)(rp + 4), sn0 = *(const f32x4*)(rp + 8), sn1 = *(const f32x4*)(rp + 12);
;                             f32x4 p0, p1;
; #pragma unroll
;                             for (int j = 0; j < 4; ++j) { p0[j] = __shfl_xor(v0[j], 16); p1[j] = __shfl_xor(v1[j], 16); }
;                             if (fq == 0) { v0 = v0 * cs0 - p0 * sn0; v1 = v1 * cs1 - p1 * sn1; }
;                             else if (fq == 1) { v0 = v0 * cs0 + p0 * sn0; v1 = v1 * cs1 + p1 * sn1; }
;                         }
;     ...
;                     u32x4 w; w.x = pk2(v0[0], v0[1]); w.y = pk2(v0[2], v0[3]); w.z = pk2(v1[0], v1[1]); w.w = pk2(v1[2], v1[3]);
;                     *(u32x4*)(dst + (size_t)row * ld + c0 + cw) = w;
;                     if (of != nullptr && orow >= 0) { float* op = of + orow + c0 + cw; *(f32x4*)op = v0; *(f32x4*)(op + 4) = v1; }
.LBB0_469:
	v_ashrrev_i32_e32 v167, 31, v202
	s_waitcnt lgkmcnt(5)
	v_mul_lo_u32 v136, v153, v202
	v_mul_lo_u32 v137, v152, v167
	v_mad_u64_u32 v[134:135], s[0:1], v152, v202, 0
	v_add3_u32 v135, v135, v137, v136
	s_waitcnt lgkmcnt(0)
	v_lshl_add_u64 v[134:135], v[134:135], 1, v[150:151]
	s_ashr_i32 s25, s24, 31
	v_lshl_add_u64 v[134:135], s[24:25], 1, v[134:135]
	v_cmp_ne_u64_e32 vcc, 0, v[146:147]
	v_cmp_lt_i64_e64 s[46:47], -1, v[148:149]
	v_cvt_pk_bf16_f32 v130, v138, v139
	v_cvt_pk_bf16_f32 v131, v140, v141
	s_waitcnt lgkmcnt(4)
	v_cvt_pk_bf16_f32 v132, v142, v143
	v_cvt_pk_bf16_f32 v133, v144, v145
	v_lshl_add_u64 v[134:135], v[134:135], 0, v[96:97]
	s_and_b64 s[0:1], vcc, s[46:47]
	global_store_dwordx4 v[134:135], v[130:133], off
	s_and_saveexec_b64 s[26:27], s[0:1]
	s_cbranch_execz .LBB0_471
	v_lshl_add_u64 v[130:131], v[148:149], 2, v[146:147]
	v_lshl_add_u64 v[130:131], s[24:25], 2, v[130:131]
	v_mov_b32_e32 v191, v97
	v_lshl_add_u64 v[130:131], v[130:131], 0, v[190:191]
	global_store_dwordx4 v[130:131], v[138:141], off
	global_store_dwordx4 v[130:131], v[142:145], off offset:16
.LBB0_471:
	s_or_b64 exec, exec, s[26:27]
	v_mov_b32_e32 v130, v198
	v_mov_b32_e32 v131, v198
	v_pk_mul_f32 v[136:137], v[30:31], v[130:131]
	v_pk_mul_f32 v[134:135], v[28:29], v[198:199]
	v_pk_mul_f32 v[132:133], v[26:27], v[130:131]
	s_and_b64 vcc, exec, s[40:41]
	v_pk_mul_f32 v[130:131], v[24:25], v[198:199]
	s_cbranch_vccnz .LBB0_479
	v_and_b32_e32 v139, 64, v229
	v_xor_b32_e32 v138, 16, v229
	v_add_u32_e32 v139, 64, v139
	v_cmp_lt_i32_e32 vcc, v138, v139
	s_nop 1
	v_cndmask_b32_e32 v138, v229, v138, vcc
	v_lshlrev_b32_e32 v138, 2, v138
	ds_bpermute_b32 v152, v138, v134
	ds_bpermute_b32 v142, v138, v130
	ds_bpermute_b32 v153, v138, v135
	ds_bpermute_b32 v143, v138, v131
	s_waitcnt lgkmcnt(6)
	ds_bpermute_b32 v218, v138, v136
	ds_bpermute_b32 v198, v138, v132
	s_waitcnt lgkmcnt(6)
	ds_bpermute_b32 v219, v138, v137
	ds_bpermute_b32 v199, v138, v133
	v_subrev_u32_e32 v148, s82, v216
	v_and_b32_e32 v148, 0x3fff, v148
	ds_read_b128 v[144:147], v148 offset:49200
	ds_read_b128 v[154:157], v148 offset:49184
	ds_read_b128 v[138:141], v148 offset:49168
	ds_read_b128 v[148:151], v148 offset:49152
	v_cmp_lt_i32_e32 vcc, 0, v169
	s_and_saveexec_b64 s[0:1], vcc
	s_xor_b64 s[24:25], exec, s[0:1]
	s_cbranch_execz .LBB0_476
	v_cmp_eq_u32_e32 vcc, 1, v169
	s_and_saveexec_b64 s[26:27], vcc
	s_cbranch_execz .LBB0_475
	s_waitcnt lgkmcnt(0)
	v_pk_mul_f32 v[156:157], v[156:157], v[218:219]
	v_pk_mul_f32 v[152:153], v[154:155], v[152:153]
	s_waitcnt lgkmcnt(0)
	v_pk_mul_f32 v[146:147], v[146:147], v[198:199]
	v_pk_mul_f32 v[142:143], v[144:145], v[142:143]
	s_waitcnt lgkmcnt(0)
	v_pk_fma_f32 v[136:137], v[136:137], v[150:151], v[156:157]
	v_pk_fma_f32 v[134:135], v[134:135], v[148:149], v[152:153]
	v_pk_fma_f32 v[132:133], v[132:133], v[140:141], v[146:147]
	v_pk_fma_f32 v[130:131], v[130:131], v[138:139], v[142:143]

;     DI void operator()(f32x4 (&acc)[2][2][4][2], const Unit& u, int wr, int wc, int fr, int fq, LAS unsigned char* lds) const {
;     ...
;                             if (fq == 0) { v0 = v0 * cs0 - p0 * sn0; v1 = v1 * cs1 - p1 * sn1; }
;                             else if (fq == 1) { v0 = v0 * cs0 + p0 * sn0; v1 = v1 * cs1 + p1 * sn1; }
.LBB0_476:
	s_andn2_saveexec_b64 s[24:25], s[24:25]
	s_cbranch_execz .LBB0_478
	s_waitcnt lgkmcnt(0)
	v_pk_mul_f32 v[156:157], v[156:157], v[218:219]
	v_pk_mul_f32 v[152:153], v[154:155], v[152:153]
	s_waitcnt lgkmcnt(0)
	v_pk_mul_f32 v[146:147], v[146:147], v[198:199]
	v_pk_mul_f32 v[142:143], v[144:145], v[142:143]
	s_waitcnt lgkmcnt(0)
	v_pk_fma_f32 v[136:137], v[136:137], v[150:151], v[156:157] neg_lo:[0,0,1] neg_hi:[0,0,1]
	v_pk_fma_f32 v[134:135], v[134:135], v[148:149], v[152:153] neg_lo:[0,0,1] neg_hi:[0,0,1]
	v_pk_fma_f32 v[132:133], v[132:133], v[140:141], v[146:147] neg_lo:[0,0,1] neg_hi:[0,0,1]
	v_pk_fma_f32 v[130:131], v[130:131], v[138:139], v[142:143] neg_lo:[0,0,1] neg_hi:[0,0,1]

; DI unsigned pk2(float lo, float hi) { f32x2 v = {lo, hi}; hbf2 r = __builtin_convertvector(v, hbf2); return __builtin_bit_cast(unsigned, r); }
;     DI void operator()(f32x4 (&acc)[2][2][4][2], const Unit& u, int wr, int wc, int fr, int fq, LAS unsigned char* lds) const {
;     ...
;                     u32x4 w; w.x = pk2(v0[0], v0[1]); w.y = pk2(v0[2], v0[3]); w.z = pk2(v1[0], v1[1]); w.w = pk2(v1[2], v1[3]);
;                     *(u32x4*)(dst + (size_t)row * ld + c0 + cw) = w;
;                     if (of != nullptr && orow >= 0) { float* op = of + orow + c0 + cw; *(f32x4*)op = v0; *(f32x4*)(op + 4) = v1; }
.LBB0_490:
	s_waitcnt lgkmcnt(5)
	v_mul_lo_u32 v136, v153, v202
	v_mul_lo_u32 v137, v152, v167
	v_mad_u64_u32 v[134:135], s[0:1], v152, v202, 0
	v_add3_u32 v135, v135, v137, v136
	s_waitcnt lgkmcnt(0)
	v_lshl_add_u64 v[134:135], v[134:135], 1, v[150:151]
	s_ashr_i32 s25, s24, 31
	v_lshl_add_u64 v[134:135], s[24:25], 1, v[134:135]
	v_cmp_ne_u64_e32 vcc, 0, v[146:147]
	v_cmp_lt_i64_e64 s[46:47], -1, v[148:149]
	v_cvt_pk_bf16_f32 v130, v138, v139
	v_cvt_pk_bf16_f32 v131, v140, v141
	s_waitcnt lgkmcnt(4)
	v_cvt_pk_bf16_f32 v132, v142, v143
	v_cvt_pk_bf16_f32 v133, v144, v145
	v_lshl_add_u64 v[134:135], v[134:135], 0, v[96:97]
	s_and_b64 s[0:1], vcc, s[46:47]
	global_store_dwordx4 v[134:135], v[130:133], off
	s_and_saveexec_b64 s[26:27], s[0:1]
	s_cbranch_execz .LBB0_492
	v_lshl_add_u64 v[130:131], v[148:149], 2, v[146:147]
	v_lshl_add_u64 v[130:131], s[24:25], 2, v[130:131]
	v_mov_b32_e32 v191, v97
	v_lshl_add_u64 v[130:131], v[130:131], 0, v[190:191]
	global_store_dwordx4 v[130:131], v[138:141], off
	global_store_dwordx4 v[130:131], v[142:145], off offset:16

;     DI void operator()(f32x4 (&acc)[2][2][4][2], const Unit& u, int wr, int wc, int fr, int fq, LAS unsigned char* lds) const {
;     ...
;                 const int row = row0 + ai * 128 + m * 16; const float rs = rsv[ai * 4 + m];
;                 int posidx; long offA, offB;
;                 const bool prm = row < TP;
;                 if (prm) { const int b = row >> 13, t = row & 8191; posidx = t;
;                     offA = t >= 8064 ? ((long)(layer * 4 + b) * 128 + (t - 8064)) * 128 : -1;
;                     offB = t >= 7680 ? ((long)(layer * 4 + b) * 512 + (t - 7680)) * 512 : -1;
;                 } else { const int sb = (row - TP) >> 6, t = (row - TP) & 63; posidx = 8192 + t;
;                     offA = ((long)(layer * 32 + sb) * 128 + 64 + t) * 128;
;                     offB = ((long)(layer * 32 + sb) * 512 + 448 + t) * 512; }
; #pragma unroll
;                 for (int bj = 0; bj < 2; ++bj) {
;                     const int gcol = u.pn * 256 + bj * 128;
;                     f32x4 v0 = acc[ai][bj][m][0] * rs, v1 = acc[ai][bj][m][1] * rs;
;                     if (gcol < 768 && gcol != 640) {
;                         if (rope_wave) {
;                             const float* rp = ROPE + (size_t)posidx * 16;
;                             const f32x4 cs0 = *(const f32x4*)rp, cs1 = *(const f32x4*)(rp + 4), sn0 = *(const f32x4*)(rp + 8), sn1 = *(const f32x4*)(rp + 12);
;                             f32x4 p0, p1;
; #pragma unroll
;                             for (int j = 0; j < 4; ++j) { p0[j] = __shfl_xor(v0[j], 16); p1[j] = __shfl_xor(v1[j], 16); }
;                             if (fq == 0) { v0 = v0 * cs0 - p0 * sn0; v1 = v1 * cs1 - p1 * sn1; }
;                             else if (fq == 1) { v0 = v0 * cs0 + p0 * sn0; v1 = v1 * cs1 + p1 * sn1; }
;                         }
.LBB0_500:
	s_or_b64 exec, exec, s[24:25]
	v_lshlrev_b32_e32 v130, 6, v130
	v_mov_b32_e32 v131, v97
	v_lshl_add_u64 v[214:215], s[82:83], 0, v[130:131]
	v_pk_mul_f32 v[136:137], v[54:55], v[196:197] op_sel_hi:[1,0]
	v_pk_mul_f32 v[134:135], v[52:53], v[196:197] op_sel_hi:[1,0]
	v_pk_mul_f32 v[132:133], v[50:51], v[196:197] op_sel_hi:[1,0]
	s_and_b64 vcc, exec, s[38:39]
	v_pk_mul_f32 v[130:131], v[48:49], v[196:197] op_sel_hi:[1,0]
	s_cbranch_vccnz .LBB0_508
	v_and_b32_e32 v139, 64, v229
	v_xor_b32_e32 v138, 16, v229
	v_add_u32_e32 v139, 64, v139
	v_cmp_lt_i32_e32 vcc, v138, v139
	s_nop 1
	v_cndmask_b32_e32 v138, v229, v138, vcc
	v_lshlrev_b32_e32 v138, 2, v138
	ds_bpermute_b32 v152, v138, v134
	ds_bpermute_b32 v142, v138, v130
	ds_bpermute_b32 v153, v138, v135
	ds_bpermute_b32 v143, v138, v131
	ds_bpermute_b32 v218, v138, v136
	ds_bpermute_b32 v216, v138, v132
	s_waitcnt lgkmcnt(6)
	ds_bpermute_b32 v219, v138, v137
	ds_bpermute_b32 v217, v138, v133
	v_subrev_u32_e32 v148, s82, v214
	v_and_b32_e32 v148, 0x3fff, v148
	ds_read_b128 v[144:147], v148 offset:49200
	ds_read_b128 v[154:157], v148 offset:49184
	ds_read_b128 v[138:141], v148 offset:49168
	ds_read_b128 v[148:151], v148 offset:49152
	v_cmp_lt_i32_e32 vcc, 0, v169
	s_and_saveexec_b64 s[0:1], vcc
	s_xor_b64 s[24:25], exec, s[0:1]
	s_cbranch_execz .LBB0_505
	v_cmp_eq_u32_e32 vcc, 1, v169
	s_and_saveexec_b64 s[26:27], vcc
	s_cbranch_execz .LBB0_504
	s_waitcnt lgkmcnt(0)
	v_pk_mul_f32 v[156:157], v[156:157], v[218:219]
	v_pk_mul_f32 v[152:153], v[154:155], v[152:153]
	s_waitcnt lgkmcnt(0)
	v_pk_mul_f32 v[146:147], v[146:147], v[216:217]
	v_pk_mul_f32 v[142:143], v[144:145], v[142:143]
	s_waitcnt lgkmcnt(0)
	v_pk_fma_f32 v[136:137], v[136:137], v[150:151], v[156:157]
	v_pk_fma_f32 v[134:135], v[134:135], v[148:149], v[152:153]
	v_pk_fma_f32 v[132:133], v[132:133], v[140:141], v[146:147]
	v_pk_fma_f32 v[130:131], v[130:131], v[138:139], v[142:143]

;     DI void operator()(f32x4 (&acc)[2][2][4][2], const Unit& u, int wr, int wc, int fr, int fq, LAS unsigned char* lds) const {
;     ...
;                             if (fq == 0) { v0 = v0 * cs0 - p0 * sn0; v1 = v1 * cs1 - p1 * sn1; }
;                             else if (fq == 1) { v0 = v0 * cs0 + p0 * sn0; v1 = v1 * cs1 + p1 * sn1; }
.LBB0_505:
	s_andn2_saveexec_b64 s[24:25], s[24:25]
	s_cbranch_execz .LBB0_507
	s_waitcnt lgkmcnt(0)
	v_pk_mul_f32 v[156:157], v[156:157], v[218:219]
	v_pk_mul_f32 v[152:153], v[154:155], v[152:153]
	s_waitcnt lgkmcnt(0)
	v_pk_mul_f32 v[146:147], v[146:147], v[216:217]
	v_pk_mul_f32 v[142:143], v[144:145], v[142:143]
	s_waitcnt lgkmcnt(0)
	v_pk_fma_f32 v[136:137], v[136:137], v[150:151], v[156:157] neg_lo:[0,0,1] neg_hi:[0,0,1]
	v_pk_fma_f32 v[134:135], v[134:135], v[148:149], v[152:153] neg_lo:[0,0,1] neg_hi:[0,0,1]
	v_pk_fma_f32 v[132:133], v[132:133], v[140:141], v[146:147] neg_lo:[0,0,1] neg_hi:[0,0,1]
	v_pk_fma_f32 v[130:131], v[130:131], v[138:139], v[142:143] neg_lo:[0,0,1] neg_hi:[0,0,1]

; #define LAS __attribute__((address_space(3)))
; DI float sigmoidf_(float a) { return fast_rcp(1.0f + fast_exp2(-a * LOG2E)); }
;     DI void operator()(f32x4 (&acc)[2][2][4][2], const Unit& u, int wr, int wc, int fr, int fq, LAS unsigned char* lds) const {
;     ...
;                     bf16_t* dst; int ld, c0; float* of = nullptr; long orow = -1;
;                     if (gcol < 512) { dst = QA; ld = 512; c0 = gcol; v0 = v0 * QSCALE; v1 = v1 * QSCALE; }
;                     else if (gcol < 640) { dst = KA; ld = 128; c0 = gcol - 512; of = out + (prm ? O_KWP : O_KWS); orow = offA; }
;                     else if (gcol < 768) { dst = VA; ld = 128; c0 = gcol - 640; of = out + (prm ? O_VWP : O_VWS); orow = offA; }
;                     else if (gcol < 1280) { dst = QB; ld = 512; c0 = gcol - 768; v0 = v0 * QSCALE; v1 = v1 * QSCALE; }
;                     else if (gcol < 1792) { dst = KB; ld = 512; c0 = gcol - 1280; of = out + (prm ? O_KBP : O_KBS); orow = offB; }
;                     else if (gcol < 2304) { dst = VB; ld = 512; c0 = gcol - 1792; of = out + (prm ? O_VBP : O_VBS); orow = offB; }
;                     else { dst = GATES; ld = 2048; c0 = gcol - 2304;
;                         const f32x4 g0 = *(const LAS f32x4*)(lds + BG_OFF + (c0 + cw) * 4), g1 = *(const LAS f32x4*)(lds + BG_OFF + (c0 + cw + 4) * 4);
; #pragma unroll
;                         for (int j = 0; j < 4; ++j) { v0[j] = sigmoidf_(v0[j] + g0[j]); v1[j] = sigmoidf_(v1[j] + g1[j]); } }
.LBB0_508:
	v_mov_b32_e32 v197, v196
	s_and_b64 vcc, exec, s[42:43]
	s_mov_b64 s[26:27], -1
	s_cbranch_vccnz .LBB0_516
	s_cmpk_lt_u32 s11, 0x280
	s_cbranch_scc1 .LBB0_682
	s_cmpk_lt_u32 s11, 0x500
	s_cbranch_scc1 .LBB0_679
	s_cmpk_lt_u32 s11, 0x700
	s_cbranch_scc1 .LBB0_676
	s_cmpk_lt_u32 s11, 0x900
	s_cbranch_scc1 .LBB0_514
	s_add_i32 s24, s11, 0xfffff700
	s_waitcnt lgkmcnt(0)
	v_or_b32_e32 v138, s24, v166
	v_lshl_add_u32 v138, v138, 2, 0
	s_waitcnt lgkmcnt(6)
	v_add_u32_e32 v142, 0x23040, v138
	ds_read_b128 v[138:141], v142
	s_waitcnt lgkmcnt(5)
	ds_read_b128 v[142:145], v142 offset:16
	s_mov_b64 s[26:27], 0
	s_waitcnt lgkmcnt(1)
	v_add_f32_e32 v138, v134, v138
	s_waitcnt lgkmcnt(0)
	v_add_f32_e32 v142, v130, v142
	v_add_f32_e32 v139, v135, v139
	v_add_f32_e32 v143, v131, v143
	v_add_f32_e32 v140, v136, v140
	v_add_f32_e32 v144, v132, v144
	v_add_f32_e32 v141, v137, v141
	v_add_f32_e32 v145, v133, v145
	v_mul_f32_e32 v138, 0xbfb8aa3b, v138
	v_mul_f32_e32 v142, 0xbfb8aa3b, v142
	v_mul_f32_e32 v139, 0xbfb8aa3b, v139
	v_mul_f32_e32 v143, 0xbfb8aa3b, v143
	v_mul_f32_e32 v140, 0xbfb8aa3b, v140
	v_mul_f32_e32 v144, 0xbfb8aa3b, v144
	v_mul_f32_e32 v141, 0xbfb8aa3b, v141
	v_mul_f32_e32 v145, 0xbfb8aa3b, v145
	v_exp_f32_e32 v138, v138
	v_exp_f32_e32 v142, v142
	v_exp_f32_e32 v139, v139
	v_exp_f32_e32 v143, v143
	v_exp_f32_e32 v140, v140
	v_exp_f32_e32 v144, v144
	v_exp_f32_e32 v141, v141
	v_exp_f32_e32 v145, v145
	v_add_f32_e32 v138, 1.0, v138
	v_add_f32_e32 v142, 1.0, v142
	v_add_f32_e32 v139, 1.0, v139
	v_add_f32_e32 v143, 1.0, v143
	v_add_f32_e32 v140, 1.0, v140
	v_add_f32_e32 v144, 1.0, v144
	v_add_f32_e32 v141, 1.0, v141
	v_add_f32_e32 v145, 1.0, v145
	v_rcp_f32_e32 v138, v138
	v_rcp_f32_e32 v142, v142
	v_rcp_f32_e32 v139, v139
	v_rcp_f32_e32 v143, v143
	v_rcp_f32_e32 v140, v140
	v_rcp_f32_e32 v144, v144
	v_rcp_f32_e32 v141, v141
	v_rcp_f32_e32 v145, v145
.LBB0_514:
	s_andn2_b64 vcc, exec, s[26:27]
	s_cbranch_vccnz .LBB0_674
	s_waitcnt lgkmcnt(0)
	v_lshlrev_b32_e32 v138, 2, v212
	v_mov_b32_e32 v139, v97
	v_lshl_add_u64 v[146:147], s[90:91], 0, v[138:139]
	v_readlane_b32 s30, v250, 42
	s_waitcnt lgkmcnt(4)
	v_mov_b64_e32 v[144:145], v[132:133]
	v_mov_b64_e32 v[140:141], v[136:137]
	s_add_i32 s24, s11, 0xfffff900
	s_mov_b64 s[28:29], 0x200
	s_waitcnt lgkmcnt(0)
	v_mov_b64_e32 v[148:149], v[208:209]
	v_readlane_b32 s31, v250, 43
	v_mov_b64_e32 v[142:143], v[130:131]
	v_mov_b64_e32 v[138:139], v[134:135]
	s_branch .LBB0_675

; DI unsigned pk2(float lo, float hi) { f32x2 v = {lo, hi}; hbf2 r = __builtin_convertvector(v, hbf2); return __builtin_bit_cast(unsigned, r); }
;     DI void operator()(f32x4 (&acc)[2][2][4][2], const Unit& u, int wr, int wc, int fr, int fq, LAS unsigned char* lds) const {
;     ...
;                 for (int bj = 0; bj < 2; ++bj) {
;                     const int gcol = u.pn * 256 + bj * 128;
;                     f32x4 v0 = acc[ai][bj][m][0] * rs, v1 = acc[ai][bj][m][1] * rs;
;                     if (gcol < 768 && gcol != 640) {
;                         if (rope_wave) {
;                             const float* rp = ROPE + (size_t)posidx * 16;
;                             const f32x4 cs0 = *(const f32x4*)rp, cs1 = *(const f32x4*)(rp + 4), sn0 = *(const f32x4*)(rp + 8), sn1 = *(const f32x4*)(rp + 12);
;                             f32x4 p0, p1;
; #pragma unroll
;                             for (int j = 0; j < 4; ++j) { p0[j] = __shfl_xor(v0[j], 16); p1[j] = __shfl_xor(v1[j], 16); }
;                             if (fq == 0) { v0 = v0 * cs0 - p0 * sn0; v1 = v1 * cs1 - p1 * sn1; }
;                             else if (fq == 1) { v0 = v0 * cs0 + p0 * sn0; v1 = v1 * cs1 + p1 * sn1; }
;                         }
;     ...
;                     u32x4 w; w.x = pk2(v0[0], v0[1]); w.y = pk2(v0[2], v0[3]); w.z = pk2(v1[0], v1[1]); w.w = pk2(v1[2], v1[3]);
;                     *(u32x4*)(dst + (size_t)row * ld + c0 + cw) = w;
;                     if (of != nullptr && orow >= 0) { float* op = of + orow + c0 + cw; *(f32x4*)op = v0; *(f32x4*)(op + 4) = v1; }
.LBB0_518:
	v_ashrrev_i32_e32 v167, 31, v198
	s_waitcnt lgkmcnt(5)
	v_mul_lo_u32 v136, v153, v198
	v_mul_lo_u32 v137, v152, v167
	v_mad_u64_u32 v[134:135], s[0:1], v152, v198, 0
	v_add3_u32 v135, v135, v137, v136
	s_waitcnt lgkmcnt(0)
	v_lshl_add_u64 v[134:135], v[134:135], 1, v[150:151]
	s_ashr_i32 s25, s24, 31
	v_lshl_add_u64 v[134:135], s[24:25], 1, v[134:135]
	v_cmp_ne_u64_e32 vcc, 0, v[146:147]
	v_cmp_lt_i64_e64 s[46:47], -1, v[148:149]
	v_cvt_pk_bf16_f32 v130, v138, v139
	v_cvt_pk_bf16_f32 v131, v140, v141
	s_waitcnt lgkmcnt(4)
	v_cvt_pk_bf16_f32 v132, v142, v143
	v_cvt_pk_bf16_f32 v133, v144, v145
	v_lshl_add_u64 v[134:135], v[134:135], 0, v[96:97]
	s_and_b64 s[0:1], vcc, s[46:47]
	global_store_dwordx4 v[134:135], v[130:133], off
	s_and_saveexec_b64 s[26:27], s[0:1]
	s_cbranch_execz .LBB0_520
	v_lshl_add_u64 v[130:131], v[148:149], 2, v[146:147]
	v_lshl_add_u64 v[130:131], s[24:25], 2, v[130:131]
	v_mov_b32_e32 v191, v97
	v_lshl_add_u64 v[130:131], v[130:131], 0, v[190:191]
	global_store_dwordx4 v[130:131], v[138:141], off
	global_store_dwordx4 v[130:131], v[142:145], off offset:16
.LBB0_520:
	s_or_b64 exec, exec, s[26:27]
	v_mov_b32_e32 v130, v196
	v_mov_b32_e32 v131, v196
	v_pk_mul_f32 v[136:137], v[22:23], v[130:131]
	v_pk_mul_f32 v[134:135], v[20:21], v[196:197]
	v_pk_mul_f32 v[132:133], v[18:19], v[130:131]
	s_and_b64 vcc, exec, s[40:41]
	v_pk_mul_f32 v[130:131], v[16:17], v[196:197]
	s_cbranch_vccnz .LBB0_528
	v_and_b32_e32 v139, 64, v229
	v_xor_b32_e32 v138, 16, v229
	v_add_u32_e32 v139, 64, v139
	v_cmp_lt_i32_e32 vcc, v138, v139
	s_nop 1
	v_cndmask_b32_e32 v138, v229, v138, vcc
	v_lshlrev_b32_e32 v138, 2, v138
	ds_bpermute_b32 v152, v138, v134
	ds_bpermute_b32 v142, v138, v130
	ds_bpermute_b32 v153, v138, v135
	ds_bpermute_b32 v143, v138, v131
	s_waitcnt lgkmcnt(6)
	ds_bpermute_b32 v216, v138, v136
	ds_bpermute_b32 v196, v138, v132
	s_waitcnt lgkmcnt(6)
	ds_bpermute_b32 v217, v138, v137
	ds_bpermute_b32 v197, v138, v133
	v_subrev_u32_e32 v148, s82, v214
	v_and_b32_e32 v148, 0x3fff, v148
	ds_read_b128 v[144:147], v148 offset:49200
	ds_read_b128 v[154:157], v148 offset:49184
	ds_read_b128 v[138:141], v148 offset:49168
	ds_read_b128 v[148:151], v148 offset:49152
	v_cmp_lt_i32_e32 vcc, 0, v169
	s_and_saveexec_b64 s[0:1], vcc
	s_xor_b64 s[24:25], exec, s[0:1]
	s_cbranch_execz .LBB0_525
	v_cmp_eq_u32_e32 vcc, 1, v169
	s_and_saveexec_b64 s[26:27], vcc
	s_cbranch_execz .LBB0_524
	s_waitcnt lgkmcnt(0)
	v_pk_mul_f32 v[156:157], v[156:157], v[216:217]
	v_pk_mul_f32 v[152:153], v[154:155], v[152:153]
	s_waitcnt lgkmcnt(0)
	v_pk_mul_f32 v[146:147], v[146:147], v[196:197]
	v_pk_mul_f32 v[142:143], v[144:145], v[142:143]
	s_waitcnt lgkmcnt(0)
	v_pk_fma_f32 v[136:137], v[136:137], v[150:151], v[156:157]
	v_pk_fma_f32 v[134:135], v[134:135], v[148:149], v[152:153]
	v_pk_fma_f32 v[132:133], v[132:133], v[140:141], v[146:147]
	v_pk_fma_f32 v[130:131], v[130:131], v[138:139], v[142:143]

;     DI void operator()(f32x4 (&acc)[2][2][4][2], const Unit& u, int wr, int wc, int fr, int fq, LAS unsigned char* lds) const {
;     ...
;                             if (fq == 0) { v0 = v0 * cs0 - p0 * sn0; v1 = v1 * cs1 - p1 * sn1; }
;                             else if (fq == 1) { v0 = v0 * cs0 + p0 * sn0; v1 = v1 * cs1 + p1 * sn1; }
.LBB0_525:
	s_andn2_saveexec_b64 s[24:25], s[24:25]
	s_cbranch_execz .LBB0_527
	s_waitcnt lgkmcnt(0)
	v_pk_mul_f32 v[156:157], v[156:157], v[216:217]
	v_pk_mul_f32 v[152:153], v[154:155], v[152:153]
	s_waitcnt lgkmcnt(0)
	v_pk_mul_f32 v[146:147], v[146:147], v[196:197]
	v_pk_mul_f32 v[142:143], v[144:145], v[142:143]
	s_waitcnt lgkmcnt(0)
	v_pk_fma_f32 v[136:137], v[136:137], v[150:151], v[156:157] neg_lo:[0,0,1] neg_hi:[0,0,1]
	v_pk_fma_f32 v[134:135], v[134:135], v[148:149], v[152:153] neg_lo:[0,0,1] neg_hi:[0,0,1]
	v_pk_fma_f32 v[132:133], v[132:133], v[140:141], v[146:147] neg_lo:[0,0,1] neg_hi:[0,0,1]
	v_pk_fma_f32 v[130:131], v[130:131], v[138:139], v[142:143] neg_lo:[0,0,1] neg_hi:[0,0,1]

;     DI void operator()(f32x4 (&acc)[2][2][4][2], const Unit& u, int wr, int wc, int fr, int fq, LAS unsigned char* lds) const {
;     ...
;                     if (gcol < 512) { dst = QA; ld = 512; c0 = gcol; v0 = v0 * QSCALE; v1 = v1 * QSCALE; }
;                     else if (gcol < 640) { dst = KA; ld = 128; c0 = gcol - 512; of = out + (prm ? O_KWP : O_KWS); orow = offA; }
;                     else if (gcol < 768) { dst = VA; ld = 128; c0 = gcol - 640; of = out + (prm ? O_VWP : O_VWS); orow = offA; }
;                     else if (gcol < 1280) { dst = QB; ld = 512; c0 = gcol - 768; v0 = v0 * QSCALE; v1 = v1 * QSCALE; }
;                     else if (gcol < 1792) { dst = KB; ld = 512; c0 = gcol - 1280; of = out + (prm ? O_KBP : O_KBS); orow = offB; }
;                     else if (gcol < 2304) { dst = VB; ld = 512; c0 = gcol - 1792; of = out + (prm ? O_VBP : O_VBS); orow = offB; }
.LBB0_535:
	s_andn2_b64 vcc, exec, s[26:27]
	s_cbranch_vccnz .LBB0_749
	s_waitcnt lgkmcnt(0)
	v_lshlrev_b32_e32 v138, 2, v212
	v_mov_b32_e32 v139, v97
	v_lshl_add_u64 v[146:147], s[90:91], 0, v[138:139]
	v_readlane_b32 s30, v250, 42
	s_waitcnt lgkmcnt(4)
	v_mov_b64_e32 v[144:145], v[132:133]
	v_mov_b64_e32 v[140:141], v[136:137]
	s_add_i32 s24, s11, 0xfffff980
	s_mov_b64 s[28:29], 0x200
	s_waitcnt lgkmcnt(0)
	v_mov_b64_e32 v[148:149], v[208:209]
	v_readlane_b32 s31, v250, 43
	v_mov_b64_e32 v[142:143], v[130:131]
	v_mov_b64_e32 v[138:139], v[134:135]
	s_branch .LBB0_750

; DI unsigned pk2(float lo, float hi) { f32x2 v = {lo, hi}; hbf2 r = __builtin_convertvector(v, hbf2); return __builtin_bit_cast(unsigned, r); }
;     DI void operator()(f32x4 (&acc)[2][2][4][2], const Unit& u, int wr, int wc, int fr, int fq, LAS unsigned char* lds) const {
;     ...
;                     u32x4 w; w.x = pk2(v0[0], v0[1]); w.y = pk2(v0[2], v0[3]); w.z = pk2(v1[0], v1[1]); w.w = pk2(v1[2], v1[3]);
;                     *(u32x4*)(dst + (size_t)row * ld + c0 + cw) = w;
;                     if (of != nullptr && orow >= 0) { float* op = of + orow + c0 + cw; *(f32x4*)op = v0; *(f32x4*)(op + 4) = v1; }
.LBB0_539:
	s_waitcnt lgkmcnt(5)
	v_mul_lo_u32 v136, v153, v198
	v_mul_lo_u32 v137, v152, v167
	v_mad_u64_u32 v[134:135], s[0:1], v152, v198, 0
	v_add3_u32 v135, v135, v137, v136
	s_waitcnt lgkmcnt(0)
	v_lshl_add_u64 v[134:135], v[134:135], 1, v[150:151]
	s_ashr_i32 s25, s24, 31
	v_lshl_add_u64 v[134:135], s[24:25], 1, v[134:135]
	v_cmp_ne_u64_e32 vcc, 0, v[146:147]
	v_cmp_lt_i64_e64 s[46:47], -1, v[148:149]
	v_cvt_pk_bf16_f32 v130, v138, v139
	v_cvt_pk_bf16_f32 v131, v140, v141
	s_waitcnt lgkmcnt(4)
	v_cvt_pk_bf16_f32 v132, v142, v143
	v_cvt_pk_bf16_f32 v133, v144, v145
	v_lshl_add_u64 v[134:135], v[134:135], 0, v[96:97]
	s_and_b64 s[0:1], vcc, s[46:47]
	global_store_dwordx4 v[134:135], v[130:133], off
	s_and_saveexec_b64 s[26:27], s[0:1]
	s_cbranch_execz .LBB0_541
	v_lshl_add_u64 v[130:131], v[148:149], 2, v[146:147]
	v_lshl_add_u64 v[130:131], s[24:25], 2, v[130:131]
	v_mov_b32_e32 v191, v97
	v_lshl_add_u64 v[130:131], v[130:131], 0, v[190:191]
	global_store_dwordx4 v[130:131], v[138:141], off
	global_store_dwordx4 v[130:131], v[142:145], off offset:16

;     DI void operator()(f32x4 (&acc)[2][2][4][2], const Unit& u, int wr, int wc, int fr, int fq, LAS unsigned char* lds) const {
;     ...
;                 const int row = row0 + ai * 128 + m * 16; const float rs = rsv[ai * 4 + m];
;                 int posidx; long offA, offB;
;                 const bool prm = row < TP;
;                 if (prm) { const int b = row >> 13, t = row & 8191; posidx = t;
;                     offA = t >= 8064 ? ((long)(layer * 4 + b) * 128 + (t - 8064)) * 128 : -1;
;                     offB = t >= 7680 ? ((long)(layer * 4 + b) * 512 + (t - 7680)) * 512 : -1;
;                 } else { const int sb = (row - TP) >> 6, t = (row - TP) & 63; posidx = 8192 + t;
;                     offA = ((long)(layer * 32 + sb) * 128 + 64 + t) * 128;
;                     offB = ((long)(layer * 32 + sb) * 512 + 448 + t) * 512; }
; #pragma unroll
;                 for (int bj = 0; bj < 2; ++bj) {
;                     const int gcol = u.pn * 256 + bj * 128;
;                     f32x4 v0 = acc[ai][bj][m][0] * rs, v1 = acc[ai][bj][m][1] * rs;
;                     if (gcol < 768 && gcol != 640) {
;                         if (rope_wave) {
;                             const float* rp = ROPE + (size_t)posidx * 16;
;                             const f32x4 cs0 = *(const f32x4*)rp, cs1 = *(const f32x4*)(rp + 4), sn0 = *(const f32x4*)(rp + 8), sn1 = *(const f32x4*)(rp + 12);
;                             f32x4 p0, p1;
; #pragma unroll
;                             for (int j = 0; j < 4; ++j) { p0[j] = __shfl_xor(v0[j], 16); p1[j] = __shfl_xor(v1[j], 16); }
;                             if (fq == 0) { v0 = v0 * cs0 - p0 * sn0; v1 = v1 * cs1 - p1 * sn1; }
;                             else if (fq == 1) { v0 = v0 * cs0 + p0 * sn0; v1 = v1 * cs1 + p1 * sn1; }
;                         }
.LBB0_549:
	s_or_b64 exec, exec, s[24:25]
	v_lshlrev_b32_e32 v130, 6, v130
	v_mov_b32_e32 v131, v97
	v_lshl_add_u64 v[212:213], s[82:83], 0, v[130:131]
	v_pk_mul_f32 v[136:137], v[46:47], v[194:195] op_sel_hi:[1,0]
	v_pk_mul_f32 v[134:135], v[44:45], v[194:195] op_sel_hi:[1,0]
	v_pk_mul_f32 v[132:133], v[42:43], v[194:195] op_sel_hi:[1,0]
	s_and_b64 vcc, exec, s[38:39]
	v_pk_mul_f32 v[130:131], v[40:41], v[194:195] op_sel_hi:[1,0]
	s_cbranch_vccnz .LBB0_557
	v_and_b32_e32 v139, 64, v229
	v_xor_b32_e32 v138, 16, v229
	v_add_u32_e32 v139, 64, v139
	v_cmp_lt_i32_e32 vcc, v138, v139
	s_nop 1
	v_cndmask_b32_e32 v138, v229, v138, vcc
	v_lshlrev_b32_e32 v138, 2, v138
	ds_bpermute_b32 v152, v138, v134
	ds_bpermute_b32 v142, v138, v130
	ds_bpermute_b32 v153, v138, v135
	ds_bpermute_b32 v143, v138, v131
	ds_bpermute_b32 v216, v138, v136
	ds_bpermute_b32 v214, v138, v132
	s_waitcnt lgkmcnt(6)
	ds_bpermute_b32 v217, v138, v137
	ds_bpermute_b32 v215, v138, v133
	v_subrev_u32_e32 v148, s82, v212
	v_and_b32_e32 v148, 0x3fff, v148
	ds_read_b128 v[144:147], v148 offset:49200
	ds_read_b128 v[154:157], v148 offset:49184
	ds_read_b128 v[138:141], v148 offset:49168
	ds_read_b128 v[148:151], v148 offset:49152
	v_cmp_lt_i32_e32 vcc, 0, v169
	s_and_saveexec_b64 s[0:1], vcc
	s_xor_b64 s[24:25], exec, s[0:1]
	s_cbranch_execz .LBB0_554
	v_cmp_eq_u32_e32 vcc, 1, v169
	s_and_saveexec_b64 s[26:27], vcc
	s_cbranch_execz .LBB0_553
	s_waitcnt lgkmcnt(0)
	v_pk_mul_f32 v[156:157], v[156:157], v[216:217]
	v_pk_mul_f32 v[152:153], v[154:155], v[152:153]
	s_waitcnt lgkmcnt(0)
	v_pk_mul_f32 v[146:147], v[146:147], v[214:215]
	v_pk_mul_f32 v[142:143], v[144:145], v[142:143]
	s_waitcnt lgkmcnt(0)
	v_pk_fma_f32 v[136:137], v[136:137], v[150:151], v[156:157]
	v_pk_fma_f32 v[134:135], v[134:135], v[148:149], v[152:153]
	v_pk_fma_f32 v[132:133], v[132:133], v[140:141], v[146:147]
	v_pk_fma_f32 v[130:131], v[130:131], v[138:139], v[142:143]

;     DI void operator()(f32x4 (&acc)[2][2][4][2], const Unit& u, int wr, int wc, int fr, int fq, LAS unsigned char* lds) const {
;     ...
;                             if (fq == 0) { v0 = v0 * cs0 - p0 * sn0; v1 = v1 * cs1 - p1 * sn1; }
;                             else if (fq == 1) { v0 = v0 * cs0 + p0 * sn0; v1 = v1 * cs1 + p1 * sn1; }
.LBB0_554:
	s_andn2_saveexec_b64 s[24:25], s[24:25]
	s_cbranch_execz .LBB0_556
	s_waitcnt lgkmcnt(0)
	v_pk_mul_f32 v[156:157], v[156:157], v[216:217]
	v_pk_mul_f32 v[152:153], v[154:155], v[152:153]
	s_waitcnt lgkmcnt(0)
	v_pk_mul_f32 v[146:147], v[146:147], v[214:215]
	v_pk_mul_f32 v[142:143], v[144:145], v[142:143]
	s_waitcnt lgkmcnt(0)
	v_pk_fma_f32 v[136:137], v[136:137], v[150:151], v[156:157] neg_lo:[0,0,1] neg_hi:[0,0,1]
	v_pk_fma_f32 v[134:135], v[134:135], v[148:149], v[152:153] neg_lo:[0,0,1] neg_hi:[0,0,1]
	v_pk_fma_f32 v[132:133], v[132:133], v[140:141], v[146:147] neg_lo:[0,0,1] neg_hi:[0,0,1]
	v_pk_fma_f32 v[130:131], v[130:131], v[138:139], v[142:143] neg_lo:[0,0,1] neg_hi:[0,0,1]

; #define LAS __attribute__((address_space(3)))
; DI float sigmoidf_(float a) { return fast_rcp(1.0f + fast_exp2(-a * LOG2E)); }
;     DI void operator()(f32x4 (&acc)[2][2][4][2], const Unit& u, int wr, int wc, int fr, int fq, LAS unsigned char* lds) const {
;     ...
;                     bf16_t* dst; int ld, c0; float* of = nullptr; long orow = -1;
;                     if (gcol < 512) { dst = QA; ld = 512; c0 = gcol; v0 = v0 * QSCALE; v1 = v1 * QSCALE; }
;                     else if (gcol < 640) { dst = KA; ld = 128; c0 = gcol - 512; of = out + (prm ? O_KWP : O_KWS); orow = offA; }
;                     else if (gcol < 768) { dst = VA; ld = 128; c0 = gcol - 640; of = out + (prm ? O_VWP : O_VWS); orow = offA; }
;                     else if (gcol < 1280) { dst = QB; ld = 512; c0 = gcol - 768; v0 = v0 * QSCALE; v1 = v1 * QSCALE; }
;                     else if (gcol < 1792) { dst = KB; ld = 512; c0 = gcol - 1280; of = out + (prm ? O_KBP : O_KBS); orow = offB; }
;                     else if (gcol < 2304) { dst = VB; ld = 512; c0 = gcol - 1792; of = out + (prm ? O_VBP : O_VBS); orow = offB; }
;                     else { dst = GATES; ld = 2048; c0 = gcol - 2304;
;                         const f32x4 g0 = *(const LAS f32x4*)(lds + BG_OFF + (c0 + cw) * 4), g1 = *(const LAS f32x4*)(lds + BG_OFF + (c0 + cw + 4) * 4);
; #pragma unroll
;                         for (int j = 0; j < 4; ++j) { v0[j] = sigmoidf_(v0[j] + g0[j]); v1[j] = sigmoidf_(v1[j] + g1[j]); } }
.LBB0_557:
	v_mov_b32_e32 v195, v194
	s_and_b64 vcc, exec, s[42:43]
	s_mov_b64 s[26:27], -1
	s_cbranch_vccnz .LBB0_565
	s_cmpk_lt_u32 s11, 0x280
	s_cbranch_scc1 .LBB0_693
	s_cmpk_lt_u32 s11, 0x500
	s_cbranch_scc1 .LBB0_690
	s_cmpk_lt_u32 s11, 0x700
	s_cbranch_scc1 .LBB0_687
	s_cmpk_lt_u32 s11, 0x900
	s_cbranch_scc1 .LBB0_563
	s_add_i32 s24, s11, 0xfffff700
	s_waitcnt lgkmcnt(0)
	v_or_b32_e32 v138, s24, v166
	v_lshl_add_u32 v138, v138, 2, 0
	s_waitcnt lgkmcnt(6)
	v_add_u32_e32 v142, 0x23040, v138
	ds_read_b128 v[138:141], v142
	s_waitcnt lgkmcnt(5)
	ds_read_b128 v[142:145], v142 offset:16
	s_mov_b64 s[26:27], 0
	s_waitcnt lgkmcnt(1)
	v_add_f32_e32 v138, v134, v138
	s_waitcnt lgkmcnt(0)
	v_add_f32_e32 v142, v130, v142
	v_add_f32_e32 v139, v135, v139
	v_add_f32_e32 v143, v131, v143
	v_add_f32_e32 v140, v136, v140
	v_add_f32_e32 v144, v132, v144
	v_add_f32_e32 v141, v137, v141
	v_add_f32_e32 v145, v133, v145
	v_mul_f32_e32 v138, 0xbfb8aa3b, v138
	v_mul_f32_e32 v142, 0xbfb8aa3b, v142
	v_mul_f32_e32 v139, 0xbfb8aa3b, v139
	v_mul_f32_e32 v143, 0xbfb8aa3b, v143
	v_mul_f32_e32 v140, 0xbfb8aa3b, v140
	v_mul_f32_e32 v144, 0xbfb8aa3b, v144
	v_mul_f32_e32 v141, 0xbfb8aa3b, v141
	v_mul_f32_e32 v145, 0xbfb8aa3b, v145
	v_exp_f32_e32 v138, v138
	v_exp_f32_e32 v142, v142
	v_exp_f32_e32 v139, v139
	v_exp_f32_e32 v143, v143
	v_exp_f32_e32 v140, v140
	v_exp_f32_e32 v144, v144
	v_exp_f32_e32 v141, v141
	v_exp_f32_e32 v145, v145
	v_add_f32_e32 v138, 1.0, v138
	v_add_f32_e32 v142, 1.0, v142
	v_add_f32_e32 v139, 1.0, v139
	v_add_f32_e32 v143, 1.0, v143
	v_add_f32_e32 v140, 1.0, v140
	v_add_f32_e32 v144, 1.0, v144
	v_add_f32_e32 v141, 1.0, v141
	v_add_f32_e32 v145, 1.0, v145
	v_rcp_f32_e32 v138, v138
	v_rcp_f32_e32 v142, v142
	v_rcp_f32_e32 v139, v139
	v_rcp_f32_e32 v143, v143
	v_rcp_f32_e32 v140, v140
	v_rcp_f32_e32 v144, v144
	v_rcp_f32_e32 v141, v141
	v_rcp_f32_e32 v145, v145
.LBB0_563:
	s_andn2_b64 vcc, exec, s[26:27]
	s_cbranch_vccnz .LBB0_685
	s_waitcnt lgkmcnt(0)
	v_lshlrev_b32_e32 v138, 2, v210
	v_mov_b32_e32 v139, v97
	v_lshl_add_u64 v[146:147], s[90:91], 0, v[138:139]
	v_readlane_b32 s30, v250, 42
	s_waitcnt lgkmcnt(4)
	v_mov_b64_e32 v[144:145], v[132:133]
	v_mov_b64_e32 v[140:141], v[136:137]
	s_add_i32 s24, s11, 0xfffff900
	s_mov_b64 s[28:29], 0x200
	s_waitcnt lgkmcnt(0)
	v_mov_b64_e32 v[148:149], v[206:207]
	v_readlane_b32 s31, v250, 43
	v_mov_b64_e32 v[142:143], v[130:131]
	v_mov_b64_e32 v[138:139], v[134:135]
	s_branch .LBB0_686

; #define LAS __attribute__((address_space(3)))
;     DI void operator()(f32x4 (&acc)[2][2][4][2], const Unit& u, int wr, int wc, int fr, int fq, LAS unsigned char* lds) const {
;     ...
;                     f32x4 v0 = acc[ai][bj][m][0] * rs, v1 = acc[ai][bj][m][1] * rs;
;                     if (gcol < 768 && gcol != 640) {
;                         if (rope_wave) {
;                             const float* rp = ROPE + (size_t)posidx * 16;
;                             const f32x4 cs0 = *(const f32x4*)rp, cs1 = *(const f32x4*)(rp + 4), sn0 = *(const f32x4*)(rp + 8), sn1 = *(const f32x4*)(rp + 12);
;                             f32x4 p0, p1;
; #pragma unroll
;                             for (int j = 0; j < 4; ++j) { p0[j] = __shfl_xor(v0[j], 16); p1[j] = __shfl_xor(v1[j], 16); }
;                             if (fq == 0) { v0 = v0 * cs0 - p0 * sn0; v1 = v1 * cs1 - p1 * sn1; }
;                             else if (fq == 1) { v0 = v0 * cs0 + p0 * sn0; v1 = v1 * cs1 + p1 * sn1; }
;                         }
;                     }
;                     bf16_t* dst; int ld, c0; float* of = nullptr; long orow = -1;
;                     if (gcol < 512) { dst = QA; ld = 512; c0 = gcol; v0 = v0 * QSCALE; v1 = v1 * QSCALE; }
;                     else if (gcol < 640) { dst = KA; ld = 128; c0 = gcol - 512; of = out + (prm ? O_KWP : O_KWS); orow = offA; }
;                     else if (gcol < 768) { dst = VA; ld = 128; c0 = gcol - 640; of = out + (prm ? O_VWP : O_VWS); orow = offA; }
;                     else if (gcol < 1280) { dst = QB; ld = 512; c0 = gcol - 768; v0 = v0 * QSCALE; v1 = v1 * QSCALE; }
;                     else if (gcol < 1792) { dst = KB; ld = 512; c0 = gcol - 1280; of = out + (prm ? O_KBP : O_KBS); orow = offB; }
;                     else if (gcol < 2304) { dst = VB; ld = 512; c0 = gcol - 1792; of = out + (prm ? O_VBP : O_VBS); orow = offB; }
;                     else { dst = GATES; ld = 2048; c0 = gcol - 2304;
;                         const f32x4 g0 = *(const LAS f32x4*)(lds + BG_OFF + (c0 + cw) * 4), g1 = *(const LAS f32x4*)(lds + BG_OFF + (c0 + cw + 4) * 4);
; #pragma unroll
;                         for (int j = 0; j < 4; ++j) { v0[j] = sigmoidf_(v0[j] + g0[j]); v1[j] = sigmoidf_(v1[j] + g1[j]); } }
;                     u32x4 w; w.x = pk2(v0[0], v0[1]); w.y = pk2(v0[2], v0[3]); w.z = pk2(v1[0], v1[1]); w.w = pk2(v1[2], v1[3]);
.LBB0_567:
	v_ashrrev_i32_e32 v167, 31, v196
	s_waitcnt lgkmcnt(5)
	v_mul_lo_u32 v136, v153, v196
	v_mul_lo_u32 v137, v152, v167
	v_mad_u64_u32 v[134:135], s[0:1], v152, v196, 0
	v_add3_u32 v135, v135, v137, v136
	s_waitcnt lgkmcnt(0)
	v_lshl_add_u64 v[134:135], v[134:135], 1, v[150:151]
	s_ashr_i32 s25, s24, 31
	v_lshl_add_u64 v[134:135], s[24:25], 1, v[134:135]
	v_cmp_ne_u64_e32 vcc, 0, v[146:147]
	v_cmp_lt_i64_e64 s[46:47], -1, v[148:149]
	v_cvt_pk_bf16_f32 v130, v138, v139
	v_cvt_pk_bf16_f32 v131, v140, v141
	s_waitcnt lgkmcnt(4)
	v_cvt_pk_bf16_f32 v132, v142, v143
	v_cvt_pk_bf16_f32 v133, v144, v145
	v_lshl_add_u64 v[134:135], v[134:135], 0, v[96:97]
	s_and_b64 s[0:1], vcc, s[46:47]
	global_store_dwordx4 v[134:135], v[130:133], off
	s_and_saveexec_b64 s[26:27], s[0:1]
	s_cbranch_execz .LBB0_569
	v_lshl_add_u64 v[130:131], v[148:149], 2, v[146:147]
	v_lshl_add_u64 v[130:131], s[24:25], 2, v[130:131]
	v_mov_b32_e32 v191, v97
	v_lshl_add_u64 v[130:131], v[130:131], 0, v[190:191]
	global_store_dwordx4 v[130:131], v[138:141], off
	global_store_dwordx4 v[130:131], v[142:145], off offset:16
.LBB0_569:
	s_or_b64 exec, exec, s[26:27]
	v_mov_b32_e32 v130, v194
	v_mov_b32_e32 v131, v194
	v_pk_mul_f32 v[136:137], v[14:15], v[130:131]
	v_pk_mul_f32 v[134:135], v[12:13], v[194:195]
	v_pk_mul_f32 v[132:133], v[10:11], v[130:131]
	s_and_b64 vcc, exec, s[40:41]
	v_pk_mul_f32 v[130:131], v[8:9], v[194:195]
	s_cbranch_vccnz .LBB0_577
	v_and_b32_e32 v139, 64, v229
	v_xor_b32_e32 v138, 16, v229
	v_add_u32_e32 v139, 64, v139
	v_cmp_lt_i32_e32 vcc, v138, v139
	s_nop 1
	v_cndmask_b32_e32 v138, v229, v138, vcc
	v_lshlrev_b32_e32 v138, 2, v138
	ds_bpermute_b32 v152, v138, v134
	ds_bpermute_b32 v142, v138, v130
	ds_bpermute_b32 v153, v138, v135
	ds_bpermute_b32 v143, v138, v131
	s_waitcnt lgkmcnt(6)
	ds_bpermute_b32 v214, v138, v136
	ds_bpermute_b32 v194, v138, v132
	s_waitcnt lgkmcnt(6)
	ds_bpermute_b32 v215, v138, v137
	ds_bpermute_b32 v195, v138, v133
	v_subrev_u32_e32 v148, s82, v212
	v_and_b32_e32 v148, 0x3fff, v148
	ds_read_b128 v[144:147], v148 offset:49200
	ds_read_b128 v[154:157], v148 offset:49184
	ds_read_b128 v[138:141], v148 offset:49168
	ds_read_b128 v[148:151], v148 offset:49152
	v_cmp_lt_i32_e32 vcc, 0, v169
	s_and_saveexec_b64 s[0:1], vcc
	s_xor_b64 s[24:25], exec, s[0:1]
	s_cbranch_execz .LBB0_574
	v_cmp_eq_u32_e32 vcc, 1, v169
	s_and_saveexec_b64 s[26:27], vcc
	s_cbranch_execz .LBB0_573
	s_waitcnt lgkmcnt(0)
	v_pk_mul_f32 v[156:157], v[156:157], v[214:215]
	v_pk_mul_f32 v[152:153], v[154:155], v[152:153]
	s_waitcnt lgkmcnt(0)
	v_pk_mul_f32 v[146:147], v[146:147], v[194:195]
	v_pk_mul_f32 v[142:143], v[144:145], v[142:143]
	s_waitcnt lgkmcnt(0)
	v_pk_fma_f32 v[136:137], v[136:137], v[150:151], v[156:157]
	v_pk_fma_f32 v[134:135], v[134:135], v[148:149], v[152:153]
	v_pk_fma_f32 v[132:133], v[132:133], v[140:141], v[146:147]
	v_pk_fma_f32 v[130:131], v[130:131], v[138:139], v[142:143]

;     DI void operator()(f32x4 (&acc)[2][2][4][2], const Unit& u, int wr, int wc, int fr, int fq, LAS unsigned char* lds) const {
;     ...
;                             if (fq == 0) { v0 = v0 * cs0 - p0 * sn0; v1 = v1 * cs1 - p1 * sn1; }
;                             else if (fq == 1) { v0 = v0 * cs0 + p0 * sn0; v1 = v1 * cs1 + p1 * sn1; }
;                         }
.LBB0_574:
	s_andn2_saveexec_b64 s[24:25], s[24:25]
	s_cbranch_execz .LBB0_576
	s_waitcnt lgkmcnt(0)
	v_pk_mul_f32 v[156:157], v[156:157], v[214:215]
	v_pk_mul_f32 v[152:153], v[154:155], v[152:153]
	s_waitcnt lgkmcnt(0)
	v_pk_mul_f32 v[146:147], v[146:147], v[194:195]
	v_pk_mul_f32 v[142:143], v[144:145], v[142:143]
	s_waitcnt lgkmcnt(0)
	v_pk_fma_f32 v[136:137], v[136:137], v[150:151], v[156:157] neg_lo:[0,0,1] neg_hi:[0,0,1]
	v_pk_fma_f32 v[134:135], v[134:135], v[148:149], v[152:153] neg_lo:[0,0,1] neg_hi:[0,0,1]
	v_pk_fma_f32 v[132:133], v[132:133], v[140:141], v[146:147] neg_lo:[0,0,1] neg_hi:[0,0,1]
	v_pk_fma_f32 v[130:131], v[130:131], v[138:139], v[142:143] neg_lo:[0,0,1] neg_hi:[0,0,1]

;     DI void operator()(f32x4 (&acc)[2][2][4][2], const Unit& u, int wr, int wc, int fr, int fq, LAS unsigned char* lds) const {
;     ...
;                     bf16_t* dst; int ld, c0; float* of = nullptr; long orow = -1;
;                     if (gcol < 512) { dst = QA; ld = 512; c0 = gcol; v0 = v0 * QSCALE; v1 = v1 * QSCALE; }
;                     else if (gcol < 640) { dst = KA; ld = 128; c0 = gcol - 512; of = out + (prm ? O_KWP : O_KWS); orow = offA; }
;                     else if (gcol < 768) { dst = VA; ld = 128; c0 = gcol - 640; of = out + (prm ? O_VWP : O_VWS); orow = offA; }
;                     else if (gcol < 1280) { dst = QB; ld = 512; c0 = gcol - 768; v0 = v0 * QSCALE; v1 = v1 * QSCALE; }
;                     else if (gcol < 1792) { dst = KB; ld = 512; c0 = gcol - 1280; of = out + (prm ? O_KBP : O_KBS); orow = offB; }
;                     else if (gcol < 2304) { dst = VB; ld = 512; c0 = gcol - 1792; of = out + (prm ? O_VBP : O_VBS); orow = offB; }
;                     else { dst = GATES; ld = 2048; c0 = gcol - 2304;
.LBB0_584:
	s_andn2_b64 vcc, exec, s[26:27]
	s_cbranch_vccnz .LBB0_763
	s_waitcnt lgkmcnt(0)
	v_lshlrev_b32_e32 v138, 2, v210
	v_mov_b32_e32 v139, v97
	v_lshl_add_u64 v[146:147], s[90:91], 0, v[138:139]
	v_readlane_b32 s30, v250, 42
	s_waitcnt lgkmcnt(4)
	v_mov_b64_e32 v[144:145], v[132:133]
	v_mov_b64_e32 v[140:141], v[136:137]
	s_add_i32 s24, s11, 0xfffff980
	s_mov_b64 s[28:29], 0x200
	s_waitcnt lgkmcnt(0)
	v_mov_b64_e32 v[148:149], v[206:207]
	v_readlane_b32 s31, v250, 43
	v_mov_b64_e32 v[142:143], v[130:131]
	v_mov_b64_e32 v[138:139], v[134:135]
	s_branch .LBB0_764

; DI unsigned pk2(float lo, float hi) { f32x2 v = {lo, hi}; hbf2 r = __builtin_convertvector(v, hbf2); return __builtin_bit_cast(unsigned, r); }
;     DI void operator()(f32x4 (&acc)[2][2][4][2], const Unit& u, int wr, int wc, int fr, int fq, LAS unsigned char* lds) const {
;     ...
;                     u32x4 w; w.x = pk2(v0[0], v0[1]); w.y = pk2(v0[2], v0[3]); w.z = pk2(v1[0], v1[1]); w.w = pk2(v1[2], v1[3]);
;                     *(u32x4*)(dst + (size_t)row * ld + c0 + cw) = w;
;                     if (of != nullptr && orow >= 0) { float* op = of + orow + c0 + cw; *(f32x4*)op = v0; *(f32x4*)(op + 4) = v1; }
.LBB0_588:
	s_waitcnt lgkmcnt(5)
	v_mul_lo_u32 v136, v153, v196
	v_mul_lo_u32 v137, v152, v167
	v_mad_u64_u32 v[134:135], s[0:1], v152, v196, 0
	v_add3_u32 v135, v135, v137, v136
	s_waitcnt lgkmcnt(0)
	v_lshl_add_u64 v[134:135], v[134:135], 1, v[150:151]
	s_ashr_i32 s25, s24, 31
	v_lshl_add_u64 v[134:135], s[24:25], 1, v[134:135]
	v_cmp_ne_u64_e32 vcc, 0, v[146:147]
	v_cmp_lt_i64_e64 s[46:47], -1, v[148:149]
	v_cvt_pk_bf16_f32 v130, v138, v139
	v_cvt_pk_bf16_f32 v131, v140, v141
	s_waitcnt lgkmcnt(4)
	v_cvt_pk_bf16_f32 v132, v142, v143
	v_cvt_pk_bf16_f32 v133, v144, v145
	v_lshl_add_u64 v[134:135], v[134:135], 0, v[96:97]
	s_and_b64 s[0:1], vcc, s[46:47]
	global_store_dwordx4 v[134:135], v[130:133], off
	s_and_saveexec_b64 s[26:27], s[0:1]
	s_cbranch_execz .LBB0_590
	v_lshl_add_u64 v[130:131], v[148:149], 2, v[146:147]
	v_lshl_add_u64 v[130:131], s[24:25], 2, v[130:131]
	v_mov_b32_e32 v191, v97
	v_lshl_add_u64 v[130:131], v[130:131], 0, v[190:191]
	global_store_dwordx4 v[130:131], v[138:141], off
	global_store_dwordx4 v[130:131], v[142:145], off offset:16

;     DI void operator()(f32x4 (&acc)[2][2][4][2], const Unit& u, int wr, int wc, int fr, int fq, LAS unsigned char* lds) const {
;     ...
;                     f32x4 v0 = acc[ai][bj][m][0] * rs, v1 = acc[ai][bj][m][1] * rs;
;                     if (gcol < 768 && gcol != 640) {
;                         if (rope_wave) {
;                             const float* rp = ROPE + (size_t)posidx * 16;
;                             const f32x4 cs0 = *(const f32x4*)rp, cs1 = *(const f32x4*)(rp + 4), sn0 = *(const f32x4*)(rp + 8), sn1 = *(const f32x4*)(rp + 12);
;                             f32x4 p0, p1;
; #pragma unroll
;                             for (int j = 0; j < 4; ++j) { p0[j] = __shfl_xor(v0[j], 16); p1[j] = __shfl_xor(v1[j], 16); }
;                             if (fq == 0) { v0 = v0 * cs0 - p0 * sn0; v1 = v1 * cs1 - p1 * sn1; }
;                             else if (fq == 1) { v0 = v0 * cs0 + p0 * sn0; v1 = v1 * cs1 + p1 * sn1; }
;                         }
.LBB0_598:
	s_or_b64 exec, exec, s[24:25]
	v_lshlrev_b32_e32 v130, 6, v132
	v_mov_b32_e32 v131, v97
	v_lshl_add_u64 v[206:207], s[82:83], 0, v[130:131]
	v_pk_mul_f32 v[136:137], v[38:39], v[188:189] op_sel_hi:[1,0]
	v_pk_mul_f32 v[134:135], v[36:37], v[188:189] op_sel_hi:[1,0]
	v_pk_mul_f32 v[132:133], v[34:35], v[188:189] op_sel_hi:[1,0]
	s_and_b64 vcc, exec, s[38:39]
	v_pk_mul_f32 v[130:131], v[32:33], v[188:189] op_sel_hi:[1,0]
	s_cbranch_vccnz .LBB0_606
	v_and_b32_e32 v139, 64, v229
	v_xor_b32_e32 v138, 16, v229
	v_add_u32_e32 v139, 64, v139
	v_cmp_lt_i32_e32 vcc, v138, v139
	s_nop 1
	v_cndmask_b32_e32 v138, v229, v138, vcc
	v_lshlrev_b32_e32 v138, 2, v138
	ds_bpermute_b32 v152, v138, v134
	ds_bpermute_b32 v142, v138, v130
	ds_bpermute_b32 v153, v138, v135
	ds_bpermute_b32 v143, v138, v131
	ds_bpermute_b32 v210, v138, v136
	ds_bpermute_b32 v208, v138, v132
	ds_bpermute_b32 v211, v138, v137
	ds_bpermute_b32 v209, v138, v133
	v_subrev_u32_e32 v148, s82, v206
	v_and_b32_e32 v148, 0x3fff, v148
	ds_read_b128 v[144:147], v148 offset:49200
	ds_read_b128 v[154:157], v148 offset:49184
	ds_read_b128 v[138:141], v148 offset:49168
	ds_read_b128 v[148:151], v148 offset:49152
	v_cmp_lt_i32_e32 vcc, 0, v169
	s_and_saveexec_b64 s[0:1], vcc
	s_xor_b64 s[24:25], exec, s[0:1]
	s_cbranch_execz .LBB0_603
	v_cmp_eq_u32_e32 vcc, 1, v169
	s_and_saveexec_b64 s[26:27], vcc
	s_cbranch_execz .LBB0_602
	s_waitcnt lgkmcnt(0)
	v_pk_mul_f32 v[156:157], v[156:157], v[210:211]
	v_pk_mul_f32 v[152:153], v[154:155], v[152:153]
	s_waitcnt lgkmcnt(0)
	v_pk_mul_f32 v[146:147], v[146:147], v[208:209]
	v_pk_mul_f32 v[142:143], v[144:145], v[142:143]
	s_waitcnt lgkmcnt(0)
	v_pk_fma_f32 v[136:137], v[136:137], v[150:151], v[156:157]
	v_pk_fma_f32 v[134:135], v[134:135], v[148:149], v[152:153]
	v_pk_fma_f32 v[132:133], v[132:133], v[140:141], v[146:147]
	v_pk_fma_f32 v[130:131], v[130:131], v[138:139], v[142:143]

;     DI void operator()(f32x4 (&acc)[2][2][4][2], const Unit& u, int wr, int wc, int fr, int fq, LAS unsigned char* lds) const {
;     ...
;                             if (fq == 0) { v0 = v0 * cs0 - p0 * sn0; v1 = v1 * cs1 - p1 * sn1; }
;                             else if (fq == 1) { v0 = v0 * cs0 + p0 * sn0; v1 = v1 * cs1 + p1 * sn1; }
;                         }
.LBB0_603:
	s_andn2_saveexec_b64 s[24:25], s[24:25]
	s_cbranch_execz .LBB0_605
	s_waitcnt lgkmcnt(0)
	v_pk_mul_f32 v[156:157], v[156:157], v[210:211]
	v_pk_mul_f32 v[152:153], v[154:155], v[152:153]
	s_waitcnt lgkmcnt(0)
	v_pk_mul_f32 v[146:147], v[146:147], v[208:209]
	v_pk_mul_f32 v[142:143], v[144:145], v[142:143]
	s_waitcnt lgkmcnt(0)
	v_pk_fma_f32 v[136:137], v[136:137], v[150:151], v[156:157] neg_lo:[0,0,1] neg_hi:[0,0,1]
	v_pk_fma_f32 v[134:135], v[134:135], v[148:149], v[152:153] neg_lo:[0,0,1] neg_hi:[0,0,1]
	v_pk_fma_f32 v[132:133], v[132:133], v[140:141], v[146:147] neg_lo:[0,0,1] neg_hi:[0,0,1]
	v_pk_fma_f32 v[130:131], v[130:131], v[138:139], v[142:143] neg_lo:[0,0,1] neg_hi:[0,0,1]

; #define LAS __attribute__((address_space(3)))
; DI float sigmoidf_(float a) { return fast_rcp(1.0f + fast_exp2(-a * LOG2E)); }
;     DI void operator()(f32x4 (&acc)[2][2][4][2], const Unit& u, int wr, int wc, int fr, int fq, LAS unsigned char* lds) const {
;     ...
;                     if (gcol < 512) { dst = QA; ld = 512; c0 = gcol; v0 = v0 * QSCALE; v1 = v1 * QSCALE; }
;                     else if (gcol < 640) { dst = KA; ld = 128; c0 = gcol - 512; of = out + (prm ? O_KWP : O_KWS); orow = offA; }
;                     else if (gcol < 768) { dst = VA; ld = 128; c0 = gcol - 640; of = out + (prm ? O_VWP : O_VWS); orow = offA; }
;                     else if (gcol < 1280) { dst = QB; ld = 512; c0 = gcol - 768; v0 = v0 * QSCALE; v1 = v1 * QSCALE; }
;                     else if (gcol < 1792) { dst = KB; ld = 512; c0 = gcol - 1280; of = out + (prm ? O_KBP : O_KBS); orow = offB; }
;                     else if (gcol < 2304) { dst = VB; ld = 512; c0 = gcol - 1792; of = out + (prm ? O_VBP : O_VBS); orow = offB; }
;                     else { dst = GATES; ld = 2048; c0 = gcol - 2304;
;                         const f32x4 g0 = *(const LAS f32x4*)(lds + BG_OFF + (c0 + cw) * 4), g1 = *(const LAS f32x4*)(lds + BG_OFF + (c0 + cw + 4) * 4);
; #pragma unroll
;                         for (int j = 0; j < 4; ++j) { v0[j] = sigmoidf_(v0[j] + g0[j]); v1[j] = sigmoidf_(v1[j] + g1[j]); } }
.LBB0_606:
	v_mov_b32_e32 v189, v188
	s_and_b64 vcc, exec, s[42:43]
	s_mov_b64 s[26:27], -1
	s_cbranch_vccnz .LBB0_614
	s_cmpk_lt_u32 s11, 0x280
	s_cbranch_scc1 .LBB0_704
	s_cmpk_lt_u32 s11, 0x500
	s_cbranch_scc1 .LBB0_701
	s_cmpk_lt_u32 s11, 0x700
	s_cbranch_scc1 .LBB0_698
	s_cmpk_lt_u32 s11, 0x900
	s_cbranch_scc1 .LBB0_612
	s_add_i32 s24, s11, 0xfffff700
	s_waitcnt lgkmcnt(0)
	v_or_b32_e32 v138, s24, v166
	v_lshl_add_u32 v138, v138, 2, 0
	s_waitcnt lgkmcnt(6)
	v_add_u32_e32 v142, 0x23040, v138
	ds_read_b128 v[138:141], v142
	s_waitcnt lgkmcnt(5)
	ds_read_b128 v[142:145], v142 offset:16
	s_mov_b64 s[26:27], 0
	s_waitcnt lgkmcnt(1)
	v_add_f32_e32 v138, v134, v138
	s_waitcnt lgkmcnt(0)
	v_add_f32_e32 v142, v130, v142
	v_add_f32_e32 v139, v135, v139
	v_add_f32_e32 v143, v131, v143
	v_add_f32_e32 v140, v136, v140
	v_add_f32_e32 v144, v132, v144
	v_add_f32_e32 v141, v137, v141
	v_add_f32_e32 v145, v133, v145
	v_mul_f32_e32 v138, 0xbfb8aa3b, v138
	v_mul_f32_e32 v142, 0xbfb8aa3b, v142
	v_mul_f32_e32 v139, 0xbfb8aa3b, v139
	v_mul_f32_e32 v143, 0xbfb8aa3b, v143
	v_mul_f32_e32 v140, 0xbfb8aa3b, v140
	v_mul_f32_e32 v144, 0xbfb8aa3b, v144
	v_mul_f32_e32 v141, 0xbfb8aa3b, v141
	v_mul_f32_e32 v145, 0xbfb8aa3b, v145
	v_exp_f32_e32 v138, v138
	v_exp_f32_e32 v142, v142
	v_exp_f32_e32 v139, v139
	v_exp_f32_e32 v143, v143
	v_exp_f32_e32 v140, v140
	v_exp_f32_e32 v144, v144
	v_exp_f32_e32 v141, v141
	v_exp_f32_e32 v145, v145
	v_add_f32_e32 v138, 1.0, v138
	v_add_f32_e32 v142, 1.0, v142
	v_add_f32_e32 v139, 1.0, v139
	v_add_f32_e32 v143, 1.0, v143
	v_add_f32_e32 v140, 1.0, v140
	v_add_f32_e32 v144, 1.0, v144
	v_add_f32_e32 v141, 1.0, v141
	v_add_f32_e32 v145, 1.0, v145
	v_rcp_f32_e32 v138, v138
	v_rcp_f32_e32 v142, v142
	v_rcp_f32_e32 v139, v139
	v_rcp_f32_e32 v143, v143
	v_rcp_f32_e32 v140, v140
	v_rcp_f32_e32 v144, v144
	v_rcp_f32_e32 v141, v141
	v_rcp_f32_e32 v145, v145
.LBB0_612:
	s_andn2_b64 vcc, exec, s[26:27]
	s_cbranch_vccnz .LBB0_696
	s_waitcnt lgkmcnt(0)
	v_lshlrev_b32_e32 v138, 2, v204
	v_mov_b32_e32 v139, v97
	v_lshl_add_u64 v[146:147], s[90:91], 0, v[138:139]
	v_readlane_b32 s30, v250, 42
	s_waitcnt lgkmcnt(4)
	v_mov_b64_e32 v[144:145], v[132:133]
	v_mov_b64_e32 v[140:141], v[136:137]
	s_add_i32 s24, s11, 0xfffff900
	s_mov_b64 s[28:29], 0x200
	s_waitcnt lgkmcnt(0)
	v_mov_b64_e32 v[148:149], v[202:203]
	v_readlane_b32 s31, v250, 43
	v_mov_b64_e32 v[142:143], v[130:131]
	v_mov_b64_e32 v[138:139], v[134:135]
	s_branch .LBB0_697

; #define LAS __attribute__((address_space(3)))
;     DI void operator()(f32x4 (&acc)[2][2][4][2], const Unit& u, int wr, int wc, int fr, int fq, LAS unsigned char* lds) const {
;     ...
;                     f32x4 v0 = acc[ai][bj][m][0] * rs, v1 = acc[ai][bj][m][1] * rs;
;                     if (gcol < 768 && gcol != 640) {
;                         if (rope_wave) {
;                             const float* rp = ROPE + (size_t)posidx * 16;
;                             const f32x4 cs0 = *(const f32x4*)rp, cs1 = *(const f32x4*)(rp + 4), sn0 = *(const f32x4*)(rp + 8), sn1 = *(const f32x4*)(rp + 12);
;                             f32x4 p0, p1;
; #pragma unroll
;                             for (int j = 0; j < 4; ++j) { p0[j] = __shfl_xor(v0[j], 16); p1[j] = __shfl_xor(v1[j], 16); }
;                             if (fq == 0) { v0 = v0 * cs0 - p0 * sn0; v1 = v1 * cs1 - p1 * sn1; }
;                             else if (fq == 1) { v0 = v0 * cs0 + p0 * sn0; v1 = v1 * cs1 + p1 * sn1; }
;                         }
;                     }
;                     bf16_t* dst; int ld, c0; float* of = nullptr; long orow = -1;
;                     if (gcol < 512) { dst = QA; ld = 512; c0 = gcol; v0 = v0 * QSCALE; v1 = v1 * QSCALE; }
;                     else if (gcol < 640) { dst = KA; ld = 128; c0 = gcol - 512; of = out + (prm ? O_KWP : O_KWS); orow = offA; }
;                     else if (gcol < 768) { dst = VA; ld = 128; c0 = gcol - 640; of = out + (prm ? O_VWP : O_VWS); orow = offA; }
;                     else if (gcol < 1280) { dst = QB; ld = 512; c0 = gcol - 768; v0 = v0 * QSCALE; v1 = v1 * QSCALE; }
;                     else if (gcol < 1792) { dst = KB; ld = 512; c0 = gcol - 1280; of = out + (prm ? O_KBP : O_KBS); orow = offB; }
;                     else if (gcol < 2304) { dst = VB; ld = 512; c0 = gcol - 1792; of = out + (prm ? O_VBP : O_VBS); orow = offB; }
;                     else { dst = GATES; ld = 2048; c0 = gcol - 2304;
;                         const f32x4 g0 = *(const LAS f32x4*)(lds + BG_OFF + (c0 + cw) * 4), g1 = *(const LAS f32x4*)(lds + BG_OFF + (c0 + cw + 4) * 4);
; #pragma unroll
;                         for (int j = 0; j < 4; ++j) { v0[j] = sigmoidf_(v0[j] + g0[j]); v1[j] = sigmoidf_(v1[j] + g1[j]); } }
;                     u32x4 w; w.x = pk2(v0[0], v0[1]); w.y = pk2(v0[2], v0[3]); w.z = pk2(v1[0], v1[1]); w.w = pk2(v1[2], v1[3]);
.LBB0_616:
	v_ashrrev_i32_e32 v167, 31, v192
	s_waitcnt lgkmcnt(5)
	v_mul_lo_u32 v136, v153, v192
	v_mul_lo_u32 v137, v152, v167
	v_mad_u64_u32 v[134:135], s[0:1], v152, v192, 0
	v_add3_u32 v135, v135, v137, v136
	s_waitcnt lgkmcnt(0)
	v_lshl_add_u64 v[134:135], v[134:135], 1, v[150:151]
	s_ashr_i32 s25, s24, 31
	v_lshl_add_u64 v[134:135], s[24:25], 1, v[134:135]
	v_cmp_ne_u64_e32 vcc, 0, v[146:147]
	v_cmp_lt_i64_e64 s[38:39], -1, v[148:149]
	v_cvt_pk_bf16_f32 v130, v138, v139
	v_cvt_pk_bf16_f32 v131, v140, v141
	s_waitcnt lgkmcnt(4)
	v_cvt_pk_bf16_f32 v132, v142, v143
	v_cvt_pk_bf16_f32 v133, v144, v145
	v_lshl_add_u64 v[134:135], v[134:135], 0, v[96:97]
	s_and_b64 s[0:1], vcc, s[38:39]
	global_store_dwordx4 v[134:135], v[130:133], off
	s_and_saveexec_b64 s[26:27], s[0:1]
	s_cbranch_execz .LBB0_618
	v_lshl_add_u64 v[130:131], v[148:149], 2, v[146:147]
	v_lshl_add_u64 v[130:131], s[24:25], 2, v[130:131]
	v_mov_b32_e32 v191, v97
	v_lshl_add_u64 v[130:131], v[130:131], 0, v[190:191]
	global_store_dwordx4 v[130:131], v[138:141], off
	global_store_dwordx4 v[130:131], v[142:145], off offset:16
.LBB0_618:
	s_or_b64 exec, exec, s[26:27]
	v_mov_b32_e32 v130, v188
	v_mov_b32_e32 v131, v188
	v_pk_mul_f32 v[136:137], v[6:7], v[130:131]
	v_pk_mul_f32 v[134:135], v[4:5], v[188:189]
	v_pk_mul_f32 v[132:133], v[2:3], v[130:131]
	s_and_b64 vcc, exec, s[40:41]
	v_pk_mul_f32 v[130:131], v[0:1], v[188:189]
	s_cbranch_vccnz .LBB0_626
	v_and_b32_e32 v139, 64, v229
	v_xor_b32_e32 v138, 16, v229
	v_add_u32_e32 v139, 64, v139
	v_cmp_lt_i32_e32 vcc, v138, v139
	s_nop 1
	v_cndmask_b32_e32 v138, v229, v138, vcc
	v_lshlrev_b32_e32 v138, 2, v138
	ds_bpermute_b32 v152, v138, v134
	ds_bpermute_b32 v142, v138, v130
	ds_bpermute_b32 v153, v138, v135
	ds_bpermute_b32 v143, v138, v131
	s_waitcnt lgkmcnt(6)
	ds_bpermute_b32 v208, v138, v136
	ds_bpermute_b32 v188, v138, v132
	s_waitcnt lgkmcnt(6)
	ds_bpermute_b32 v209, v138, v137
	ds_bpermute_b32 v189, v138, v133
	v_subrev_u32_e32 v148, s82, v206
	v_and_b32_e32 v148, 0x3fff, v148
	ds_read_b128 v[144:147], v148 offset:49200
	ds_read_b128 v[154:157], v148 offset:49184
	ds_read_b128 v[138:141], v148 offset:49168
	ds_read_b128 v[148:151], v148 offset:49152
	v_cmp_lt_i32_e32 vcc, 0, v169
	s_and_saveexec_b64 s[0:1], vcc
	s_xor_b64 s[24:25], exec, s[0:1]
	s_cbranch_execz .LBB0_623
	v_cmp_eq_u32_e32 vcc, 1, v169
	s_and_saveexec_b64 s[26:27], vcc
	s_cbranch_execz .LBB0_622
	s_waitcnt lgkmcnt(0)
	v_pk_mul_f32 v[156:157], v[156:157], v[208:209]
	v_pk_mul_f32 v[152:153], v[154:155], v[152:153]
	s_waitcnt lgkmcnt(0)
	v_pk_mul_f32 v[146:147], v[146:147], v[188:189]
	v_pk_mul_f32 v[142:143], v[144:145], v[142:143]
	s_waitcnt lgkmcnt(0)
	v_pk_fma_f32 v[136:137], v[136:137], v[150:151], v[156:157]
	v_pk_fma_f32 v[134:135], v[134:135], v[148:149], v[152:153]
	v_pk_fma_f32 v[132:133], v[132:133], v[140:141], v[146:147]
	v_pk_fma_f32 v[130:131], v[130:131], v[138:139], v[142:143]

;     DI void operator()(f32x4 (&acc)[2][2][4][2], const Unit& u, int wr, int wc, int fr, int fq, LAS unsigned char* lds) const {
;     ...
;                             if (fq == 0) { v0 = v0 * cs0 - p0 * sn0; v1 = v1 * cs1 - p1 * sn1; }
;                             else if (fq == 1) { v0 = v0 * cs0 + p0 * sn0; v1 = v1 * cs1 + p1 * sn1; }
;                         }
.LBB0_623:
	s_andn2_saveexec_b64 s[24:25], s[24:25]
	s_cbranch_execz .LBB0_625
	s_waitcnt lgkmcnt(0)
	v_pk_mul_f32 v[156:157], v[156:157], v[208:209]
	v_pk_mul_f32 v[152:153], v[154:155], v[152:153]
	s_waitcnt lgkmcnt(0)
	v_pk_mul_f32 v[146:147], v[146:147], v[188:189]
	v_pk_mul_f32 v[142:143], v[144:145], v[142:143]
	s_waitcnt lgkmcnt(0)
	v_pk_fma_f32 v[136:137], v[136:137], v[150:151], v[156:157] neg_lo:[0,0,1] neg_hi:[0,0,1]
	v_pk_fma_f32 v[134:135], v[134:135], v[148:149], v[152:153] neg_lo:[0,0,1] neg_hi:[0,0,1]
	v_pk_fma_f32 v[132:133], v[132:133], v[140:141], v[146:147] neg_lo:[0,0,1] neg_hi:[0,0,1]
	v_pk_fma_f32 v[130:131], v[130:131], v[138:139], v[142:143] neg_lo:[0,0,1] neg_hi:[0,0,1]

; #define LAS __attribute__((address_space(3)))
; DI float sigmoidf_(float a) { return fast_rcp(1.0f + fast_exp2(-a * LOG2E)); }
;     DI void operator()(f32x4 (&acc)[2][2][4][2], const Unit& u, int wr, int wc, int fr, int fq, LAS unsigned char* lds) const {
;     ...
;                     if (gcol < 512) { dst = QA; ld = 512; c0 = gcol; v0 = v0 * QSCALE; v1 = v1 * QSCALE; }
;                     else if (gcol < 640) { dst = KA; ld = 128; c0 = gcol - 512; of = out + (prm ? O_KWP : O_KWS); orow = offA; }
;                     else if (gcol < 768) { dst = VA; ld = 128; c0 = gcol - 640; of = out + (prm ? O_VWP : O_VWS); orow = offA; }
;                     else if (gcol < 1280) { dst = QB; ld = 512; c0 = gcol - 768; v0 = v0 * QSCALE; v1 = v1 * QSCALE; }
;                     else if (gcol < 1792) { dst = KB; ld = 512; c0 = gcol - 1280; of = out + (prm ? O_KBP : O_KBS); orow = offB; }
;                     else if (gcol < 2304) { dst = VB; ld = 512; c0 = gcol - 1792; of = out + (prm ? O_VBP : O_VBS); orow = offB; }
;                     else { dst = GATES; ld = 2048; c0 = gcol - 2304;
;                         const f32x4 g0 = *(const LAS f32x4*)(lds + BG_OFF + (c0 + cw) * 4), g1 = *(const LAS f32x4*)(lds + BG_OFF + (c0 + cw + 4) * 4);
; #pragma unroll
;                         for (int j = 0; j < 4; ++j) { v0[j] = sigmoidf_(v0[j] + g0[j]); v1[j] = sigmoidf_(v1[j] + g1[j]); } }
.LBB0_626:
	s_and_b64 vcc, exec, s[44:45]
	s_mov_b64 s[26:27], -1
	s_cbranch_vccnz .LBB0_635
	s_cmpk_lt_u32 s13, 0x280
	s_cbranch_scc1 .LBB0_788
	s_andn2_b64 vcc, exec, s[22:23]
	s_mov_b64 s[22:23], -1
	s_cbranch_vccnz .LBB0_785
	s_cmpk_lt_u32 s11, 0x500
	s_cbranch_scc1 .LBB0_782
	s_cmpk_lt_u32 s11, 0x700
	s_cbranch_scc1 .LBB0_779
	s_cmpk_lt_u32 s11, 0x900
	s_cbranch_scc1 .LBB0_633
	s_add_i32 s24, s11, 0xfffff780
	s_waitcnt lgkmcnt(0)
	v_or_b32_e32 v138, s24, v166
	v_lshl_add_u32 v138, v138, 2, 0
	s_waitcnt lgkmcnt(6)
	v_add_u32_e32 v142, 0x23040, v138
	ds_read_b128 v[138:141], v142
	s_waitcnt lgkmcnt(5)
	ds_read_b128 v[142:145], v142 offset:16
	s_mov_b64 s[22:23], 0
	s_waitcnt lgkmcnt(1)
	v_add_f32_e32 v138, v134, v138
	s_waitcnt lgkmcnt(0)
	v_add_f32_e32 v142, v130, v142
	v_add_f32_e32 v139, v135, v139
	v_add_f32_e32 v143, v131, v143
	v_add_f32_e32 v140, v136, v140
	v_add_f32_e32 v144, v132, v144
	v_add_f32_e32 v141, v137, v141
	v_add_f32_e32 v145, v133, v145
	v_mul_f32_e32 v138, 0xbfb8aa3b, v138
	v_mul_f32_e32 v142, 0xbfb8aa3b, v142
	v_mul_f32_e32 v139, 0xbfb8aa3b, v139
	v_mul_f32_e32 v143, 0xbfb8aa3b, v143
	v_mul_f32_e32 v140, 0xbfb8aa3b, v140
	v_mul_f32_e32 v144, 0xbfb8aa3b, v144
	v_mul_f32_e32 v141, 0xbfb8aa3b, v141
	v_mul_f32_e32 v145, 0xbfb8aa3b, v145
	v_exp_f32_e32 v138, v138
	v_exp_f32_e32 v142, v142
	v_exp_f32_e32 v139, v139
	v_exp_f32_e32 v143, v143
	v_exp_f32_e32 v140, v140
	v_exp_f32_e32 v144, v144
	v_exp_f32_e32 v141, v141
	v_exp_f32_e32 v145, v145
	v_add_f32_e32 v138, 1.0, v138
	v_add_f32_e32 v142, 1.0, v142
	v_add_f32_e32 v139, 1.0, v139
	v_add_f32_e32 v143, 1.0, v143
	v_add_f32_e32 v140, 1.0, v140
	v_add_f32_e32 v144, 1.0, v144
	v_add_f32_e32 v141, 1.0, v141
	v_add_f32_e32 v145, 1.0, v145
	v_rcp_f32_e32 v138, v138
	v_rcp_f32_e32 v142, v142
	v_rcp_f32_e32 v139, v139
	v_rcp_f32_e32 v143, v143
	v_rcp_f32_e32 v140, v140
	v_rcp_f32_e32 v144, v144
	v_rcp_f32_e32 v141, v141
	v_rcp_f32_e32 v145, v145
.LBB0_633:
	s_andn2_b64 vcc, exec, s[22:23]
	s_cbranch_vccnz .LBB0_777
	s_waitcnt lgkmcnt(0)
	v_lshlrev_b32_e32 v138, 2, v204
	v_mov_b32_e32 v139, v97
	v_lshl_add_u64 v[146:147], s[90:91], 0, v[138:139]
	v_readlane_b32 s28, v250, 42
	s_waitcnt lgkmcnt(4)
	v_mov_b64_e32 v[144:145], v[132:133]
	v_mov_b64_e32 v[140:141], v[136:137]
	s_add_i32 s24, s11, 0xfffff980
	s_mov_b64 s[26:27], 0x200
	s_waitcnt lgkmcnt(0)
	v_mov_b64_e32 v[148:149], v[202:203]
	v_readlane_b32 s29, v250, 43
	v_mov_b64_e32 v[142:143], v[130:131]
	v_mov_b64_e32 v[138:139], v[134:135]
	s_branch .LBB0_778

; DI unsigned pk2(float lo, float hi) { f32x2 v = {lo, hi}; hbf2 r = __builtin_convertvector(v, hbf2); return __builtin_bit_cast(unsigned, r); }
;     DI void operator()(f32x4 (&acc)[2][2][4][2], const Unit& u, int wr, int wc, int fr, int fq, LAS unsigned char* lds) const {
;     ...
;                     u32x4 w; w.x = pk2(v0[0], v0[1]); w.y = pk2(v0[2], v0[3]); w.z = pk2(v1[0], v1[1]); w.w = pk2(v1[2], v1[3]);
;                     *(u32x4*)(dst + (size_t)row * ld + c0 + cw) = w;
;                     if (of != nullptr && orow >= 0) { float* op = of + orow + c0 + cw; *(f32x4*)op = v0; *(f32x4*)(op + 4) = v1; }
.LBB0_637:
	s_waitcnt lgkmcnt(5)
	v_mul_lo_u32 v136, v153, v192
	v_mul_lo_u32 v137, v152, v167
	v_mad_u64_u32 v[134:135], s[0:1], v152, v192, 0
	v_add3_u32 v135, v135, v137, v136
	s_waitcnt lgkmcnt(0)
	v_lshl_add_u64 v[134:135], v[134:135], 1, v[150:151]
	s_ashr_i32 s25, s24, 31
	v_lshl_add_u64 v[134:135], s[24:25], 1, v[134:135]
	v_cmp_ne_u64_e32 vcc, 0, v[146:147]
	v_cmp_lt_i64_e64 s[38:39], -1, v[148:149]
	v_cvt_pk_bf16_f32 v130, v138, v139
	v_cvt_pk_bf16_f32 v131, v140, v141
	s_waitcnt lgkmcnt(4)
	v_cvt_pk_bf16_f32 v132, v142, v143
	v_cvt_pk_bf16_f32 v133, v144, v145
	v_lshl_add_u64 v[134:135], v[134:135], 0, v[96:97]
	s_and_b64 s[0:1], vcc, s[38:39]
	global_store_dwordx4 v[134:135], v[130:133], off
	s_and_saveexec_b64 s[22:23], s[0:1]
	s_cbranch_execz .LBB0_639
	v_lshl_add_u64 v[130:131], v[148:149], 2, v[146:147]
	v_lshl_add_u64 v[130:131], s[24:25], 2, v[130:131]
	v_mov_b32_e32 v191, v97
	v_lshl_add_u64 v[130:131], v[130:131], 0, v[190:191]
	global_store_dwordx4 v[130:131], v[138:141], off
	global_store_dwordx4 v[130:131], v[142:145], off offset:16
.LBB0_639:
	s_cmp_lt_i32 s97, 3
	s_cbranch_scc0 .Lrope_post_skip
	s_waitcnt lgkmcnt(0)
	s_barrier
	s_barrier

;     DI void operator()(f32x4 (&acc)[2][2][4][2], const Unit& u, int wr, int wc, int fr, int fq, LAS unsigned char* lds) const {
;     ...
;                     bf16_t* dst; int ld, c0; float* of = nullptr; long orow = -1;
;                     if (gcol < 512) { dst = QA; ld = 512; c0 = gcol; v0 = v0 * QSCALE; v1 = v1 * QSCALE; }
;                     else if (gcol < 640) { dst = KA; ld = 128; c0 = gcol - 512; of = out + (prm ? O_KWP : O_KWS); orow = offA; }
;                     else if (gcol < 768) { dst = VA; ld = 128; c0 = gcol - 640; of = out + (prm ? O_VWP : O_VWS); orow = offA; }
;                     else if (gcol < 1280) { dst = QB; ld = 512; c0 = gcol - 768; v0 = v0 * QSCALE; v1 = v1 * QSCALE; }
;                     else if (gcol < 1792) { dst = KB; ld = 512; c0 = gcol - 1280; of = out + (prm ? O_KBP : O_KBS); orow = offB; }
;                     else if (gcol < 2304) { dst = VB; ld = 512; c0 = gcol - 1792; of = out + (prm ? O_VBP : O_VBS); orow = offB; }
;                     else { dst = GATES; ld = 2048; c0 = gcol - 2304;
.LBB0_643:
	s_andn2_b64 vcc, exec, s[26:27]
	s_cbranch_vccnz .LBB0_645
	s_waitcnt lgkmcnt(0)
	v_lshlrev_b32_e32 v138, 2, v216
	v_mov_b32_e32 v139, v97
	v_readlane_b32 s0, v250, 46
	v_lshl_add_u64 v[146:147], s[90:91], 0, v[138:139]
	v_readlane_b32 s1, v250, 47
	s_waitcnt lgkmcnt(4)
	v_mov_b64_e32 v[144:145], v[132:133]
	v_mov_b64_e32 v[140:141], v[136:137]
	s_add_i32 s24, s11, 0xfffffb00
	s_waitcnt lgkmcnt(0)
	v_mov_b64_e32 v[150:151], s[0:1]
	v_mov_b64_e32 v[152:153], 0x200
	v_mov_b64_e32 v[148:149], v[214:215]
	v_mov_b64_e32 v[142:143], v[130:131]
	v_mov_b64_e32 v[138:139], v[134:135]

;     DI void operator()(f32x4 (&acc)[2][2][4][2], const Unit& u, int wr, int wc, int fr, int fq, LAS unsigned char* lds) const {
;     ...
;                     if (gcol < 512) { dst = QA; ld = 512; c0 = gcol; v0 = v0 * QSCALE; v1 = v1 * QSCALE; }
;                     else if (gcol < 640) { dst = KA; ld = 128; c0 = gcol - 512; of = out + (prm ? O_KWP : O_KWS); orow = offA; }
;                     else if (gcol < 768) { dst = VA; ld = 128; c0 = gcol - 640; of = out + (prm ? O_VWP : O_VWS); orow = offA; }
;                     else if (gcol < 1280) { dst = QB; ld = 512; c0 = gcol - 768; v0 = v0 * QSCALE; v1 = v1 * QSCALE; }
.LBB0_646:
	s_andn2_b64 vcc, exec, s[26:27]
	s_cbranch_vccnz .LBB0_648
	v_readlane_b32 s0, v250, 44
	v_readlane_b32 s1, v250, 45
	s_add_i32 s24, s11, 0xfffffd00
	s_waitcnt lgkmcnt(0)
	v_pk_mul_f32 v[140:141], v[136:137], s[66:67] op_sel_hi:[1,0]
	v_pk_mul_f32 v[138:139], v[134:135], s[66:67] op_sel_hi:[1,0]
	v_pk_mul_f32 v[144:145], v[132:133], s[66:67] op_sel_hi:[1,0]
	s_waitcnt lgkmcnt(4)
	v_pk_mul_f32 v[142:143], v[130:131], s[66:67] op_sel_hi:[1,0]
	v_mov_b64_e32 v[146:147], 0
	s_waitcnt lgkmcnt(0)
	v_mov_b64_e32 v[148:149], -1
	v_mov_b64_e32 v[150:151], s[0:1]
	v_mov_b64_e32 v[152:153], 0x200

;     DI void operator()(f32x4 (&acc)[2][2][4][2], const Unit& u, int wr, int wc, int fr, int fq, LAS unsigned char* lds) const {
;     ...
;                     bf16_t* dst; int ld, c0; float* of = nullptr; long orow = -1;
;                     if (gcol < 512) { dst = QA; ld = 512; c0 = gcol; v0 = v0 * QSCALE; v1 = v1 * QSCALE; }
;                     else if (gcol < 640) { dst = KA; ld = 128; c0 = gcol - 512; of = out + (prm ? O_KWP : O_KWS); orow = offA; }
;                     else if (gcol < 768) { dst = VA; ld = 128; c0 = gcol - 640; of = out + (prm ? O_VWP : O_VWS); orow = offA; }
.LBB0_649:
	s_andn2_b64 vcc, exec, s[26:27]
	s_cbranch_vccnz .LBB0_651
	s_waitcnt lgkmcnt(0)
	v_lshlrev_b32_e32 v138, 2, v210
	v_mov_b32_e32 v139, v97
	v_lshl_add_u64 v[146:147], s[90:91], 0, v[138:139]
	s_waitcnt lgkmcnt(4)
	v_mov_b64_e32 v[144:145], v[132:133]
	v_mov_b64_e32 v[140:141], v[136:137]
	s_add_i32 s24, s11, 0xfffffe00
	s_waitcnt lgkmcnt(0)
	v_mov_b64_e32 v[150:151], s[78:79]
	v_mov_b64_e32 v[152:153], 0x80
	v_mov_b64_e32 v[148:149], v[208:209]
	v_mov_b64_e32 v[142:143], v[130:131]
	v_mov_b64_e32 v[138:139], v[134:135]

;     DI void operator()(f32x4 (&acc)[2][2][4][2], const Unit& u, int wr, int wc, int fr, int fq, LAS unsigned char* lds) const {
;     ...
;                     bf16_t* dst; int ld, c0; float* of = nullptr; long orow = -1;
;                     if (gcol < 512) { dst = QA; ld = 512; c0 = gcol; v0 = v0 * QSCALE; v1 = v1 * QSCALE; }
;                     else if (gcol < 640) { dst = KA; ld = 128; c0 = gcol - 512; of = out + (prm ? O_KWP : O_KWS); orow = offA; }
;                     else if (gcol < 768) { dst = VA; ld = 128; c0 = gcol - 640; of = out + (prm ? O_VWP : O_VWS); orow = offA; }
;                     else if (gcol < 1280) { dst = QB; ld = 512; c0 = gcol - 768; v0 = v0 * QSCALE; v1 = v1 * QSCALE; }
;                     else if (gcol < 1792) { dst = KB; ld = 512; c0 = gcol - 1280; of = out + (prm ? O_KBP : O_KBS); orow = offB; }
;                     else if (gcol < 2304) { dst = VB; ld = 512; c0 = gcol - 1792; of = out + (prm ? O_VBP : O_VBS); orow = offB; }
;                     else { dst = GATES; ld = 2048; c0 = gcol - 2304;
.LBB0_654:
	s_andn2_b64 vcc, exec, s[26:27]
	s_cbranch_vccnz .LBB0_656
	s_waitcnt lgkmcnt(0)
	v_lshlrev_b32_e32 v138, 2, v212
	v_mov_b32_e32 v139, v97
	v_readlane_b32 s0, v250, 46
	v_lshl_add_u64 v[146:147], s[90:91], 0, v[138:139]
	v_readlane_b32 s1, v250, 47
	s_waitcnt lgkmcnt(4)
	v_mov_b64_e32 v[144:145], v[132:133]
	v_mov_b64_e32 v[140:141], v[136:137]
	s_add_i32 s24, s11, 0xfffffb00
	s_waitcnt lgkmcnt(0)
	v_mov_b64_e32 v[150:151], s[0:1]
	v_mov_b64_e32 v[152:153], 0x200
	v_mov_b64_e32 v[148:149], v[210:211]
	v_mov_b64_e32 v[142:143], v[130:131]
	v_mov_b64_e32 v[138:139], v[134:135]

;     DI void operator()(f32x4 (&acc)[2][2][4][2], const Unit& u, int wr, int wc, int fr, int fq, LAS unsigned char* lds) const {
;     ...
;                     bf16_t* dst; int ld, c0; float* of = nullptr; long orow = -1;
;                     if (gcol < 512) { dst = QA; ld = 512; c0 = gcol; v0 = v0 * QSCALE; v1 = v1 * QSCALE; }
;                     else if (gcol < 640) { dst = KA; ld = 128; c0 = gcol - 512; of = out + (prm ? O_KWP : O_KWS); orow = offA; }
;                     else if (gcol < 768) { dst = VA; ld = 128; c0 = gcol - 640; of = out + (prm ? O_VWP : O_VWS); orow = offA; }
.LBB0_660:
	s_andn2_b64 vcc, exec, s[26:27]
	s_cbranch_vccnz .LBB0_662
	s_waitcnt lgkmcnt(0)
	v_lshlrev_b32_e32 v138, 2, v202
	v_mov_b32_e32 v139, v97
	v_lshl_add_u64 v[146:147], s[90:91], 0, v[138:139]
	s_waitcnt lgkmcnt(4)
	v_mov_b64_e32 v[144:145], v[132:133]
	v_mov_b64_e32 v[140:141], v[136:137]
	s_add_i32 s24, s11, 0xfffffe00
	s_waitcnt lgkmcnt(0)
	v_mov_b64_e32 v[150:151], s[78:79]
	v_mov_b64_e32 v[152:153], 0x80
	s_waitcnt lgkmcnt(0)
	v_mov_b64_e32 v[148:149], v[206:207]
	v_mov_b64_e32 v[142:143], v[130:131]
	v_mov_b64_e32 v[138:139], v[134:135]

;     DI void operator()(f32x4 (&acc)[2][2][4][2], const Unit& u, int wr, int wc, int fr, int fq, LAS unsigned char* lds) const {
;     ...
;                     bf16_t* dst; int ld, c0; float* of = nullptr; long orow = -1;
;                     if (gcol < 512) { dst = QA; ld = 512; c0 = gcol; v0 = v0 * QSCALE; v1 = v1 * QSCALE; }
;                     else if (gcol < 640) { dst = KA; ld = 128; c0 = gcol - 512; of = out + (prm ? O_KWP : O_KWS); orow = offA; }
;                     else if (gcol < 768) { dst = VA; ld = 128; c0 = gcol - 640; of = out + (prm ? O_VWP : O_VWS); orow = offA; }
.LBB0_671:
	s_andn2_b64 vcc, exec, s[26:27]
	s_cbranch_vccnz .LBB0_673
	s_waitcnt lgkmcnt(0)
	v_lshlrev_b32_e32 v138, 2, v206
	v_mov_b32_e32 v139, v97
	v_lshl_add_u64 v[146:147], s[90:91], 0, v[138:139]
	s_waitcnt lgkmcnt(4)
	v_mov_b64_e32 v[144:145], v[132:133]
	v_mov_b64_e32 v[140:141], v[136:137]
	s_add_i32 s24, s11, 0xfffffe00
	s_waitcnt lgkmcnt(0)
	v_mov_b64_e32 v[150:151], s[78:79]
	v_mov_b64_e32 v[152:153], 0x80
	v_mov_b64_e32 v[148:149], v[204:205]
	v_mov_b64_e32 v[142:143], v[130:131]
	v_mov_b64_e32 v[138:139], v[134:135]

;     DI void operator()(f32x4 (&acc)[2][2][4][2], const Unit& u, int wr, int wc, int fr, int fq, LAS unsigned char* lds) const {
;     ...
;                     bf16_t* dst; int ld, c0; float* of = nullptr; long orow = -1;
;                     if (gcol < 512) { dst = QA; ld = 512; c0 = gcol; v0 = v0 * QSCALE; v1 = v1 * QSCALE; }
;                     else if (gcol < 640) { dst = KA; ld = 128; c0 = gcol - 512; of = out + (prm ? O_KWP : O_KWS); orow = offA; }
;                     else if (gcol < 768) { dst = VA; ld = 128; c0 = gcol - 640; of = out + (prm ? O_VWP : O_VWS); orow = offA; }
;                     else if (gcol < 1280) { dst = QB; ld = 512; c0 = gcol - 768; v0 = v0 * QSCALE; v1 = v1 * QSCALE; }
;                     else if (gcol < 1792) { dst = KB; ld = 512; c0 = gcol - 1280; of = out + (prm ? O_KBP : O_KBS); orow = offB; }
;                     else if (gcol < 2304) { dst = VB; ld = 512; c0 = gcol - 1792; of = out + (prm ? O_VBP : O_VBS); orow = offB; }
;                     else { dst = GATES; ld = 2048; c0 = gcol - 2304;
.LBB0_676:
	s_andn2_b64 vcc, exec, s[26:27]
	s_cbranch_vccnz .LBB0_678
	s_waitcnt lgkmcnt(0)
	v_lshlrev_b32_e32 v138, 2, v210
	v_mov_b32_e32 v139, v97
	v_readlane_b32 s0, v250, 46
	v_lshl_add_u64 v[146:147], s[90:91], 0, v[138:139]
	v_readlane_b32 s1, v250, 47
	s_waitcnt lgkmcnt(4)
	v_mov_b64_e32 v[144:145], v[132:133]
	v_mov_b64_e32 v[140:141], v[136:137]
	s_add_i32 s24, s11, 0xfffffb00
	s_waitcnt lgkmcnt(0)
	v_mov_b64_e32 v[150:151], s[0:1]
	v_mov_b64_e32 v[152:153], 0x200
	v_mov_b64_e32 v[148:149], v[208:209]
	v_mov_b64_e32 v[142:143], v[130:131]
	v_mov_b64_e32 v[138:139], v[134:135]

;     DI void operator()(f32x4 (&acc)[2][2][4][2], const Unit& u, int wr, int wc, int fr, int fq, LAS unsigned char* lds) const {
;     ...
;                     bf16_t* dst; int ld, c0; float* of = nullptr; long orow = -1;
;                     if (gcol < 512) { dst = QA; ld = 512; c0 = gcol; v0 = v0 * QSCALE; v1 = v1 * QSCALE; }
;                     else if (gcol < 640) { dst = KA; ld = 128; c0 = gcol - 512; of = out + (prm ? O_KWP : O_KWS); orow = offA; }
;                     else if (gcol < 768) { dst = VA; ld = 128; c0 = gcol - 640; of = out + (prm ? O_VWP : O_VWS); orow = offA; }
.LBB0_682:
	s_andn2_b64 vcc, exec, s[26:27]
	s_cbranch_vccnz .LBB0_684
	s_waitcnt lgkmcnt(0)
	v_lshlrev_b32_e32 v138, 2, v204
	v_mov_b32_e32 v139, v97
	v_lshl_add_u64 v[146:147], s[90:91], 0, v[138:139]
	s_waitcnt lgkmcnt(4)
	v_mov_b64_e32 v[144:145], v[132:133]
	v_mov_b64_e32 v[140:141], v[136:137]
	s_add_i32 s24, s11, 0xfffffe00
	s_waitcnt lgkmcnt(0)
	v_mov_b64_e32 v[150:151], s[78:79]
	v_mov_b64_e32 v[152:153], 0x80
	v_mov_b64_e32 v[148:149], v[202:203]
	v_mov_b64_e32 v[142:143], v[130:131]
	v_mov_b64_e32 v[138:139], v[134:135]

;     DI void operator()(f32x4 (&acc)[2][2][4][2], const Unit& u, int wr, int wc, int fr, int fq, LAS unsigned char* lds) const {
;     ...
;                     bf16_t* dst; int ld, c0; float* of = nullptr; long orow = -1;
;                     if (gcol < 512) { dst = QA; ld = 512; c0 = gcol; v0 = v0 * QSCALE; v1 = v1 * QSCALE; }
;                     else if (gcol < 640) { dst = KA; ld = 128; c0 = gcol - 512; of = out + (prm ? O_KWP : O_KWS); orow = offA; }
;                     else if (gcol < 768) { dst = VA; ld = 128; c0 = gcol - 640; of = out + (prm ? O_VWP : O_VWS); orow = offA; }
;                     else if (gcol < 1280) { dst = QB; ld = 512; c0 = gcol - 768; v0 = v0 * QSCALE; v1 = v1 * QSCALE; }
;                     else if (gcol < 1792) { dst = KB; ld = 512; c0 = gcol - 1280; of = out + (prm ? O_KBP : O_KBS); orow = offB; }
;                     else if (gcol < 2304) { dst = VB; ld = 512; c0 = gcol - 1792; of = out + (prm ? O_VBP : O_VBS); orow = offB; }
;                     else { dst = GATES; ld = 2048; c0 = gcol - 2304;
.LBB0_687:
	s_andn2_b64 vcc, exec, s[26:27]
	s_cbranch_vccnz .LBB0_689
	s_waitcnt lgkmcnt(0)
	v_lshlrev_b32_e32 v138, 2, v208
	v_mov_b32_e32 v139, v97
	v_readlane_b32 s0, v250, 46
	v_lshl_add_u64 v[146:147], s[90:91], 0, v[138:139]
	v_readlane_b32 s1, v250, 47
	s_waitcnt lgkmcnt(4)
	v_mov_b64_e32 v[144:145], v[132:133]
	v_mov_b64_e32 v[140:141], v[136:137]
	s_add_i32 s24, s11, 0xfffffb00
	s_waitcnt lgkmcnt(0)
	v_mov_b64_e32 v[150:151], s[0:1]
	v_mov_b64_e32 v[152:153], 0x200
	v_mov_b64_e32 v[148:149], v[206:207]
	v_mov_b64_e32 v[142:143], v[130:131]
	v_mov_b64_e32 v[138:139], v[134:135]

;     DI void operator()(f32x4 (&acc)[2][2][4][2], const Unit& u, int wr, int wc, int fr, int fq, LAS unsigned char* lds) const {
;     ...
;                     bf16_t* dst; int ld, c0; float* of = nullptr; long orow = -1;
;                     if (gcol < 512) { dst = QA; ld = 512; c0 = gcol; v0 = v0 * QSCALE; v1 = v1 * QSCALE; }
;                     else if (gcol < 640) { dst = KA; ld = 128; c0 = gcol - 512; of = out + (prm ? O_KWP : O_KWS); orow = offA; }
;                     else if (gcol < 768) { dst = VA; ld = 128; c0 = gcol - 640; of = out + (prm ? O_VWP : O_VWS); orow = offA; }
.LBB0_693:
	s_andn2_b64 vcc, exec, s[26:27]
	s_cbranch_vccnz .LBB0_695
	s_waitcnt lgkmcnt(0)
	v_lshlrev_b32_e32 v138, 2, v202
	v_mov_b32_e32 v139, v97
	v_lshl_add_u64 v[146:147], s[90:91], 0, v[138:139]
	s_waitcnt lgkmcnt(4)
	v_mov_b64_e32 v[144:145], v[132:133]
	v_mov_b64_e32 v[140:141], v[136:137]
	s_add_i32 s24, s11, 0xfffffe00
	s_waitcnt lgkmcnt(0)
	v_mov_b64_e32 v[150:151], s[78:79]
	v_mov_b64_e32 v[152:153], 0x80
	s_waitcnt lgkmcnt(0)
	v_mov_b64_e32 v[148:149], v[198:199]
	v_mov_b64_e32 v[142:143], v[130:131]
	v_mov_b64_e32 v[138:139], v[134:135]

;     DI void operator()(f32x4 (&acc)[2][2][4][2], const Unit& u, int wr, int wc, int fr, int fq, LAS unsigned char* lds) const {
;     ...
;                     bf16_t* dst; int ld, c0; float* of = nullptr; long orow = -1;
;                     if (gcol < 512) { dst = QA; ld = 512; c0 = gcol; v0 = v0 * QSCALE; v1 = v1 * QSCALE; }
;                     else if (gcol < 640) { dst = KA; ld = 128; c0 = gcol - 512; of = out + (prm ? O_KWP : O_KWS); orow = offA; }
;                     else if (gcol < 768) { dst = VA; ld = 128; c0 = gcol - 640; of = out + (prm ? O_VWP : O_VWS); orow = offA; }
;                     else if (gcol < 1280) { dst = QB; ld = 512; c0 = gcol - 768; v0 = v0 * QSCALE; v1 = v1 * QSCALE; }
;                     else if (gcol < 1792) { dst = KB; ld = 512; c0 = gcol - 1280; of = out + (prm ? O_KBP : O_KBS); orow = offB; }
;                     else if (gcol < 2304) { dst = VB; ld = 512; c0 = gcol - 1792; of = out + (prm ? O_VBP : O_VBS); orow = offB; }
;                     else { dst = GATES; ld = 2048; c0 = gcol - 2304;
.LBB0_698:
	s_andn2_b64 vcc, exec, s[26:27]
	s_cbranch_vccnz .LBB0_700
	s_waitcnt lgkmcnt(0)
	v_lshlrev_b32_e32 v138, 2, v200
	v_mov_b32_e32 v139, v97
	v_readlane_b32 s0, v250, 46
	v_lshl_add_u64 v[146:147], s[90:91], 0, v[138:139]
	v_readlane_b32 s1, v250, 47
	s_waitcnt lgkmcnt(4)
	v_mov_b64_e32 v[144:145], v[132:133]
	v_mov_b64_e32 v[140:141], v[136:137]
	s_add_i32 s24, s11, 0xfffffb00
	s_waitcnt lgkmcnt(0)
	v_mov_b64_e32 v[150:151], s[0:1]
	v_mov_b64_e32 v[152:153], 0x200
	v_mov_b64_e32 v[148:149], v[202:203]
	v_mov_b64_e32 v[142:143], v[130:131]
	v_mov_b64_e32 v[138:139], v[134:135]

;     DI void operator()(f32x4 (&acc)[2][2][4][2], const Unit& u, int wr, int wc, int fr, int fq, LAS unsigned char* lds) const {
;     ...
;                     bf16_t* dst; int ld, c0; float* of = nullptr; long orow = -1;
;                     if (gcol < 512) { dst = QA; ld = 512; c0 = gcol; v0 = v0 * QSCALE; v1 = v1 * QSCALE; }
;                     else if (gcol < 640) { dst = KA; ld = 128; c0 = gcol - 512; of = out + (prm ? O_KWP : O_KWS); orow = offA; }
;                     else if (gcol < 768) { dst = VA; ld = 128; c0 = gcol - 640; of = out + (prm ? O_VWP : O_VWS); orow = offA; }
.LBB0_704:
	s_andn2_b64 vcc, exec, s[26:27]
	s_cbranch_vccnz .LBB0_706
	s_waitcnt lgkmcnt(0)
	v_lshlrev_b32_e32 v138, 2, v196
	v_mov_b32_e32 v139, v97
	v_lshl_add_u64 v[146:147], s[90:91], 0, v[138:139]
	s_waitcnt lgkmcnt(4)
	v_mov_b64_e32 v[144:145], v[132:133]
	v_mov_b64_e32 v[140:141], v[136:137]
	s_add_i32 s24, s11, 0xfffffe00
	s_waitcnt lgkmcnt(0)
	v_mov_b64_e32 v[150:151], s[78:79]
	v_mov_b64_e32 v[152:153], 0x80
	v_mov_b64_e32 v[148:149], v[194:195]
	v_mov_b64_e32 v[142:143], v[130:131]
	v_mov_b64_e32 v[138:139], v[134:135]

;     DI void operator()(f32x4 (&acc)[2][2][4][2], const Unit& u, int wr, int wc, int fr, int fq, LAS unsigned char* lds) const {
;     ...
;                     bf16_t* dst; int ld, c0; float* of = nullptr; long orow = -1;
;                     if (gcol < 512) { dst = QA; ld = 512; c0 = gcol; v0 = v0 * QSCALE; v1 = v1 * QSCALE; }
;                     else if (gcol < 640) { dst = KA; ld = 128; c0 = gcol - 512; of = out + (prm ? O_KWP : O_KWS); orow = offA; }
;                     else if (gcol < 768) { dst = VA; ld = 128; c0 = gcol - 640; of = out + (prm ? O_VWP : O_VWS); orow = offA; }
;                     else if (gcol < 1280) { dst = QB; ld = 512; c0 = gcol - 768; v0 = v0 * QSCALE; v1 = v1 * QSCALE; }
;                     else if (gcol < 1792) { dst = KB; ld = 512; c0 = gcol - 1280; of = out + (prm ? O_KBP : O_KBS); orow = offB; }
;                     else if (gcol < 2304) { dst = VB; ld = 512; c0 = gcol - 1792; of = out + (prm ? O_VBP : O_VBS); orow = offB; }
;                     else { dst = GATES; ld = 2048; c0 = gcol - 2304;
.LBB0_723:
	s_andn2_b64 vcc, exec, s[26:27]
	s_cbranch_vccnz .LBB0_725
	s_waitcnt lgkmcnt(0)
	v_lshlrev_b32_e32 v138, 2, v212
	v_mov_b32_e32 v139, v97
	v_readlane_b32 s0, v250, 46
	v_lshl_add_u64 v[146:147], s[90:91], 0, v[138:139]
	v_readlane_b32 s1, v250, 47
	s_waitcnt lgkmcnt(4)
	v_mov_b64_e32 v[144:145], v[132:133]
	v_mov_b64_e32 v[140:141], v[136:137]
	s_add_i32 s24, s11, 0xfffffb80
	s_waitcnt lgkmcnt(0)
	v_mov_b64_e32 v[150:151], s[0:1]
	v_mov_b64_e32 v[152:153], 0x200
	v_mov_b64_e32 v[148:149], v[210:211]
	v_mov_b64_e32 v[142:143], v[130:131]
	v_mov_b64_e32 v[138:139], v[134:135]

;     DI void operator()(f32x4 (&acc)[2][2][4][2], const Unit& u, int wr, int wc, int fr, int fq, LAS unsigned char* lds) const {
;     ...
;                     bf16_t* dst; int ld, c0; float* of = nullptr; long orow = -1;
;                     if (gcol < 512) { dst = QA; ld = 512; c0 = gcol; v0 = v0 * QSCALE; v1 = v1 * QSCALE; }
;                     else if (gcol < 640) { dst = KA; ld = 128; c0 = gcol - 512; of = out + (prm ? O_KWP : O_KWS); orow = offA; }
;                     else if (gcol < 768) { dst = VA; ld = 128; c0 = gcol - 640; of = out + (prm ? O_VWP : O_VWS); orow = offA; }
.LBB0_729:
	s_andn2_b64 vcc, exec, s[26:27]
	s_cbranch_vccnz .LBB0_731
	s_waitcnt lgkmcnt(0)
	v_lshlrev_b32_e32 v138, 2, v208
	v_mov_b32_e32 v139, v97
	v_readlane_b32 s0, v250, 40
	v_lshl_add_u64 v[146:147], s[90:91], 0, v[138:139]
	v_readlane_b32 s1, v250, 41
	s_waitcnt lgkmcnt(4)
	v_mov_b64_e32 v[144:145], v[132:133]
	v_mov_b64_e32 v[140:141], v[136:137]
	s_add_i32 s24, s11, 0xfffffe00
	s_waitcnt lgkmcnt(0)
	v_mov_b64_e32 v[150:151], s[0:1]
	v_mov_b64_e32 v[152:153], 0x80
	s_waitcnt lgkmcnt(0)
	v_mov_b64_e32 v[148:149], v[206:207]
	v_mov_b64_e32 v[142:143], v[130:131]
	v_mov_b64_e32 v[138:139], v[134:135]

;     DI void operator()(f32x4 (&acc)[2][2][4][2], const Unit& u, int wr, int wc, int fr, int fq, LAS unsigned char* lds) const {
;     ...
;                     bf16_t* dst; int ld, c0; float* of = nullptr; long orow = -1;
;                     if (gcol < 512) { dst = QA; ld = 512; c0 = gcol; v0 = v0 * QSCALE; v1 = v1 * QSCALE; }
;                     else if (gcol < 640) { dst = KA; ld = 128; c0 = gcol - 512; of = out + (prm ? O_KWP : O_KWS); orow = offA; }
;                     else if (gcol < 768) { dst = VA; ld = 128; c0 = gcol - 640; of = out + (prm ? O_VWP : O_VWS); orow = offA; }
.LBB0_732:
	s_andn2_b64 vcc, exec, s[26:27]
	s_cbranch_vccnz .LBB0_734
	s_waitcnt lgkmcnt(0)
	v_lshlrev_b32_e32 v138, 2, v202
	v_mov_b32_e32 v139, v97
	v_lshl_add_u64 v[146:147], s[90:91], 0, v[138:139]
	s_waitcnt lgkmcnt(4)
	v_mov_b64_e32 v[144:145], v[132:133]
	v_mov_b64_e32 v[140:141], v[136:137]
	s_add_i32 s24, s11, 0xfffffe80
	s_waitcnt lgkmcnt(0)
	v_mov_b64_e32 v[150:151], s[78:79]
	v_mov_b64_e32 v[152:153], 0x80
	s_waitcnt lgkmcnt(0)
	v_mov_b64_e32 v[148:149], v[206:207]
	v_mov_b64_e32 v[142:143], v[130:131]
	v_mov_b64_e32 v[138:139], v[134:135]

;     DI void operator()(f32x4 (&acc)[2][2][4][2], const Unit& u, int wr, int wc, int fr, int fq, LAS unsigned char* lds) const {
;     ...
;                     bf16_t* dst; int ld, c0; float* of = nullptr; long orow = -1;
;                     if (gcol < 512) { dst = QA; ld = 512; c0 = gcol; v0 = v0 * QSCALE; v1 = v1 * QSCALE; }
;                     else if (gcol < 640) { dst = KA; ld = 128; c0 = gcol - 512; of = out + (prm ? O_KWP : O_KWS); orow = offA; }
;                     else if (gcol < 768) { dst = VA; ld = 128; c0 = gcol - 640; of = out + (prm ? O_VWP : O_VWS); orow = offA; }
.LBB0_743:
	s_andn2_b64 vcc, exec, s[26:27]
	s_cbranch_vccnz .LBB0_745
	s_waitcnt lgkmcnt(0)
	v_lshlrev_b32_e32 v138, 2, v208
	v_mov_b32_e32 v139, v97
	v_readlane_b32 s0, v250, 40
	v_lshl_add_u64 v[146:147], s[90:91], 0, v[138:139]
	v_readlane_b32 s1, v250, 41
	s_waitcnt lgkmcnt(4)
	v_mov_b64_e32 v[144:145], v[132:133]
	v_mov_b64_e32 v[140:141], v[136:137]
	s_add_i32 s24, s11, 0xfffffe00
	s_waitcnt lgkmcnt(0)
	v_mov_b64_e32 v[150:151], s[0:1]
	v_mov_b64_e32 v[152:153], 0x80
	v_mov_b64_e32 v[148:149], v[204:205]
	v_mov_b64_e32 v[142:143], v[130:131]
	v_mov_b64_e32 v[138:139], v[134:135]

;     DI void operator()(f32x4 (&acc)[2][2][4][2], const Unit& u, int wr, int wc, int fr, int fq, LAS unsigned char* lds) const {
;     ...
;                     bf16_t* dst; int ld, c0; float* of = nullptr; long orow = -1;
;                     if (gcol < 512) { dst = QA; ld = 512; c0 = gcol; v0 = v0 * QSCALE; v1 = v1 * QSCALE; }
;                     else if (gcol < 640) { dst = KA; ld = 128; c0 = gcol - 512; of = out + (prm ? O_KWP : O_KWS); orow = offA; }
;                     else if (gcol < 768) { dst = VA; ld = 128; c0 = gcol - 640; of = out + (prm ? O_VWP : O_VWS); orow = offA; }
.LBB0_746:
	s_andn2_b64 vcc, exec, s[26:27]
	s_cbranch_vccnz .LBB0_748
	s_waitcnt lgkmcnt(0)
	v_lshlrev_b32_e32 v138, 2, v206
	v_mov_b32_e32 v139, v97
	v_lshl_add_u64 v[146:147], s[90:91], 0, v[138:139]
	s_waitcnt lgkmcnt(4)
	v_mov_b64_e32 v[144:145], v[132:133]
	v_mov_b64_e32 v[140:141], v[136:137]
	s_add_i32 s24, s11, 0xfffffe80
	s_waitcnt lgkmcnt(0)
	v_mov_b64_e32 v[150:151], s[78:79]
	v_mov_b64_e32 v[152:153], 0x80
	v_mov_b64_e32 v[148:149], v[204:205]
	v_mov_b64_e32 v[142:143], v[130:131]
	v_mov_b64_e32 v[138:139], v[134:135]

;     DI void operator()(f32x4 (&acc)[2][2][4][2], const Unit& u, int wr, int wc, int fr, int fq, LAS unsigned char* lds) const {
;     ...
;                     bf16_t* dst; int ld, c0; float* of = nullptr; long orow = -1;
;                     if (gcol < 512) { dst = QA; ld = 512; c0 = gcol; v0 = v0 * QSCALE; v1 = v1 * QSCALE; }
;                     else if (gcol < 640) { dst = KA; ld = 128; c0 = gcol - 512; of = out + (prm ? O_KWP : O_KWS); orow = offA; }
;                     else if (gcol < 768) { dst = VA; ld = 128; c0 = gcol - 640; of = out + (prm ? O_VWP : O_VWS); orow = offA; }
;                     else if (gcol < 1280) { dst = QB; ld = 512; c0 = gcol - 768; v0 = v0 * QSCALE; v1 = v1 * QSCALE; }
;                     else if (gcol < 1792) { dst = KB; ld = 512; c0 = gcol - 1280; of = out + (prm ? O_KBP : O_KBS); orow = offB; }
;                     else if (gcol < 2304) { dst = VB; ld = 512; c0 = gcol - 1792; of = out + (prm ? O_VBP : O_VBS); orow = offB; }
;                     else { dst = GATES; ld = 2048; c0 = gcol - 2304;
.LBB0_751:
	s_andn2_b64 vcc, exec, s[26:27]
	s_cbranch_vccnz .LBB0_753
	s_waitcnt lgkmcnt(0)
	v_lshlrev_b32_e32 v138, 2, v210
	v_mov_b32_e32 v139, v97
	v_readlane_b32 s0, v250, 46
	v_lshl_add_u64 v[146:147], s[90:91], 0, v[138:139]
	v_readlane_b32 s1, v250, 47
	s_waitcnt lgkmcnt(4)
	v_mov_b64_e32 v[144:145], v[132:133]
	v_mov_b64_e32 v[140:141], v[136:137]
	s_add_i32 s24, s11, 0xfffffb80
	s_waitcnt lgkmcnt(0)
	v_mov_b64_e32 v[150:151], s[0:1]
	v_mov_b64_e32 v[152:153], 0x200
	v_mov_b64_e32 v[148:149], v[208:209]
	v_mov_b64_e32 v[142:143], v[130:131]
	v_mov_b64_e32 v[138:139], v[134:135]

;     DI void operator()(f32x4 (&acc)[2][2][4][2], const Unit& u, int wr, int wc, int fr, int fq, LAS unsigned char* lds) const {
;     ...
;                     bf16_t* dst; int ld, c0; float* of = nullptr; long orow = -1;
;                     if (gcol < 512) { dst = QA; ld = 512; c0 = gcol; v0 = v0 * QSCALE; v1 = v1 * QSCALE; }
;                     else if (gcol < 640) { dst = KA; ld = 128; c0 = gcol - 512; of = out + (prm ? O_KWP : O_KWS); orow = offA; }
;                     else if (gcol < 768) { dst = VA; ld = 128; c0 = gcol - 640; of = out + (prm ? O_VWP : O_VWS); orow = offA; }
.LBB0_757:
	s_andn2_b64 vcc, exec, s[26:27]
	s_cbranch_vccnz .LBB0_759
	s_waitcnt lgkmcnt(0)
	v_lshlrev_b32_e32 v138, 2, v206
	v_mov_b32_e32 v139, v97
	v_readlane_b32 s0, v250, 40
	v_lshl_add_u64 v[146:147], s[90:91], 0, v[138:139]
	v_readlane_b32 s1, v250, 41
	s_waitcnt lgkmcnt(4)
	v_mov_b64_e32 v[144:145], v[132:133]
	v_mov_b64_e32 v[140:141], v[136:137]
	s_add_i32 s24, s11, 0xfffffe00
	s_waitcnt lgkmcnt(0)
	v_mov_b64_e32 v[150:151], s[0:1]
	v_mov_b64_e32 v[152:153], 0x80
	v_mov_b64_e32 v[148:149], v[202:203]
	v_mov_b64_e32 v[142:143], v[130:131]
	v_mov_b64_e32 v[138:139], v[134:135]

;     DI void operator()(f32x4 (&acc)[2][2][4][2], const Unit& u, int wr, int wc, int fr, int fq, LAS unsigned char* lds) const {
;     ...
;                     bf16_t* dst; int ld, c0; float* of = nullptr; long orow = -1;
;                     if (gcol < 512) { dst = QA; ld = 512; c0 = gcol; v0 = v0 * QSCALE; v1 = v1 * QSCALE; }
;                     else if (gcol < 640) { dst = KA; ld = 128; c0 = gcol - 512; of = out + (prm ? O_KWP : O_KWS); orow = offA; }
;                     else if (gcol < 768) { dst = VA; ld = 128; c0 = gcol - 640; of = out + (prm ? O_VWP : O_VWS); orow = offA; }
.LBB0_760:
	s_andn2_b64 vcc, exec, s[26:27]
	s_cbranch_vccnz .LBB0_762
	s_waitcnt lgkmcnt(0)
	v_lshlrev_b32_e32 v138, 2, v204
	v_mov_b32_e32 v139, v97
	v_lshl_add_u64 v[146:147], s[90:91], 0, v[138:139]
	s_waitcnt lgkmcnt(4)
	v_mov_b64_e32 v[144:145], v[132:133]
	v_mov_b64_e32 v[140:141], v[136:137]
	s_add_i32 s24, s11, 0xfffffe80
	s_waitcnt lgkmcnt(0)
	v_mov_b64_e32 v[150:151], s[78:79]
	v_mov_b64_e32 v[152:153], 0x80
	v_mov_b64_e32 v[148:149], v[202:203]
	v_mov_b64_e32 v[142:143], v[130:131]
	v_mov_b64_e32 v[138:139], v[134:135]

;     DI void operator()(f32x4 (&acc)[2][2][4][2], const Unit& u, int wr, int wc, int fr, int fq, LAS unsigned char* lds) const {
;     ...
;                     bf16_t* dst; int ld, c0; float* of = nullptr; long orow = -1;
;                     if (gcol < 512) { dst = QA; ld = 512; c0 = gcol; v0 = v0 * QSCALE; v1 = v1 * QSCALE; }
;                     else if (gcol < 640) { dst = KA; ld = 128; c0 = gcol - 512; of = out + (prm ? O_KWP : O_KWS); orow = offA; }
;                     else if (gcol < 768) { dst = VA; ld = 128; c0 = gcol - 640; of = out + (prm ? O_VWP : O_VWS); orow = offA; }
;                     else if (gcol < 1280) { dst = QB; ld = 512; c0 = gcol - 768; v0 = v0 * QSCALE; v1 = v1 * QSCALE; }
;                     else if (gcol < 1792) { dst = KB; ld = 512; c0 = gcol - 1280; of = out + (prm ? O_KBP : O_KBS); orow = offB; }
;                     else if (gcol < 2304) { dst = VB; ld = 512; c0 = gcol - 1792; of = out + (prm ? O_VBP : O_VBS); orow = offB; }
;                     else { dst = GATES; ld = 2048; c0 = gcol - 2304;
.LBB0_765:
	s_andn2_b64 vcc, exec, s[26:27]
	s_cbranch_vccnz .LBB0_767
	s_waitcnt lgkmcnt(0)
	v_lshlrev_b32_e32 v138, 2, v208
	v_mov_b32_e32 v139, v97
	v_readlane_b32 s0, v250, 46
	v_lshl_add_u64 v[146:147], s[90:91], 0, v[138:139]
	v_readlane_b32 s1, v250, 47
	s_waitcnt lgkmcnt(4)
	v_mov_b64_e32 v[144:145], v[132:133]
	v_mov_b64_e32 v[140:141], v[136:137]
	s_add_i32 s24, s11, 0xfffffb80
	s_waitcnt lgkmcnt(0)
	v_mov_b64_e32 v[150:151], s[0:1]
	v_mov_b64_e32 v[152:153], 0x200
	v_mov_b64_e32 v[148:149], v[206:207]
	v_mov_b64_e32 v[142:143], v[130:131]
	v_mov_b64_e32 v[138:139], v[134:135]

;     DI void operator()(f32x4 (&acc)[2][2][4][2], const Unit& u, int wr, int wc, int fr, int fq, LAS unsigned char* lds) const {
;     ...
;                     bf16_t* dst; int ld, c0; float* of = nullptr; long orow = -1;
;                     if (gcol < 512) { dst = QA; ld = 512; c0 = gcol; v0 = v0 * QSCALE; v1 = v1 * QSCALE; }
;                     else if (gcol < 640) { dst = KA; ld = 128; c0 = gcol - 512; of = out + (prm ? O_KWP : O_KWS); orow = offA; }
;                     else if (gcol < 768) { dst = VA; ld = 128; c0 = gcol - 640; of = out + (prm ? O_VWP : O_VWS); orow = offA; }
.LBB0_771:
	s_andn2_b64 vcc, exec, s[26:27]
	s_cbranch_vccnz .LBB0_773
	s_waitcnt lgkmcnt(0)
	v_lshlrev_b32_e32 v138, 2, v204
	v_mov_b32_e32 v139, v97
	v_readlane_b32 s0, v250, 40
	v_lshl_add_u64 v[146:147], s[90:91], 0, v[138:139]
	v_readlane_b32 s1, v250, 41
	s_waitcnt lgkmcnt(4)
	v_mov_b64_e32 v[144:145], v[132:133]
	v_mov_b64_e32 v[140:141], v[136:137]
	s_add_i32 s24, s11, 0xfffffe00
	s_waitcnt lgkmcnt(0)
	v_mov_b64_e32 v[150:151], s[0:1]
	v_mov_b64_e32 v[152:153], 0x80
	s_waitcnt lgkmcnt(0)
	v_mov_b64_e32 v[148:149], v[198:199]
	v_mov_b64_e32 v[142:143], v[130:131]
	v_mov_b64_e32 v[138:139], v[134:135]

;     DI void operator()(f32x4 (&acc)[2][2][4][2], const Unit& u, int wr, int wc, int fr, int fq, LAS unsigned char* lds) const {
;     ...
;                     bf16_t* dst; int ld, c0; float* of = nullptr; long orow = -1;
;                     if (gcol < 512) { dst = QA; ld = 512; c0 = gcol; v0 = v0 * QSCALE; v1 = v1 * QSCALE; }
;                     else if (gcol < 640) { dst = KA; ld = 128; c0 = gcol - 512; of = out + (prm ? O_KWP : O_KWS); orow = offA; }
;                     else if (gcol < 768) { dst = VA; ld = 128; c0 = gcol - 640; of = out + (prm ? O_VWP : O_VWS); orow = offA; }
.LBB0_774:
	s_andn2_b64 vcc, exec, s[26:27]
	s_cbranch_vccnz .LBB0_776
	s_waitcnt lgkmcnt(0)
	v_lshlrev_b32_e32 v138, 2, v202
	v_mov_b32_e32 v139, v97
	v_lshl_add_u64 v[146:147], s[90:91], 0, v[138:139]
	s_waitcnt lgkmcnt(4)
	v_mov_b64_e32 v[144:145], v[132:133]
	v_mov_b64_e32 v[140:141], v[136:137]
	s_add_i32 s24, s11, 0xfffffe80
	s_waitcnt lgkmcnt(0)
	v_mov_b64_e32 v[150:151], s[78:79]
	v_mov_b64_e32 v[152:153], 0x80
	s_waitcnt lgkmcnt(0)
	v_mov_b64_e32 v[148:149], v[198:199]
	v_mov_b64_e32 v[142:143], v[130:131]
	v_mov_b64_e32 v[138:139], v[134:135]

; #define LAS __attribute__((address_space(3)))
; DI float sigmoidf_(float a) { return fast_rcp(1.0f + fast_exp2(-a * LOG2E)); }
;     DI void operator()(f32x4 (&acc)[2][2][4][2], const Unit& u, int wr, int wc, int fr, int fq, LAS unsigned char* lds) const {
;     ...
;                     else { dst = GATES; ld = 2048; c0 = gcol - 2304;
;                         const f32x4 g0 = *(const LAS f32x4*)(lds + BG_OFF + (c0 + cw) * 4), g1 = *(const LAS f32x4*)(lds + BG_OFF + (c0 + cw + 4) * 4);
; #pragma unroll
;                         for (int j = 0; j < 4; ++j) { v0[j] = sigmoidf_(v0[j] + g0[j]); v1[j] = sigmoidf_(v1[j] + g1[j]); } }
.LBB0_777:
	v_readlane_b32 s28, v250, 38
	s_mov_b64 s[26:27], 0x800
	s_waitcnt lgkmcnt(0)
	v_mov_b64_e32 v[146:147], 0
	s_waitcnt lgkmcnt(0)
	v_mov_b64_e32 v[148:149], -1
	v_readlane_b32 s29, v250, 39

;     DI void operator()(f32x4 (&acc)[2][2][4][2], const Unit& u, int wr, int wc, int fr, int fq, LAS unsigned char* lds) const {
;     ...
;                     bf16_t* dst; int ld, c0; float* of = nullptr; long orow = -1;
;                     if (gcol < 512) { dst = QA; ld = 512; c0 = gcol; v0 = v0 * QSCALE; v1 = v1 * QSCALE; }
;                     else if (gcol < 640) { dst = KA; ld = 128; c0 = gcol - 512; of = out + (prm ? O_KWP : O_KWS); orow = offA; }
;                     else if (gcol < 768) { dst = VA; ld = 128; c0 = gcol - 640; of = out + (prm ? O_VWP : O_VWS); orow = offA; }
;                     else if (gcol < 1280) { dst = QB; ld = 512; c0 = gcol - 768; v0 = v0 * QSCALE; v1 = v1 * QSCALE; }
;                     else if (gcol < 1792) { dst = KB; ld = 512; c0 = gcol - 1280; of = out + (prm ? O_KBP : O_KBS); orow = offB; }
;                     else if (gcol < 2304) { dst = VB; ld = 512; c0 = gcol - 1792; of = out + (prm ? O_VBP : O_VBS); orow = offB; }
;                     else { dst = GATES; ld = 2048; c0 = gcol - 2304;
.LBB0_779:
	s_andn2_b64 vcc, exec, s[22:23]
	s_cbranch_vccnz .LBB0_781
	s_waitcnt lgkmcnt(0)
	v_lshlrev_b32_e32 v138, 2, v200
	v_mov_b32_e32 v139, v97
	v_readlane_b32 s0, v250, 46
	v_lshl_add_u64 v[146:147], s[90:91], 0, v[138:139]
	v_readlane_b32 s1, v250, 47
	s_waitcnt lgkmcnt(4)
	v_mov_b64_e32 v[144:145], v[132:133]
	v_mov_b64_e32 v[140:141], v[136:137]
	s_add_i32 s24, s11, 0xfffffb80
	s_waitcnt lgkmcnt(0)
	v_mov_b64_e32 v[150:151], s[0:1]
	v_mov_b64_e32 v[152:153], 0x200
	v_mov_b64_e32 v[148:149], v[202:203]
	v_mov_b64_e32 v[142:143], v[130:131]
	v_mov_b64_e32 v[138:139], v[134:135]

;     DI void operator()(f32x4 (&acc)[2][2][4][2], const Unit& u, int wr, int wc, int fr, int fq, LAS unsigned char* lds) const {
;     ...
;                     if (gcol < 512) { dst = QA; ld = 512; c0 = gcol; v0 = v0 * QSCALE; v1 = v1 * QSCALE; }
;                     else if (gcol < 640) { dst = KA; ld = 128; c0 = gcol - 512; of = out + (prm ? O_KWP : O_KWS); orow = offA; }
;                     else if (gcol < 768) { dst = VA; ld = 128; c0 = gcol - 640; of = out + (prm ? O_VWP : O_VWS); orow = offA; }
;                     else if (gcol < 1280) { dst = QB; ld = 512; c0 = gcol - 768; v0 = v0 * QSCALE; v1 = v1 * QSCALE; }
.LBB0_782:
	s_andn2_b64 vcc, exec, s[22:23]
	s_cbranch_vccnz .LBB0_784
	v_readlane_b32 s0, v250, 44
	v_readlane_b32 s1, v250, 45
	s_add_i32 s24, s11, 0xfffffd80
	s_waitcnt lgkmcnt(0)
	v_pk_mul_f32 v[140:141], v[136:137], s[66:67] op_sel_hi:[1,0]
	v_pk_mul_f32 v[138:139], v[134:135], s[66:67] op_sel_hi:[1,0]
	v_pk_mul_f32 v[144:145], v[132:133], s[66:67] op_sel_hi:[1,0]
	s_waitcnt lgkmcnt(4)
	v_pk_mul_f32 v[142:143], v[130:131], s[66:67] op_sel_hi:[1,0]
	v_mov_b64_e32 v[146:147], 0
	s_waitcnt lgkmcnt(0)
	v_mov_b64_e32 v[148:149], -1
	v_mov_b64_e32 v[150:151], s[0:1]
	v_mov_b64_e32 v[152:153], 0x200

;     DI void operator()(f32x4 (&acc)[2][2][4][2], const Unit& u, int wr, int wc, int fr, int fq, LAS unsigned char* lds) const {
;     ...
;                     bf16_t* dst; int ld, c0; float* of = nullptr; long orow = -1;
;                     if (gcol < 512) { dst = QA; ld = 512; c0 = gcol; v0 = v0 * QSCALE; v1 = v1 * QSCALE; }
;                     else if (gcol < 640) { dst = KA; ld = 128; c0 = gcol - 512; of = out + (prm ? O_KWP : O_KWS); orow = offA; }
;                     else if (gcol < 768) { dst = VA; ld = 128; c0 = gcol - 640; of = out + (prm ? O_VWP : O_VWS); orow = offA; }
.LBB0_785:
	s_andn2_b64 vcc, exec, s[22:23]
	s_cbranch_vccnz .LBB0_787
	s_waitcnt lgkmcnt(0)
	v_lshlrev_b32_e32 v138, 2, v198
	v_mov_b32_e32 v139, v97
	v_readlane_b32 s0, v250, 40
	v_lshl_add_u64 v[146:147], s[90:91], 0, v[138:139]
	v_readlane_b32 s1, v250, 41
	s_waitcnt lgkmcnt(4)
	v_mov_b64_e32 v[144:145], v[132:133]
	v_mov_b64_e32 v[140:141], v[136:137]
	s_add_i32 s24, s11, 0xfffffe00
	s_waitcnt lgkmcnt(0)
	v_mov_b64_e32 v[150:151], s[0:1]
	v_mov_b64_e32 v[152:153], 0x80
	v_mov_b64_e32 v[148:149], v[194:195]
	v_mov_b64_e32 v[142:143], v[130:131]
	v_mov_b64_e32 v[138:139], v[134:135]

;     DI void operator()(f32x4 (&acc)[2][2][4][2], const Unit& u, int wr, int wc, int fr, int fq, LAS unsigned char* lds) const {
;     ...
;                     bf16_t* dst; int ld, c0; float* of = nullptr; long orow = -1;
;                     if (gcol < 512) { dst = QA; ld = 512; c0 = gcol; v0 = v0 * QSCALE; v1 = v1 * QSCALE; }
;                     else if (gcol < 640) { dst = KA; ld = 128; c0 = gcol - 512; of = out + (prm ? O_KWP : O_KWS); orow = offA; }
;                     else if (gcol < 768) { dst = VA; ld = 128; c0 = gcol - 640; of = out + (prm ? O_VWP : O_VWS); orow = offA; }
.LBB0_788:
	s_andn2_b64 vcc, exec, s[26:27]
	s_cbranch_vccnz .LBB0_790
	s_waitcnt lgkmcnt(0)
	v_lshlrev_b32_e32 v138, 2, v196
	v_mov_b32_e32 v139, v97
	v_lshl_add_u64 v[146:147], s[90:91], 0, v[138:139]
	s_waitcnt lgkmcnt(4)
	v_mov_b64_e32 v[144:145], v[132:133]
	v_mov_b64_e32 v[140:141], v[136:137]
	s_add_i32 s24, s11, 0xfffffe80
	s_waitcnt lgkmcnt(0)
	v_mov_b64_e32 v[150:151], s[78:79]
	v_mov_b64_e32 v[152:153], 0x80
	v_mov_b64_e32 v[148:149], v[194:195]
	v_mov_b64_e32 v[142:143], v[130:131]
	v_mov_b64_e32 v[138:139], v[134:135]
